# GEMM MFMA order: accumulate chains with the weight fragment (SrcA) shared across consecutive accumulators
# baseline (speedup 1.0000x reference)
; #define PG8_STAGE(bufoff, gbase, voff) do { _Pragma("unroll") for (int _i = 0; _i < 2; ++_i) \
;         __builtin_amdgcn_global_load_lds((const unsigned*)((const char*)(gbase) + (voff)[_i]), (LAS unsigned*)(lds + (bufoff) + ldsw + _i * 8192), 16, 0, 0); } while (0)
; #define PG8_LDA(dst, b, h) do { _Pragma("unroll") for (int m = 0; m < 4; ++m) _Pragma("unroll") for (int k = 0; k < 2; ++k) dst[m][k] = *(const LAS bf16x8*)(lds + PG8_SA(b, h) + aoff + m * 2048 + k * 1024); } while (0)
; #define PG8_LDB(dst, b, h) do { _Pragma("unroll") for (int n = 0; n < 2; ++n) _Pragma("unroll") for (int k = 0; k < 2; ++k) dst[n][k] = *(const LAS bf16x8*)(lds + PG8_SB(b, h) + boff + n * 2048 + k * 1024); } while (0)
; #define PG8_MMA(ai, bj, At, Bt) do { __builtin_amdgcn_s_setprio(1); _Pragma("unroll") for (int m = 0; m < 4; ++m) _Pragma("unroll") for (int n = 0; n < 2; ++n) _Pragma("unroll") for (int k = 0; k < 2; ++k) \
;         acc[ai][bj][m][n] = __builtin_amdgcn_mfma_f32_16x16x32_bf16(Bt[n][k], At[m][k], acc[ai][bj][m][n], 0, 0, 0); __builtin_amdgcn_s_setprio(0); } while (0)
; #define PG8_WAIT_V(n) asm volatile("s_waitcnt vmcnt(" #n ")" ::: "memory")
; #define PG8_WAIT_L(n) asm volatile("s_waitcnt lgkmcnt(" #n ")" ::: "memory")
; #define PG8_BAR __builtin_amdgcn_s_barrier()
;     ...
;         const bool has_next = S.next(ui + 1, nxt);
;         const char* nA = has_next ? oa.base + (size_t)nxt.pm * oa.tstep : cA; const char* nA2 = has_next ? oa.base2 + (size_t)nxt.pm * oa.tstep : cA2; const char* nB = has_next ? ob.base + (size_t)nxt.pn * ob.tstep : cB;
; #pragma nounroll
;         for (int t = 0; t < nt; t += 2) {
;             const bool last = (t == nt - 2);
;             const char* a1 = PG8_ATILE(cA, cA2, t + 1);
;             const char* a2 = last ? nA : PG8_ATILE(cA, cA2, t + 2); const char* b2 = last ? nB : cB + (size_t)(t + 2) * 128;
;             const char* a3 = last ? nA + kA1 : PG8_ATILE(cA, cA2, t + 3); const char* b3 = b2 + kB1;
;             if constexpr (SP2) {
;             PG8_LDB(B0, 0, 0); PG8_LDB(B1, 0, 1); PG8_SCHED; PG8_LDA(At, 0, 0); PG8_STAGE(PG8_SA(1, 1), a1 + hA, voffA);
;             PG8_WAIT_V(8); PG8_WAIT_L(0); PG8_BAR; PG8_MMA(0, 0, At, B0); PG8_MMA(0, 1, At, B1); PG8_BAR; PG8_SCHED;
;             PG8_LDA(At, 0, 1); PG8_STAGE(PG8_SB(0, 0), b2, voffB); PG8_STAGE(PG8_SB(0, 1), b2 + hB, voffB); PG8_STAGE(PG8_SA(0, 0), a2, voffA);
.LBB0_96:
	s_and_b64 s[2:3], exec, s[80:81]
	s_cselect_b32 s73, s27, s13
	s_cselect_b32 s72, s26, s9
	s_add_i32 s17, 0, 0x10000
	s_add_i32 s36, 0, 0x14000
	v_add_u32_e32 v132, s17, v182
	v_add_u32_e32 v180, s36, v182
	ds_read_b128 v[16:19], v132
	ds_read_b128 v[24:27], v132 offset:1024
	ds_read_b128 v[120:123], v132 offset:2048
	ds_read_b128 v[132:135], v132 offset:3072
	ds_read_b128 v[140:143], v180
	ds_read_b128 v[148:151], v180 offset:1024
	ds_read_b128 v[176:179], v180 offset:2048
	ds_read_b128 v[184:187], v180 offset:3072
	s_add_u32 s2, s78, 0x10000
	s_addc_u32 s3, s79, 0
	v_lshl_add_u64 v[180:181], s[2:3], 0, v[152:153]
	s_add_i32 m0, s94, 0xc000
	ds_read_b128 v[188:191], v183
	ds_read_b128 v[192:195], v183 offset:1024
	ds_read_b128 v[196:199], v183 offset:2048
	ds_read_b128 v[200:203], v183 offset:3072
	ds_read_b128 v[208:211], v183 offset:4096
	ds_read_b128 v[214:217], v183 offset:5120
	ds_read_b128 v[230:233], v183 offset:6144
	ds_read_b128 v[234:237], v183 offset:7168
	global_load_lds_dwordx4 v[180:181], off
	v_lshl_add_u64 v[180:181], s[2:3], 0, v[154:155]
	s_add_i32 m0, s94, 0xe000
	s_nop 0
	global_load_lds_dwordx4 v[180:181], off
	s_waitcnt vmcnt(8)
	s_waitcnt lgkmcnt(0)
	s_barrier
	s_setprio 1
	s_waitcnt lgkmcnt(0)
	v_mfma_f32_16x16x32_bf16 v[144:147], v[16:19], v[188:191], v[144:147]
	v_mfma_f32_16x16x32_bf16 v[144:147], v[24:27], v[192:195], v[144:147]
	v_mfma_f32_16x16x32_bf16 v[116:119], v[24:27], v[200:203], v[116:119]
	v_mfma_f32_16x16x32_bf16 v[116:119], v[16:19], v[196:199], v[116:119]
	v_mfma_f32_16x16x32_bf16 v[100:103], v[16:19], v[208:211], v[100:103]
	v_mfma_f32_16x16x32_bf16 v[100:103], v[24:27], v[214:217], v[100:103]
	v_mfma_f32_16x16x32_bf16 v[84:87], v[24:27], v[234:237], v[84:87]
	v_mfma_f32_16x16x32_bf16 v[84:87], v[16:19], v[230:233], v[84:87]
	v_mfma_f32_16x16x32_bf16 v[80:83], v[120:123], v[230:233], v[80:83]
	v_mfma_f32_16x16x32_bf16 v[80:83], v[132:135], v[234:237], v[80:83]
	v_mfma_f32_16x16x32_bf16 v[96:99], v[132:135], v[214:217], v[96:99]
	v_mfma_f32_16x16x32_bf16 v[96:99], v[120:123], v[208:211], v[96:99]
	v_mfma_f32_16x16x32_bf16 v[112:115], v[120:123], v[196:199], v[112:115]
	v_mfma_f32_16x16x32_bf16 v[112:115], v[132:135], v[200:203], v[112:115]
	v_mfma_f32_16x16x32_bf16 v[136:139], v[132:135], v[192:195], v[136:139]
	v_mfma_f32_16x16x32_bf16 v[136:139], v[120:123], v[188:191], v[136:139]
	s_setprio 0
	s_setprio 1
	v_mfma_f32_16x16x32_bf16 v[128:131], v[140:143], v[188:191], v[128:131]
	v_mfma_f32_16x16x32_bf16 v[128:131], v[148:151], v[192:195], v[128:131]
	v_mfma_f32_16x16x32_bf16 v[108:111], v[148:151], v[200:203], v[108:111]
	v_mfma_f32_16x16x32_bf16 v[108:111], v[140:143], v[196:199], v[108:111]
	v_mfma_f32_16x16x32_bf16 v[92:95], v[140:143], v[208:211], v[92:95]
	v_mfma_f32_16x16x32_bf16 v[92:95], v[148:151], v[214:217], v[92:95]
	v_mfma_f32_16x16x32_bf16 v[76:79], v[148:151], v[234:237], v[76:79]
	v_mfma_f32_16x16x32_bf16 v[76:79], v[140:143], v[230:233], v[76:79]
	v_mfma_f32_16x16x32_bf16 v[72:75], v[176:179], v[230:233], v[72:75]
	v_mfma_f32_16x16x32_bf16 v[72:75], v[184:187], v[234:237], v[72:75]
	v_mfma_f32_16x16x32_bf16 v[88:91], v[184:187], v[214:217], v[88:91]
	v_mfma_f32_16x16x32_bf16 v[88:91], v[176:179], v[208:211], v[88:91]
	v_mfma_f32_16x16x32_bf16 v[104:107], v[176:179], v[196:199], v[104:107]
	v_mfma_f32_16x16x32_bf16 v[104:107], v[184:187], v[200:203], v[104:107]
	v_mfma_f32_16x16x32_bf16 v[124:127], v[184:187], v[192:195], v[124:127]
	v_mfma_f32_16x16x32_bf16 v[124:127], v[176:179], v[188:191], v[124:127]
	s_setprio 0
	s_barrier
	s_add_i32 s2, s17, s93
	v_lshl_add_u64 v[180:181], s[72:73], 0, v[156:157]
	s_mov_b32 m0, s2
	ds_read_b128 v[188:191], v183 offset:16384
	ds_read_b128 v[192:195], v183 offset:17408
	ds_read_b128 v[196:199], v183 offset:18432
	ds_read_b128 v[200:203], v183 offset:19456
	ds_read_b128 v[208:211], v183 offset:20480
	ds_read_b128 v[214:217], v183 offset:21504
	ds_read_b128 v[230:233], v183 offset:22528
	ds_read_b128 v[234:237], v183 offset:23552
	global_load_lds_dwordx4 v[180:181], off
	s_add_i32 m0, s2, 0x2000
	s_add_u32 s2, s72, 0x18000
	v_lshl_add_u64 v[204:205], s[72:73], 0, v[168:169]
	s_addc_u32 s3, s73, 0
	s_add_i32 s17, s36, s93
	global_load_lds_dwordx4 v[204:205], off
	v_lshl_add_u64 v[206:207], s[2:3], 0, v[156:157]
	s_mov_b32 m0, s17
	s_nop 0
	global_load_lds_dwordx4 v[206:207], off
	v_lshl_add_u64 v[206:207], s[2:3], 0, v[168:169]
	s_add_i32 m0, s17, 0x2000
	s_nop 0
	global_load_lds_dwordx4 v[206:207], off
	v_lshl_add_u64 v[206:207], s[76:77], 0, v[152:153]
	s_mov_b32 m0, s94
	s_nop 0
	global_load_lds_dwordx4 v[206:207], off
	v_lshl_add_u64 v[206:207], s[76:77], 0, v[154:155]
	s_mov_b32 m0, s95
	s_nop 0
	global_load_lds_dwordx4 v[206:207], off
	s_waitcnt vmcnt(8)
	s_waitcnt lgkmcnt(0)
	s_barrier
; #define PG8_STAGE(bufoff, gbase, voff) do { _Pragma("unroll") for (int _i = 0; _i < 2; ++_i) \
;         __builtin_amdgcn_global_load_lds((const unsigned*)((const char*)(gbase) + (voff)[_i]), (LAS unsigned*)(lds + (bufoff) + ldsw + _i * 8192), 16, 0, 0); } while (0)
; #define PG8_LDA(dst, b, h) do { _Pragma("unroll") for (int m = 0; m < 4; ++m) _Pragma("unroll") for (int k = 0; k < 2; ++k) dst[m][k] = *(const LAS bf16x8*)(lds + PG8_SA(b, h) + aoff + m * 2048 + k * 1024); } while (0)
; #define PG8_LDB(dst, b, h) do { _Pragma("unroll") for (int n = 0; n < 2; ++n) _Pragma("unroll") for (int k = 0; k < 2; ++k) dst[n][k] = *(const LAS bf16x8*)(lds + PG8_SB(b, h) + boff + n * 2048 + k * 1024); } while (0)
; #define PG8_MMA(ai, bj, At, Bt) do { __builtin_amdgcn_s_setprio(1); _Pragma("unroll") for (int m = 0; m < 4; ++m) _Pragma("unroll") for (int n = 0; n < 2; ++n) _Pragma("unroll") for (int k = 0; k < 2; ++k) \
;         acc[ai][bj][m][n] = __builtin_amdgcn_mfma_f32_16x16x32_bf16(Bt[n][k], At[m][k], acc[ai][bj][m][n], 0, 0, 0); __builtin_amdgcn_s_setprio(0); } while (0)
; #define PG8_WAIT_V(n) asm volatile("s_waitcnt vmcnt(" #n ")" ::: "memory")
; #define PG8_WAIT_L(n) asm volatile("s_waitcnt lgkmcnt(" #n ")" ::: "memory")
; #define PG8_BAR __builtin_amdgcn_s_barrier()
; #define PG8_SCHED __builtin_amdgcn_sched_barrier(0)
;     ...
;             PG8_WAIT_V(8); PG8_WAIT_L(0); PG8_BAR; PG8_MMA(1, 0, At, B0); PG8_MMA(1, 1, At, B1); PG8_BAR; PG8_SCHED;
;             PG8_LDB(B0, 1, 0); PG8_LDB(B1, 1, 1); PG8_SCHED; PG8_LDA(At, 1, 0); PG8_STAGE(PG8_SA(0, 1), a2 + hA, voffA);
;             PG8_WAIT_V(8); PG8_WAIT_L(0); PG8_BAR; PG8_MMA(0, 0, At, B0); PG8_MMA(0, 1, At, B1); PG8_BAR; PG8_SCHED;
	s_setprio 1
	s_waitcnt lgkmcnt(0)
	v_mfma_f32_16x16x32_bf16 v[68:71], v[16:19], v[188:191], v[68:71]
	v_mfma_f32_16x16x32_bf16 v[68:71], v[24:27], v[192:195], v[68:71]
	v_mfma_f32_16x16x32_bf16 v[52:55], v[24:27], v[200:203], v[52:55]
	v_mfma_f32_16x16x32_bf16 v[52:55], v[16:19], v[196:199], v[52:55]
	v_mfma_f32_16x16x32_bf16 v[36:39], v[16:19], v[208:211], v[36:39]
	v_mfma_f32_16x16x32_bf16 v[36:39], v[24:27], v[214:217], v[36:39]
	v_mfma_f32_16x16x32_bf16 v[12:15], v[24:27], v[234:237], v[12:15]
	v_mfma_f32_16x16x32_bf16 v[12:15], v[16:19], v[230:233], v[12:15]
	v_mfma_f32_16x16x32_bf16 v[8:11], v[120:123], v[230:233], v[8:11]
	v_mfma_f32_16x16x32_bf16 v[8:11], v[132:135], v[234:237], v[8:11]
	v_mfma_f32_16x16x32_bf16 v[32:35], v[132:135], v[214:217], v[32:35]
	v_mfma_f32_16x16x32_bf16 v[32:35], v[120:123], v[208:211], v[32:35]
	v_mfma_f32_16x16x32_bf16 v[48:51], v[120:123], v[196:199], v[48:51]
	v_mfma_f32_16x16x32_bf16 v[48:51], v[132:135], v[200:203], v[48:51]
	v_mfma_f32_16x16x32_bf16 v[64:67], v[132:135], v[192:195], v[64:67]
	v_mfma_f32_16x16x32_bf16 v[64:67], v[120:123], v[188:191], v[64:67]
	s_setprio 0
	s_setprio 1
	v_mfma_f32_16x16x32_bf16 v[44:47], v[140:143], v[196:199], v[44:47]
	v_mfma_f32_16x16x32_bf16 v[44:47], v[148:151], v[200:203], v[44:47]
	v_mfma_f32_16x16x32_bf16 v[40:43], v[176:179], v[196:199], v[40:43]
	v_mfma_f32_16x16x32_bf16 v[40:43], v[184:187], v[200:203], v[40:43]
	v_mfma_f32_16x16x32_bf16 v[28:31], v[140:143], v[208:211], v[28:31]
	v_mfma_f32_16x16x32_bf16 v[28:31], v[148:151], v[214:217], v[28:31]
	v_mfma_f32_16x16x32_bf16 v[20:23], v[176:179], v[208:211], v[20:23]
	v_mfma_f32_16x16x32_bf16 v[20:23], v[184:187], v[214:217], v[20:23]
	v_mfma_f32_16x16x32_bf16 v[4:7], v[140:143], v[230:233], v[4:7]
	v_mfma_f32_16x16x32_bf16 v[4:7], v[148:151], v[234:237], v[4:7]
	v_mfma_f32_16x16x32_bf16 v[0:3], v[176:179], v[230:233], v[0:3]
	v_mfma_f32_16x16x32_bf16 v[0:3], v[184:187], v[234:237], v[0:3]
	v_mfma_f32_16x16x32_bf16 v[16:19], v[140:143], v[188:191], v[60:63]
	v_mfma_f32_16x16x32_bf16 v[16:19], v[148:151], v[192:195], v[16:19]
	v_mfma_f32_16x16x32_bf16 v[24:27], v[176:179], v[188:191], v[56:59]
	v_mfma_f32_16x16x32_bf16 v[24:27], v[184:187], v[192:195], v[24:27]
	s_setprio 0
	s_barrier
	s_add_i32 s17, 0, 0x18000
	s_add_i32 s36, 0, 0x1c000
	v_add_u32_e32 v132, s17, v182
	v_add_u32_e32 v184, s36, v182
	ds_read_b128 v[56:59], v132
	ds_read_b128 v[60:63], v132 offset:1024
	ds_read_b128 v[120:123], v132 offset:2048
	ds_read_b128 v[132:135], v132 offset:3072
	ds_read_b128 v[140:143], v184
	ds_read_b128 v[148:151], v184 offset:1024
	ds_read_b128 v[176:179], v184 offset:2048
	ds_read_b128 v[184:187], v184 offset:3072
	s_add_u32 s2, s76, 0x10000
	s_addc_u32 s3, s77, 0
	s_mov_b32 m0, s44
	v_lshl_add_u64 v[206:207], s[2:3], 0, v[152:153]
	ds_read_b128 v[188:191], v183 offset:32768
	ds_read_b128 v[192:195], v183 offset:33792
	ds_read_b128 v[196:199], v183 offset:34816
	ds_read_b128 v[200:203], v183 offset:35840
	ds_read_b128 v[208:211], v183 offset:36864
	ds_read_b128 v[214:217], v183 offset:37888
	ds_read_b128 v[230:233], v183 offset:38912
	ds_read_b128 v[234:237], v183 offset:39936
	global_load_lds_dwordx4 v[206:207], off
	v_lshl_add_u64 v[206:207], s[2:3], 0, v[154:155]
	s_mov_b32 m0, s45
	s_nop 0
	global_load_lds_dwordx4 v[206:207], off
	s_waitcnt vmcnt(8)
	s_waitcnt lgkmcnt(0)
	s_barrier
	s_setprio 1
	s_waitcnt lgkmcnt(0)
	v_mfma_f32_16x16x32_bf16 v[144:147], v[56:59], v[188:191], v[144:147]
	v_mfma_f32_16x16x32_bf16 v[144:147], v[60:63], v[192:195], v[144:147]
	v_mfma_f32_16x16x32_bf16 v[116:119], v[60:63], v[200:203], v[116:119]
	v_mfma_f32_16x16x32_bf16 v[116:119], v[56:59], v[196:199], v[116:119]
	v_mfma_f32_16x16x32_bf16 v[100:103], v[56:59], v[208:211], v[100:103]
	v_mfma_f32_16x16x32_bf16 v[100:103], v[60:63], v[214:217], v[100:103]
	v_mfma_f32_16x16x32_bf16 v[84:87], v[60:63], v[234:237], v[84:87]
	v_mfma_f32_16x16x32_bf16 v[84:87], v[56:59], v[230:233], v[84:87]
	v_mfma_f32_16x16x32_bf16 v[80:83], v[120:123], v[230:233], v[80:83]
	v_mfma_f32_16x16x32_bf16 v[80:83], v[132:135], v[234:237], v[80:83]
	v_mfma_f32_16x16x32_bf16 v[96:99], v[132:135], v[214:217], v[96:99]
	v_mfma_f32_16x16x32_bf16 v[96:99], v[120:123], v[208:211], v[96:99]
	v_mfma_f32_16x16x32_bf16 v[112:115], v[120:123], v[196:199], v[112:115]
	v_mfma_f32_16x16x32_bf16 v[112:115], v[132:135], v[200:203], v[112:115]
	v_mfma_f32_16x16x32_bf16 v[136:139], v[132:135], v[192:195], v[136:139]
	v_mfma_f32_16x16x32_bf16 v[136:139], v[120:123], v[188:191], v[136:139]
	s_setprio 0
	s_setprio 1
	v_mfma_f32_16x16x32_bf16 v[128:131], v[140:143], v[188:191], v[128:131]
	v_mfma_f32_16x16x32_bf16 v[128:131], v[148:151], v[192:195], v[128:131]
	v_mfma_f32_16x16x32_bf16 v[108:111], v[148:151], v[200:203], v[108:111]
	v_mfma_f32_16x16x32_bf16 v[108:111], v[140:143], v[196:199], v[108:111]
	v_mfma_f32_16x16x32_bf16 v[92:95], v[140:143], v[208:211], v[92:95]
	v_mfma_f32_16x16x32_bf16 v[92:95], v[148:151], v[214:217], v[92:95]
	v_mfma_f32_16x16x32_bf16 v[76:79], v[148:151], v[234:237], v[76:79]
	v_mfma_f32_16x16x32_bf16 v[76:79], v[140:143], v[230:233], v[76:79]
	v_mfma_f32_16x16x32_bf16 v[72:75], v[176:179], v[230:233], v[72:75]
	v_mfma_f32_16x16x32_bf16 v[72:75], v[184:187], v[234:237], v[72:75]
	v_mfma_f32_16x16x32_bf16 v[88:91], v[184:187], v[214:217], v[88:91]
	v_mfma_f32_16x16x32_bf16 v[88:91], v[176:179], v[208:211], v[88:91]
	v_mfma_f32_16x16x32_bf16 v[104:107], v[176:179], v[196:199], v[104:107]
	v_mfma_f32_16x16x32_bf16 v[104:107], v[184:187], v[200:203], v[104:107]
	v_mfma_f32_16x16x32_bf16 v[124:127], v[184:187], v[192:195], v[124:127]
	v_mfma_f32_16x16x32_bf16 v[124:127], v[176:179], v[188:191], v[124:127]
	s_setprio 0
	s_barrier
; #define PG8_STAGE(bufoff, gbase, voff) do { _Pragma("unroll") for (int _i = 0; _i < 2; ++_i) \
;         __builtin_amdgcn_global_load_lds((const unsigned*)((const char*)(gbase) + (voff)[_i]), (LAS unsigned*)(lds + (bufoff) + ldsw + _i * 8192), 16, 0, 0); } while (0)
; #define PG8_LDA(dst, b, h) do { _Pragma("unroll") for (int m = 0; m < 4; ++m) _Pragma("unroll") for (int k = 0; k < 2; ++k) dst[m][k] = *(const LAS bf16x8*)(lds + PG8_SA(b, h) + aoff + m * 2048 + k * 1024); } while (0)
; #define PG8_MMA(ai, bj, At, Bt) do { __builtin_amdgcn_s_setprio(1); _Pragma("unroll") for (int m = 0; m < 4; ++m) _Pragma("unroll") for (int n = 0; n < 2; ++n) _Pragma("unroll") for (int k = 0; k < 2; ++k) \
;         acc[ai][bj][m][n] = __builtin_amdgcn_mfma_f32_16x16x32_bf16(Bt[n][k], At[m][k], acc[ai][bj][m][n], 0, 0, 0); __builtin_amdgcn_s_setprio(0); } while (0)
; #define PG8_WAIT_V(n) asm volatile("s_waitcnt vmcnt(" #n ")" ::: "memory")
; #define PG8_WAIT_L(n) asm volatile("s_waitcnt lgkmcnt(" #n ")" ::: "memory")
; #define PG8_BAR __builtin_amdgcn_s_barrier()
; #define PG8_SCHED __builtin_amdgcn_sched_barrier(0)
;     ...
;         for (int t = 0; t < nt; t += 2) {
;             const bool last = (t == nt - 2);
;     ...
;             PG8_LDA(At, 1, 1); PG8_STAGE(PG8_SB(1, 0), b3, voffB); PG8_STAGE(PG8_SB(1, 1), b3 + hB, voffB); PG8_STAGE(PG8_SA(1, 0), a3, voffA);
;             PG8_WAIT_V(8); PG8_WAIT_L(0); PG8_BAR; PG8_MMA(1, 0, At, B0); PG8_MMA(1, 1, At, B1); PG8_BAR; PG8_SCHED;
	s_add_i32 s2, s17, s93
	v_lshl_add_u64 v[180:181], v[180:181], 0, s[38:39]
	s_mov_b32 m0, s2
	ds_read_b128 v[188:191], v183 offset:49152
	ds_read_b128 v[192:195], v183 offset:50176
	ds_read_b128 v[196:199], v183 offset:51200
	ds_read_b128 v[200:203], v183 offset:52224
	ds_read_b128 v[208:211], v183 offset:53248
	ds_read_b128 v[214:217], v183 offset:54272
	ds_read_b128 v[230:233], v183 offset:55296
	ds_read_b128 v[234:237], v183 offset:56320
	global_load_lds_dwordx4 v[180:181], off
	s_add_i32 m0, s2, 0x2000
	s_add_u32 s2, s72, 0x18080
	v_lshl_add_u64 v[180:181], v[204:205], 0, s[38:39]
	s_addc_u32 s3, s73, 0
	s_add_i32 s17, s36, s93
	global_load_lds_dwordx4 v[180:181], off
	v_lshl_add_u64 v[180:181], s[2:3], 0, v[156:157]
	s_mov_b32 m0, s17
	s_nop 0
	global_load_lds_dwordx4 v[180:181], off
	v_lshl_add_u64 v[180:181], s[2:3], 0, v[168:169]
	s_add_i32 m0, s17, 0x2000
	s_nop 0
	global_load_lds_dwordx4 v[180:181], off
	v_lshl_add_u64 v[180:181], s[74:75], 0, v[152:153]
	s_mov_b32 m0, s51
	s_nop 0
	global_load_lds_dwordx4 v[180:181], off
	v_lshl_add_u64 v[180:181], s[74:75], 0, v[154:155]
	s_mov_b32 m0, s50
	s_nop 0
	global_load_lds_dwordx4 v[180:181], off
	s_waitcnt vmcnt(8)
	s_waitcnt lgkmcnt(0)
	s_barrier
	s_setprio 1
	s_waitcnt lgkmcnt(0)
	v_mfma_f32_16x16x32_bf16 v[68:71], v[56:59], v[188:191], v[68:71]
	v_mfma_f32_16x16x32_bf16 v[68:71], v[60:63], v[192:195], v[68:71]
	v_mfma_f32_16x16x32_bf16 v[52:55], v[60:63], v[200:203], v[52:55]
	v_mfma_f32_16x16x32_bf16 v[52:55], v[56:59], v[196:199], v[52:55]
	v_mfma_f32_16x16x32_bf16 v[36:39], v[56:59], v[208:211], v[36:39]
	v_mfma_f32_16x16x32_bf16 v[36:39], v[60:63], v[214:217], v[36:39]
	v_mfma_f32_16x16x32_bf16 v[12:15], v[60:63], v[234:237], v[12:15]
	v_mfma_f32_16x16x32_bf16 v[12:15], v[56:59], v[230:233], v[12:15]
	v_mfma_f32_16x16x32_bf16 v[8:11], v[120:123], v[230:233], v[8:11]
	v_mfma_f32_16x16x32_bf16 v[8:11], v[132:135], v[234:237], v[8:11]
	v_mfma_f32_16x16x32_bf16 v[32:35], v[132:135], v[214:217], v[32:35]
	v_mfma_f32_16x16x32_bf16 v[32:35], v[120:123], v[208:211], v[32:35]
	v_mfma_f32_16x16x32_bf16 v[48:51], v[120:123], v[196:199], v[48:51]
	v_mfma_f32_16x16x32_bf16 v[48:51], v[132:135], v[200:203], v[48:51]
	v_mfma_f32_16x16x32_bf16 v[64:67], v[132:135], v[192:195], v[64:67]
	v_mfma_f32_16x16x32_bf16 v[64:67], v[120:123], v[188:191], v[64:67]
	s_setprio 0
	s_setprio 1
	v_mfma_f32_16x16x32_bf16 v[16:19], v[140:143], v[188:191], v[16:19]
	v_mfma_f32_16x16x32_bf16 v[60:63], v[148:151], v[192:195], v[16:19]
	v_mfma_f32_16x16x32_bf16 v[16:19], v[176:179], v[188:191], v[24:27]
	v_mfma_f32_16x16x32_bf16 v[56:59], v[184:187], v[192:195], v[16:19]
	v_mfma_f32_16x16x32_bf16 v[16:19], v[140:143], v[196:199], v[44:47]
	v_mfma_f32_16x16x32_bf16 v[44:47], v[148:151], v[200:203], v[16:19]
	v_mfma_f32_16x16x32_bf16 v[16:19], v[176:179], v[196:199], v[40:43]
	v_mfma_f32_16x16x32_bf16 v[40:43], v[184:187], v[200:203], v[16:19]
	v_mfma_f32_16x16x32_bf16 v[16:19], v[140:143], v[208:211], v[28:31]
	v_mfma_f32_16x16x32_bf16 v[28:31], v[148:151], v[214:217], v[16:19]
	v_mfma_f32_16x16x32_bf16 v[16:19], v[176:179], v[208:211], v[20:23]
	v_mfma_f32_16x16x32_bf16 v[4:7], v[140:143], v[230:233], v[4:7]
	v_mfma_f32_16x16x32_bf16 v[0:3], v[176:179], v[230:233], v[0:3]
	v_mfma_f32_16x16x32_bf16 v[20:23], v[184:187], v[214:217], v[16:19]
	v_mfma_f32_16x16x32_bf16 v[4:7], v[148:151], v[234:237], v[4:7]
	v_mfma_f32_16x16x32_bf16 v[0:3], v[184:187], v[234:237], v[0:3]
	s_setprio 0
	s_barrier
	s_add_u32 s90, s90, 0x100
	s_addc_u32 s91, s91, 0
	s_add_u32 s9, s9, 0x100
	s_addc_u32 s13, s13, 0
	s_cmp_gt_u32 s15, 3
	s_mov_b32 s72, s15
	s_cbranch_scc1 .LBB0_103

; #define PG8_STAGE(bufoff, gbase, voff) do { _Pragma("unroll") for (int _i = 0; _i < 2; ++_i) \
;         __builtin_amdgcn_global_load_lds((const unsigned*)((const char*)(gbase) + (voff)[_i]), (LAS unsigned*)(lds + (bufoff) + ldsw + _i * 8192), 16, 0, 0); } while (0)
; #define PG8_LDA(dst, b, h) do { _Pragma("unroll") for (int m = 0; m < 4; ++m) _Pragma("unroll") for (int k = 0; k < 2; ++k) dst[m][k] = *(const LAS bf16x8*)(lds + PG8_SA(b, h) + aoff + m * 2048 + k * 1024); } while (0)
; #define PG8_LDB(dst, b, h) do { _Pragma("unroll") for (int n = 0; n < 2; ++n) _Pragma("unroll") for (int k = 0; k < 2; ++k) dst[n][k] = *(const LAS bf16x8*)(lds + PG8_SB(b, h) + boff + n * 2048 + k * 1024); } while (0)
; #define PG8_MMA(ai, bj, At, Bt) do { __builtin_amdgcn_s_setprio(1); _Pragma("unroll") for (int m = 0; m < 4; ++m) _Pragma("unroll") for (int n = 0; n < 2; ++n) _Pragma("unroll") for (int k = 0; k < 2; ++k) \
;         acc[ai][bj][m][n] = __builtin_amdgcn_mfma_f32_16x16x32_bf16(Bt[n][k], At[m][k], acc[ai][bj][m][n], 0, 0, 0); __builtin_amdgcn_s_setprio(0); } while (0)
; #define PG8_WAIT_V(n) asm volatile("s_waitcnt vmcnt(" #n ")" ::: "memory")
; #define PG8_WAIT_L(n) asm volatile("s_waitcnt lgkmcnt(" #n ")" ::: "memory")
; #define PG8_BAR __builtin_amdgcn_s_barrier()
;     ...
;         const bool has_next = S.next(ui + 1, nxt);
;         const char* nA = has_next ? oa.base + (size_t)nxt.pm * oa.tstep : cA; const char* nA2 = has_next ? oa.base2 + (size_t)nxt.pm * oa.tstep : cA2; const char* nB = has_next ? ob.base + (size_t)nxt.pn * ob.tstep : cB;
; #pragma nounroll
;         for (int t = 0; t < nt; t += 2) {
;             const bool last = (t == nt - 2);
;             const char* a1 = PG8_ATILE(cA, cA2, t + 1);
;             const char* a2 = last ? nA : PG8_ATILE(cA, cA2, t + 2); const char* b2 = last ? nB : cB + (size_t)(t + 2) * 128;
;             const char* a3 = last ? nA + kA1 : PG8_ATILE(cA, cA2, t + 3); const char* b3 = b2 + kB1;
;             if constexpr (SP2) {
;             PG8_LDB(B0, 0, 0); PG8_LDB(B1, 0, 1); PG8_SCHED; PG8_LDA(At, 0, 0); PG8_STAGE(PG8_SA(1, 1), a1 + hA, voffA);
;             PG8_WAIT_V(8); PG8_WAIT_L(0); PG8_BAR; PG8_MMA(0, 0, At, B0); PG8_MMA(0, 1, At, B1); PG8_BAR; PG8_SCHED;
;             PG8_LDA(At, 0, 1); PG8_STAGE(PG8_SB(0, 0), b2, voffB); PG8_STAGE(PG8_SB(0, 1), b2 + hB, voffB); PG8_STAGE(PG8_SA(0, 0), a2, voffA);
.LBB0_119:
	s_add_u32 s2, s52, s94
	s_addc_u32 s3, s53, s95
	s_add_u32 s76, s2, 0x100
	s_addc_u32 s77, s3, 0
	s_add_u32 s74, s80, s94
	s_addc_u32 s75, s81, s95
	s_add_u32 s2, s2, 0x180
	s_addc_u32 s3, s3, 0
	s_add_i32 vcc_hi, 0, 0x10000
	s_add_i32 s12, 0, 0x14000
	v_add_u32_e32 v155, vcc_hi, v153
	ds_read_b128 v[168:171], v155
	ds_read_b128 v[172:175], v155 offset:1024
	ds_read_b128 v[176:179], v155 offset:2048
	ds_read_b128 v[180:183], v155 offset:3072
	v_add_u32_e32 v155, s12, v153
	ds_read_b128 v[184:187], v155
	ds_read_b128 v[188:191], v155 offset:1024
	ds_read_b128 v[192:195], v155 offset:2048
	ds_read_b128 v[196:199], v155 offset:3072
	s_cmpk_eq_i32 s94, 0x300
	s_cselect_b32 s73, s97, s3
	s_cselect_b32 s72, s96, s2
	s_cselect_b32 s75, s82, s75
	s_cselect_b32 s74, s91, s74
	s_cselect_b32 s77, s83, s77
	s_cselect_b32 s76, s89, s76
	v_lshl_add_u64 v[204:205], v[142:143], 0, s[94:95]
	s_add_i32 m0, s1, 0xc000
	ds_read_b128 v[208:211], v154
	ds_read_b128 v[214:217], v154 offset:1024
	ds_read_b128 v[230:233], v154 offset:2048
	ds_read_b128 v[234:237], v154 offset:3072
	ds_read_b128 v[238:241], v154 offset:4096
	ds_read_b128 v[242:245], v154 offset:5120
	ds_read_b128 v[246:249], v154 offset:6144
	ds_read_b128 v[200:203], v154 offset:7168
	global_load_lds_dwordx4 v[204:205], off
	v_lshl_add_u64 v[204:205], v[144:145], 0, s[94:95]
	s_add_i32 m0, s1, 0xe000
	s_nop 0
	global_load_lds_dwordx4 v[204:205], off
	s_waitcnt vmcnt(8)
	s_waitcnt lgkmcnt(0)
	s_barrier
	s_setprio 1
	s_waitcnt lgkmcnt(0)
	v_mfma_f32_16x16x32_bf16 v[124:127], v[168:171], v[208:211], v[124:127]
	v_mfma_f32_16x16x32_bf16 v[124:127], v[172:175], v[214:217], v[124:127]
	v_mfma_f32_16x16x32_bf16 v[116:119], v[172:175], v[234:237], v[116:119]
	v_mfma_f32_16x16x32_bf16 v[116:119], v[168:171], v[230:233], v[116:119]
	v_mfma_f32_16x16x32_bf16 v[108:111], v[168:171], v[238:241], v[108:111]
	v_mfma_f32_16x16x32_bf16 v[108:111], v[172:175], v[242:245], v[108:111]
	v_mfma_f32_16x16x32_bf16 v[92:95], v[172:175], v[200:203], v[92:95]
	v_mfma_f32_16x16x32_bf16 v[92:95], v[168:171], v[246:249], v[92:95]
	v_mfma_f32_16x16x32_bf16 v[84:87], v[176:179], v[246:249], v[84:87]
	v_mfma_f32_16x16x32_bf16 v[84:87], v[180:183], v[200:203], v[84:87]
	v_mfma_f32_16x16x32_bf16 v[100:103], v[180:183], v[242:245], v[100:103]
	v_mfma_f32_16x16x32_bf16 v[100:103], v[176:179], v[238:241], v[100:103]
	v_mfma_f32_16x16x32_bf16 v[112:115], v[176:179], v[230:233], v[112:115]
	v_mfma_f32_16x16x32_bf16 v[112:115], v[180:183], v[234:237], v[112:115]
	v_mfma_f32_16x16x32_bf16 v[120:123], v[180:183], v[214:217], v[120:123]
	v_mfma_f32_16x16x32_bf16 v[120:123], v[176:179], v[208:211], v[120:123]
	s_setprio 0
	s_setprio 1
	v_mfma_f32_16x16x32_bf16 v[104:107], v[184:187], v[208:211], v[104:107]
	v_mfma_f32_16x16x32_bf16 v[104:107], v[188:191], v[214:217], v[104:107]
	v_mfma_f32_16x16x32_bf16 v[88:91], v[188:191], v[234:237], v[88:91]
	v_mfma_f32_16x16x32_bf16 v[88:91], v[184:187], v[230:233], v[88:91]
	v_mfma_f32_16x16x32_bf16 v[76:79], v[184:187], v[238:241], v[76:79]
	v_mfma_f32_16x16x32_bf16 v[76:79], v[188:191], v[242:245], v[76:79]
	v_mfma_f32_16x16x32_bf16 v[68:71], v[188:191], v[200:203], v[68:71]
	v_mfma_f32_16x16x32_bf16 v[68:71], v[184:187], v[246:249], v[68:71]
	v_mfma_f32_16x16x32_bf16 v[64:67], v[192:195], v[246:249], v[64:67]
	v_mfma_f32_16x16x32_bf16 v[64:67], v[196:199], v[200:203], v[64:67]
	v_mfma_f32_16x16x32_bf16 v[72:75], v[196:199], v[242:245], v[72:75]
	v_mfma_f32_16x16x32_bf16 v[72:75], v[192:195], v[238:241], v[72:75]
	v_mfma_f32_16x16x32_bf16 v[80:83], v[192:195], v[230:233], v[80:83]
	v_mfma_f32_16x16x32_bf16 v[80:83], v[196:199], v[234:237], v[80:83]
	v_mfma_f32_16x16x32_bf16 v[96:99], v[196:199], v[214:217], v[96:99]
	v_mfma_f32_16x16x32_bf16 v[96:99], v[192:195], v[208:211], v[96:99]
	s_setprio 0
	s_barrier
	s_add_i32 s2, vcc_hi, s0
	v_lshl_add_u64 v[204:205], s[74:75], 0, v[130:131]
	s_mov_b32 m0, s2
	ds_read_b128 v[200:203], v154 offset:16384
	ds_read_b128 v[208:211], v154 offset:17408
	ds_read_b128 v[214:217], v154 offset:18432
	ds_read_b128 v[230:233], v154 offset:19456
	ds_read_b128 v[234:237], v154 offset:20480
	ds_read_b128 v[238:241], v154 offset:21504
	ds_read_b128 v[242:245], v154 offset:22528
	ds_read_b128 v[246:249], v154 offset:23552
	global_load_lds_dwordx4 v[204:205], off
	s_add_i32 m0, s2, 0x2000
	s_add_u32 s2, s74, 0x20000
	v_lshl_add_u64 v[206:207], s[74:75], 0, v[134:135]
	s_addc_u32 s3, s75, 0
	s_add_i32 s12, s12, s0
	global_load_lds_dwordx4 v[206:207], off
	v_lshl_add_u64 v[250:251], s[2:3], 0, v[130:131]
	s_mov_b32 m0, s12
	s_nop 0
	global_load_lds_dwordx4 v[250:251], off
	v_lshl_add_u64 v[250:251], s[2:3], 0, v[134:135]
	s_add_i32 m0, s12, 0x2000
	s_nop 0
	global_load_lds_dwordx4 v[250:251], off
	v_lshl_add_u64 v[250:251], s[76:77], 0, v[128:129]
	s_mov_b32 m0, s1
	s_nop 0
	global_load_lds_dwordx4 v[250:251], off
	v_lshl_add_u64 v[250:251], s[76:77], 0, v[132:133]
	s_mov_b32 m0, s4
	s_nop 0
	global_load_lds_dwordx4 v[250:251], off
	s_waitcnt vmcnt(8)
	s_waitcnt lgkmcnt(0)
	s_barrier
; #define PG8_STAGE(bufoff, gbase, voff) do { _Pragma("unroll") for (int _i = 0; _i < 2; ++_i) \
;         __builtin_amdgcn_global_load_lds((const unsigned*)((const char*)(gbase) + (voff)[_i]), (LAS unsigned*)(lds + (bufoff) + ldsw + _i * 8192), 16, 0, 0); } while (0)
; #define PG8_LDA(dst, b, h) do { _Pragma("unroll") for (int m = 0; m < 4; ++m) _Pragma("unroll") for (int k = 0; k < 2; ++k) dst[m][k] = *(const LAS bf16x8*)(lds + PG8_SA(b, h) + aoff + m * 2048 + k * 1024); } while (0)
; #define PG8_LDB(dst, b, h) do { _Pragma("unroll") for (int n = 0; n < 2; ++n) _Pragma("unroll") for (int k = 0; k < 2; ++k) dst[n][k] = *(const LAS bf16x8*)(lds + PG8_SB(b, h) + boff + n * 2048 + k * 1024); } while (0)
; #define PG8_MMA(ai, bj, At, Bt) do { __builtin_amdgcn_s_setprio(1); _Pragma("unroll") for (int m = 0; m < 4; ++m) _Pragma("unroll") for (int n = 0; n < 2; ++n) _Pragma("unroll") for (int k = 0; k < 2; ++k) \
;         acc[ai][bj][m][n] = __builtin_amdgcn_mfma_f32_16x16x32_bf16(Bt[n][k], At[m][k], acc[ai][bj][m][n], 0, 0, 0); __builtin_amdgcn_s_setprio(0); } while (0)
; #define PG8_WAIT_V(n) asm volatile("s_waitcnt vmcnt(" #n ")" ::: "memory")
; #define PG8_WAIT_L(n) asm volatile("s_waitcnt lgkmcnt(" #n ")" ::: "memory")
; #define PG8_BAR __builtin_amdgcn_s_barrier()
; #define PG8_SCHED __builtin_amdgcn_sched_barrier(0)
;     ...
;             PG8_WAIT_V(8); PG8_WAIT_L(0); PG8_BAR; PG8_MMA(1, 0, At, B0); PG8_MMA(1, 1, At, B1); PG8_BAR; PG8_SCHED;
;             PG8_LDB(B0, 1, 0); PG8_LDB(B1, 1, 1); PG8_SCHED; PG8_LDA(At, 1, 0); PG8_STAGE(PG8_SA(0, 1), a2 + hA, voffA);
;             PG8_WAIT_V(8); PG8_WAIT_L(0); PG8_BAR; PG8_MMA(0, 0, At, B0); PG8_MMA(0, 1, At, B1); PG8_BAR; PG8_SCHED;
	s_setprio 1
	s_waitcnt lgkmcnt(0)
	v_mfma_f32_16x16x32_bf16 v[60:63], v[168:171], v[200:203], v[60:63]
	v_mfma_f32_16x16x32_bf16 v[60:63], v[172:175], v[208:211], v[60:63]
	v_mfma_f32_16x16x32_bf16 v[52:55], v[172:175], v[230:233], v[52:55]
	v_mfma_f32_16x16x32_bf16 v[52:55], v[168:171], v[214:217], v[52:55]
	v_mfma_f32_16x16x32_bf16 v[44:47], v[168:171], v[234:237], v[44:47]
	v_mfma_f32_16x16x32_bf16 v[44:47], v[172:175], v[238:241], v[44:47]
	v_mfma_f32_16x16x32_bf16 v[28:31], v[172:175], v[246:249], v[28:31]
	v_mfma_f32_16x16x32_bf16 v[28:31], v[168:171], v[242:245], v[28:31]
	v_mfma_f32_16x16x32_bf16 v[20:23], v[176:179], v[242:245], v[20:23]
	v_mfma_f32_16x16x32_bf16 v[20:23], v[180:183], v[246:249], v[20:23]
	v_mfma_f32_16x16x32_bf16 v[36:39], v[180:183], v[238:241], v[36:39]
	v_mfma_f32_16x16x32_bf16 v[36:39], v[176:179], v[234:237], v[36:39]
	v_mfma_f32_16x16x32_bf16 v[48:51], v[176:179], v[214:217], v[48:51]
	v_mfma_f32_16x16x32_bf16 v[48:51], v[180:183], v[230:233], v[48:51]
	v_mfma_f32_16x16x32_bf16 v[56:59], v[180:183], v[208:211], v[56:59]
	v_mfma_f32_16x16x32_bf16 v[56:59], v[176:179], v[200:203], v[56:59]
	s_setprio 0
	s_setprio 1
	v_mfma_f32_16x16x32_bf16 v[40:43], v[184:187], v[200:203], v[40:43]
	v_mfma_f32_16x16x32_bf16 v[40:43], v[188:191], v[208:211], v[40:43]
	v_mfma_f32_16x16x32_bf16 v[24:27], v[188:191], v[230:233], v[24:27]
	v_mfma_f32_16x16x32_bf16 v[24:27], v[184:187], v[214:217], v[24:27]
	v_mfma_f32_16x16x32_bf16 v[12:15], v[184:187], v[234:237], v[12:15]
	v_mfma_f32_16x16x32_bf16 v[12:15], v[188:191], v[238:241], v[12:15]
	v_mfma_f32_16x16x32_bf16 v[4:7], v[188:191], v[246:249], v[4:7]
	v_mfma_f32_16x16x32_bf16 v[4:7], v[184:187], v[242:245], v[4:7]
	v_mfma_f32_16x16x32_bf16 v[0:3], v[192:195], v[242:245], v[0:3]
	v_mfma_f32_16x16x32_bf16 v[0:3], v[196:199], v[246:249], v[0:3]
	v_mfma_f32_16x16x32_bf16 v[8:11], v[196:199], v[238:241], v[8:11]
	v_mfma_f32_16x16x32_bf16 v[8:11], v[192:195], v[234:237], v[8:11]
	v_mfma_f32_16x16x32_bf16 v[16:19], v[192:195], v[214:217], v[16:19]
	v_mfma_f32_16x16x32_bf16 v[16:19], v[196:199], v[230:233], v[16:19]
	v_mfma_f32_16x16x32_bf16 v[32:35], v[196:199], v[208:211], v[32:35]
	v_mfma_f32_16x16x32_bf16 v[32:35], v[192:195], v[200:203], v[32:35]
	s_setprio 0
	s_barrier
	s_add_i32 s12, 0, 0x18000
	v_add_u32_e32 v155, s12, v153
	s_add_i32 s13, 0, 0x1c000
	ds_read_b128 v[168:171], v155
	ds_read_b128 v[172:175], v155 offset:1024
	ds_read_b128 v[176:179], v155 offset:2048
	ds_read_b128 v[180:183], v155 offset:3072
	v_add_u32_e32 v155, s13, v153
	ds_read_b128 v[184:187], v155
	ds_read_b128 v[188:191], v155 offset:1024
	ds_read_b128 v[192:195], v155 offset:2048
	ds_read_b128 v[196:199], v155 offset:3072
	s_add_u32 s2, s76, 0x20000
	s_addc_u32 s3, s77, 0
	s_mov_b32 m0, s5
	v_lshl_add_u64 v[250:251], s[2:3], 0, v[128:129]
	ds_read_b128 v[200:203], v154 offset:32768
	ds_read_b128 v[208:211], v154 offset:33792
	ds_read_b128 v[214:217], v154 offset:34816
	ds_read_b128 v[230:233], v154 offset:35840
	ds_read_b128 v[234:237], v154 offset:36864
	ds_read_b128 v[238:241], v154 offset:37888
	ds_read_b128 v[242:245], v154 offset:38912
	ds_read_b128 v[246:249], v154 offset:39936
	global_load_lds_dwordx4 v[250:251], off
	v_lshl_add_u64 v[250:251], s[2:3], 0, v[132:133]
	s_mov_b32 m0, s6
	s_nop 0
	global_load_lds_dwordx4 v[250:251], off
	s_waitcnt vmcnt(8)
	s_waitcnt lgkmcnt(0)
	s_barrier
	s_setprio 1
	s_waitcnt lgkmcnt(0)
	v_mfma_f32_16x16x32_bf16 v[124:127], v[168:171], v[200:203], v[124:127]
	v_mfma_f32_16x16x32_bf16 v[124:127], v[172:175], v[208:211], v[124:127]
	v_mfma_f32_16x16x32_bf16 v[116:119], v[172:175], v[230:233], v[116:119]
	v_mfma_f32_16x16x32_bf16 v[116:119], v[168:171], v[214:217], v[116:119]
	v_mfma_f32_16x16x32_bf16 v[108:111], v[168:171], v[234:237], v[108:111]
	v_mfma_f32_16x16x32_bf16 v[108:111], v[172:175], v[238:241], v[108:111]
	v_mfma_f32_16x16x32_bf16 v[92:95], v[172:175], v[246:249], v[92:95]
	v_mfma_f32_16x16x32_bf16 v[92:95], v[168:171], v[242:245], v[92:95]
	v_mfma_f32_16x16x32_bf16 v[84:87], v[176:179], v[242:245], v[84:87]
	v_mfma_f32_16x16x32_bf16 v[84:87], v[180:183], v[246:249], v[84:87]
	v_mfma_f32_16x16x32_bf16 v[100:103], v[180:183], v[238:241], v[100:103]
	v_mfma_f32_16x16x32_bf16 v[100:103], v[176:179], v[234:237], v[100:103]
	v_mfma_f32_16x16x32_bf16 v[112:115], v[176:179], v[214:217], v[112:115]
	v_mfma_f32_16x16x32_bf16 v[112:115], v[180:183], v[230:233], v[112:115]
	v_mfma_f32_16x16x32_bf16 v[120:123], v[180:183], v[208:211], v[120:123]
	v_mfma_f32_16x16x32_bf16 v[120:123], v[176:179], v[200:203], v[120:123]
	s_setprio 0
	s_setprio 1
	v_mfma_f32_16x16x32_bf16 v[104:107], v[184:187], v[200:203], v[104:107]
	v_mfma_f32_16x16x32_bf16 v[104:107], v[188:191], v[208:211], v[104:107]
	v_mfma_f32_16x16x32_bf16 v[88:91], v[188:191], v[230:233], v[88:91]
	v_mfma_f32_16x16x32_bf16 v[88:91], v[184:187], v[214:217], v[88:91]
	v_mfma_f32_16x16x32_bf16 v[76:79], v[184:187], v[234:237], v[76:79]
	v_mfma_f32_16x16x32_bf16 v[76:79], v[188:191], v[238:241], v[76:79]
	v_mfma_f32_16x16x32_bf16 v[68:71], v[188:191], v[246:249], v[68:71]
	v_mfma_f32_16x16x32_bf16 v[68:71], v[184:187], v[242:245], v[68:71]
	v_mfma_f32_16x16x32_bf16 v[64:67], v[192:195], v[242:245], v[64:67]
	v_mfma_f32_16x16x32_bf16 v[64:67], v[196:199], v[246:249], v[64:67]
	v_mfma_f32_16x16x32_bf16 v[72:75], v[196:199], v[238:241], v[72:75]
	v_mfma_f32_16x16x32_bf16 v[72:75], v[192:195], v[234:237], v[72:75]
	v_mfma_f32_16x16x32_bf16 v[80:83], v[192:195], v[214:217], v[80:83]
	v_mfma_f32_16x16x32_bf16 v[80:83], v[196:199], v[230:233], v[80:83]
	v_mfma_f32_16x16x32_bf16 v[96:99], v[196:199], v[208:211], v[96:99]
	v_mfma_f32_16x16x32_bf16 v[96:99], v[192:195], v[200:203], v[96:99]
	s_setprio 0
	s_barrier
; #define PG8_STAGE(bufoff, gbase, voff) do { _Pragma("unroll") for (int _i = 0; _i < 2; ++_i) \
;         __builtin_amdgcn_global_load_lds((const unsigned*)((const char*)(gbase) + (voff)[_i]), (LAS unsigned*)(lds + (bufoff) + ldsw + _i * 8192), 16, 0, 0); } while (0)
; #define PG8_LDA(dst, b, h) do { _Pragma("unroll") for (int m = 0; m < 4; ++m) _Pragma("unroll") for (int k = 0; k < 2; ++k) dst[m][k] = *(const LAS bf16x8*)(lds + PG8_SA(b, h) + aoff + m * 2048 + k * 1024); } while (0)
; #define PG8_MMA(ai, bj, At, Bt) do { __builtin_amdgcn_s_setprio(1); _Pragma("unroll") for (int m = 0; m < 4; ++m) _Pragma("unroll") for (int n = 0; n < 2; ++n) _Pragma("unroll") for (int k = 0; k < 2; ++k) \
;         acc[ai][bj][m][n] = __builtin_amdgcn_mfma_f32_16x16x32_bf16(Bt[n][k], At[m][k], acc[ai][bj][m][n], 0, 0, 0); __builtin_amdgcn_s_setprio(0); } while (0)
; #define PG8_WAIT_V(n) asm volatile("s_waitcnt vmcnt(" #n ")" ::: "memory")
; #define PG8_WAIT_L(n) asm volatile("s_waitcnt lgkmcnt(" #n ")" ::: "memory")
; #define PG8_BAR __builtin_amdgcn_s_barrier()
; #define PG8_SCHED __builtin_amdgcn_sched_barrier(0)
;     ...
;         for (int t = 0; t < nt; t += 2) {
;             const bool last = (t == nt - 2);
;     ...
;             PG8_LDA(At, 1, 1); PG8_STAGE(PG8_SB(1, 0), b3, voffB); PG8_STAGE(PG8_SB(1, 1), b3 + hB, voffB); PG8_STAGE(PG8_SA(1, 0), a3, voffA);
;             PG8_WAIT_V(8); PG8_WAIT_L(0); PG8_BAR; PG8_MMA(1, 0, At, B0); PG8_MMA(1, 1, At, B1); PG8_BAR; PG8_SCHED;
	s_add_i32 s2, s12, s0
	v_lshl_add_u64 v[204:205], v[204:205], 0, s[38:39]
	s_mov_b32 m0, s2
	ds_read_b128 v[200:203], v154 offset:49152
	ds_read_b128 v[208:211], v154 offset:50176
	ds_read_b128 v[214:217], v154 offset:51200
	ds_read_b128 v[230:233], v154 offset:52224
	ds_read_b128 v[234:237], v154 offset:53248
	ds_read_b128 v[238:241], v154 offset:54272
	ds_read_b128 v[242:245], v154 offset:55296
	ds_read_b128 v[246:249], v154 offset:56320
	global_load_lds_dwordx4 v[204:205], off
	s_add_i32 m0, s2, 0x2000
	s_add_u32 s2, s74, 0x20080
	v_lshl_add_u64 v[204:205], v[206:207], 0, s[38:39]
	s_addc_u32 s3, s75, 0
	s_add_i32 s12, s13, s0
	global_load_lds_dwordx4 v[204:205], off
	v_lshl_add_u64 v[204:205], s[2:3], 0, v[130:131]
	s_mov_b32 m0, s12
	s_nop 0
	global_load_lds_dwordx4 v[204:205], off
	v_lshl_add_u64 v[204:205], s[2:3], 0, v[134:135]
	s_add_i32 m0, s12, 0x2000
	s_nop 0
	global_load_lds_dwordx4 v[204:205], off
	v_lshl_add_u64 v[204:205], s[72:73], 0, v[128:129]
	s_mov_b32 m0, s8
	s_nop 0
	global_load_lds_dwordx4 v[204:205], off
	v_lshl_add_u64 v[204:205], s[72:73], 0, v[132:133]
	s_mov_b32 m0, s9
	s_nop 0
	global_load_lds_dwordx4 v[204:205], off
	s_waitcnt vmcnt(8)
	s_waitcnt lgkmcnt(0)
	s_barrier
	s_setprio 1
	s_waitcnt lgkmcnt(0)
	v_mfma_f32_16x16x32_bf16 v[60:63], v[168:171], v[200:203], v[60:63]
	v_mfma_f32_16x16x32_bf16 v[60:63], v[172:175], v[208:211], v[60:63]
	v_mfma_f32_16x16x32_bf16 v[52:55], v[172:175], v[230:233], v[52:55]
	v_mfma_f32_16x16x32_bf16 v[52:55], v[168:171], v[214:217], v[52:55]
	v_mfma_f32_16x16x32_bf16 v[44:47], v[168:171], v[234:237], v[44:47]
	v_mfma_f32_16x16x32_bf16 v[44:47], v[172:175], v[238:241], v[44:47]
	v_mfma_f32_16x16x32_bf16 v[28:31], v[172:175], v[246:249], v[28:31]
	v_mfma_f32_16x16x32_bf16 v[28:31], v[168:171], v[242:245], v[28:31]
	v_mfma_f32_16x16x32_bf16 v[20:23], v[176:179], v[242:245], v[20:23]
	v_mfma_f32_16x16x32_bf16 v[20:23], v[180:183], v[246:249], v[20:23]
	v_mfma_f32_16x16x32_bf16 v[36:39], v[180:183], v[238:241], v[36:39]
	v_mfma_f32_16x16x32_bf16 v[36:39], v[176:179], v[234:237], v[36:39]
	v_mfma_f32_16x16x32_bf16 v[48:51], v[176:179], v[214:217], v[48:51]
	v_mfma_f32_16x16x32_bf16 v[48:51], v[180:183], v[230:233], v[48:51]
	v_mfma_f32_16x16x32_bf16 v[56:59], v[180:183], v[208:211], v[56:59]
	v_mfma_f32_16x16x32_bf16 v[56:59], v[176:179], v[200:203], v[56:59]
	s_setprio 0
	s_setprio 1
	v_mfma_f32_16x16x32_bf16 v[40:43], v[184:187], v[200:203], v[40:43]
	v_mfma_f32_16x16x32_bf16 v[40:43], v[188:191], v[208:211], v[40:43]
	v_mfma_f32_16x16x32_bf16 v[24:27], v[188:191], v[230:233], v[24:27]
	v_mfma_f32_16x16x32_bf16 v[24:27], v[184:187], v[214:217], v[24:27]
	v_mfma_f32_16x16x32_bf16 v[12:15], v[184:187], v[234:237], v[12:15]
	v_mfma_f32_16x16x32_bf16 v[12:15], v[188:191], v[238:241], v[12:15]
	v_mfma_f32_16x16x32_bf16 v[4:7], v[188:191], v[246:249], v[4:7]
	v_mfma_f32_16x16x32_bf16 v[4:7], v[184:187], v[242:245], v[4:7]
	v_mfma_f32_16x16x32_bf16 v[0:3], v[192:195], v[242:245], v[0:3]
	v_mfma_f32_16x16x32_bf16 v[0:3], v[196:199], v[246:249], v[0:3]
	v_mfma_f32_16x16x32_bf16 v[8:11], v[196:199], v[238:241], v[8:11]
	v_mfma_f32_16x16x32_bf16 v[8:11], v[192:195], v[234:237], v[8:11]
	v_mfma_f32_16x16x32_bf16 v[16:19], v[192:195], v[214:217], v[16:19]
	v_mfma_f32_16x16x32_bf16 v[16:19], v[196:199], v[230:233], v[16:19]
	v_mfma_f32_16x16x32_bf16 v[32:35], v[196:199], v[208:211], v[32:35]
	v_mfma_f32_16x16x32_bf16 v[32:35], v[192:195], v[200:203], v[32:35]
	s_setprio 0
	s_barrier
	s_add_i32 vcc_lo, vcc_lo, 2
	s_add_u32 s94, s94, 0x100
	s_addc_u32 s95, s95, 0
	s_cmp_gt_u32 vcc_lo, 5
	s_cbranch_scc0 .LBB0_119
	s_and_b64 vcc, exec, s[30:31]
	s_cbranch_vccz .LBB0_122
	s_barrier

; #define PG8_STAGE(bufoff, gbase, voff) do { _Pragma("unroll") for (int _i = 0; _i < 2; ++_i) \
;         __builtin_amdgcn_global_load_lds((const unsigned*)((const char*)(gbase) + (voff)[_i]), (LAS unsigned*)(lds + (bufoff) + ldsw + _i * 8192), 16, 0, 0); } while (0)
; #define PG8_LDA(dst, b, h) do { _Pragma("unroll") for (int m = 0; m < 4; ++m) _Pragma("unroll") for (int k = 0; k < 2; ++k) dst[m][k] = *(const LAS bf16x8*)(lds + PG8_SA(b, h) + aoff + m * 2048 + k * 1024); } while (0)
; #define PG8_LDB(dst, b, h) do { _Pragma("unroll") for (int n = 0; n < 2; ++n) _Pragma("unroll") for (int k = 0; k < 2; ++k) dst[n][k] = *(const LAS bf16x8*)(lds + PG8_SB(b, h) + boff + n * 2048 + k * 1024); } while (0)
; #define PG8_MMA(ai, bj, At, Bt) do { __builtin_amdgcn_s_setprio(1); _Pragma("unroll") for (int m = 0; m < 4; ++m) _Pragma("unroll") for (int n = 0; n < 2; ++n) _Pragma("unroll") for (int k = 0; k < 2; ++k) \
;         acc[ai][bj][m][n] = __builtin_amdgcn_mfma_f32_16x16x32_bf16(Bt[n][k], At[m][k], acc[ai][bj][m][n], 0, 0, 0); __builtin_amdgcn_s_setprio(0); } while (0)
; #define PG8_WAIT_V(n) asm volatile("s_waitcnt vmcnt(" #n ")" ::: "memory")
; #define PG8_WAIT_L(n) asm volatile("s_waitcnt lgkmcnt(" #n ")" ::: "memory")
; #define PG8_BAR __builtin_amdgcn_s_barrier()
;     ...
;         const bool has_next = S.next(ui + 1, nxt);
;         const char* nA = has_next ? oa.base + (size_t)nxt.pm * oa.tstep : cA; const char* nA2 = has_next ? oa.base2 + (size_t)nxt.pm * oa.tstep : cA2; const char* nB = has_next ? ob.base + (size_t)nxt.pn * ob.tstep : cB;
; #pragma nounroll
;         for (int t = 0; t < nt; t += 2) {
;             const bool last = (t == nt - 2);
;             const char* a1 = PG8_ATILE(cA, cA2, t + 1);
;             const char* a2 = last ? nA : PG8_ATILE(cA, cA2, t + 2); const char* b2 = last ? nB : cB + (size_t)(t + 2) * 128;
;             const char* a3 = last ? nA + kA1 : PG8_ATILE(cA, cA2, t + 3); const char* b3 = b2 + kB1;
;             if constexpr (SP2) {
;             PG8_LDB(B0, 0, 0); PG8_LDB(B1, 0, 1); PG8_SCHED; PG8_LDA(At, 0, 0); PG8_STAGE(PG8_SA(1, 1), a1 + hA, voffA);
;             PG8_WAIT_V(8); PG8_WAIT_L(0); PG8_BAR; PG8_MMA(0, 0, At, B0); PG8_MMA(0, 1, At, B1); PG8_BAR; PG8_SCHED;
;             PG8_LDA(At, 0, 1); PG8_STAGE(PG8_SB(0, 0), b2, voffB); PG8_STAGE(PG8_SB(0, 1), b2 + hB, voffB); PG8_STAGE(PG8_SA(0, 0), a2, voffA);
.LBB0_155:
	s_add_u32 s29, s34, s44
	s_addc_u32 s36, s35, s45
	s_add_u32 s54, s29, 0x800000
	s_addc_u32 s55, s36, 0
	s_add_u32 s29, s29, 0xc00000
	s_addc_u32 s36, s36, 0
	s_add_i32 s82, 0, 0x10000
	s_add_i32 s83, 0, 0x14000
	v_add_u32_e32 v168, s82, v180
	v_add_u32_e32 v183, s83, v180
	ds_read_b128 v[120:123], v168
	ds_read_b128 v[132:135], v168 offset:1024
	ds_read_b128 v[140:143], v168 offset:2048
	ds_read_b128 v[168:171], v168 offset:3072
	ds_read_b128 v[172:175], v183
	ds_read_b128 v[176:179], v183 offset:1024
	ds_read_b128 v[184:187], v183 offset:2048
	ds_read_b128 v[188:191], v183 offset:3072
	s_cmp_eq_u32 s44, 0x3800000
	s_cselect_b32 s53, s8, s36
	s_cselect_b32 s52, s7, s29
	s_cselect_b32 s73, s5, s17
	s_cselect_b32 s72, s6, s9
	s_cselect_b32 s75, s1, s55
	s_cselect_b32 s74, s4, s54
	v_lshl_add_u64 v[204:205], v[110:111], 0, s[44:45]
	s_add_i32 m0, s78, 0xc000
	ds_read_b128 v[192:195], v182
	ds_read_b128 v[196:199], v182 offset:1024
	ds_read_b128 v[200:203], v182 offset:2048
	ds_read_b128 v[208:211], v182 offset:3072
	ds_read_b128 v[214:217], v182 offset:4096
	ds_read_b128 v[230:233], v182 offset:5120
	ds_read_b128 v[234:237], v182 offset:6144
	ds_read_b128 v[238:241], v182 offset:7168
	global_load_lds_dwordx4 v[204:205], off
	v_lshl_add_u64 v[204:205], v[108:109], 0, s[44:45]
	s_add_i32 m0, s78, 0xe000
	s_nop 0
	global_load_lds_dwordx4 v[204:205], off
	s_waitcnt vmcnt(8)
	s_waitcnt lgkmcnt(0)
	s_barrier
	s_setprio 1
	s_waitcnt lgkmcnt(0)
	v_mfma_f32_16x16x32_bf16 v[136:139], v[120:123], v[192:195], v[136:139]
	v_mfma_f32_16x16x32_bf16 v[136:139], v[132:135], v[196:199], v[136:139]
	v_mfma_f32_16x16x32_bf16 v[112:115], v[132:135], v[208:211], v[112:115]
	v_mfma_f32_16x16x32_bf16 v[112:115], v[120:123], v[200:203], v[112:115]
	v_mfma_f32_16x16x32_bf16 v[92:95], v[120:123], v[214:217], v[92:95]
	v_mfma_f32_16x16x32_bf16 v[92:95], v[132:135], v[230:233], v[92:95]
	v_mfma_f32_16x16x32_bf16 v[76:79], v[132:135], v[238:241], v[76:79]
	v_mfma_f32_16x16x32_bf16 v[76:79], v[120:123], v[234:237], v[76:79]
	v_mfma_f32_16x16x32_bf16 v[72:75], v[140:143], v[234:237], v[72:75]
	v_mfma_f32_16x16x32_bf16 v[72:75], v[168:171], v[238:241], v[72:75]
	v_mfma_f32_16x16x32_bf16 v[88:91], v[168:171], v[230:233], v[88:91]
	v_mfma_f32_16x16x32_bf16 v[88:91], v[140:143], v[214:217], v[88:91]
	v_mfma_f32_16x16x32_bf16 v[104:107], v[140:143], v[200:203], v[104:107]
	v_mfma_f32_16x16x32_bf16 v[104:107], v[168:171], v[208:211], v[104:107]
	v_mfma_f32_16x16x32_bf16 v[128:131], v[168:171], v[196:199], v[128:131]
	v_mfma_f32_16x16x32_bf16 v[128:131], v[140:143], v[192:195], v[128:131]
	s_setprio 0
	s_setprio 1
	v_mfma_f32_16x16x32_bf16 v[124:127], v[172:175], v[192:195], v[124:127]
	v_mfma_f32_16x16x32_bf16 v[124:127], v[176:179], v[196:199], v[124:127]
	v_mfma_f32_16x16x32_bf16 v[100:103], v[176:179], v[208:211], v[100:103]
	v_mfma_f32_16x16x32_bf16 v[100:103], v[172:175], v[200:203], v[100:103]
	v_mfma_f32_16x16x32_bf16 v[84:87], v[172:175], v[214:217], v[84:87]
	v_mfma_f32_16x16x32_bf16 v[84:87], v[176:179], v[230:233], v[84:87]
	v_mfma_f32_16x16x32_bf16 v[68:71], v[176:179], v[238:241], v[68:71]
	v_mfma_f32_16x16x32_bf16 v[68:71], v[172:175], v[234:237], v[68:71]
	v_mfma_f32_16x16x32_bf16 v[64:67], v[184:187], v[234:237], v[64:67]
	v_mfma_f32_16x16x32_bf16 v[64:67], v[188:191], v[238:241], v[64:67]
	v_mfma_f32_16x16x32_bf16 v[80:83], v[188:191], v[230:233], v[80:83]
	v_mfma_f32_16x16x32_bf16 v[80:83], v[184:187], v[214:217], v[80:83]
	v_mfma_f32_16x16x32_bf16 v[96:99], v[184:187], v[200:203], v[96:99]
	v_mfma_f32_16x16x32_bf16 v[96:99], v[188:191], v[208:211], v[96:99]
	v_mfma_f32_16x16x32_bf16 v[116:119], v[188:191], v[196:199], v[116:119]
	v_mfma_f32_16x16x32_bf16 v[116:119], v[184:187], v[192:195], v[116:119]
	s_setprio 0
	s_barrier
	s_add_i32 s29, s82, s77
	v_lshl_add_u64 v[204:205], s[72:73], 0, v[146:147]
	s_mov_b32 m0, s29
	ds_read_b128 v[192:195], v182 offset:16384
	ds_read_b128 v[196:199], v182 offset:17408
	ds_read_b128 v[200:203], v182 offset:18432
	ds_read_b128 v[208:211], v182 offset:19456
	ds_read_b128 v[214:217], v182 offset:20480
	ds_read_b128 v[230:233], v182 offset:21504
	ds_read_b128 v[234:237], v182 offset:22528
	ds_read_b128 v[238:241], v182 offset:23552
	global_load_lds_dwordx4 v[204:205], off
	s_add_i32 m0, s29, 0x2000
	s_add_u32 s54, s72, 0x40000
	v_lshl_add_u64 v[206:207], s[72:73], 0, v[150:151]
	s_addc_u32 s55, s73, 0
	s_add_i32 s29, s83, s77
	global_load_lds_dwordx4 v[206:207], off
	v_lshl_add_u64 v[242:243], s[54:55], 0, v[146:147]
	s_mov_b32 m0, s29
	s_nop 0
	global_load_lds_dwordx4 v[242:243], off
	v_lshl_add_u64 v[242:243], s[54:55], 0, v[150:151]
	s_add_i32 m0, s29, 0x2000
	s_nop 0
	global_load_lds_dwordx4 v[242:243], off
	v_lshl_add_u64 v[242:243], s[74:75], 0, v[144:145]
	s_mov_b32 m0, s78
	s_nop 0
	global_load_lds_dwordx4 v[242:243], off
	v_lshl_add_u64 v[242:243], s[74:75], 0, v[148:149]
	s_mov_b32 m0, s79
	s_nop 0
	global_load_lds_dwordx4 v[242:243], off
	s_waitcnt vmcnt(8)
	s_waitcnt lgkmcnt(0)
	s_barrier
; #define PG8_STAGE(bufoff, gbase, voff) do { _Pragma("unroll") for (int _i = 0; _i < 2; ++_i) \
;         __builtin_amdgcn_global_load_lds((const unsigned*)((const char*)(gbase) + (voff)[_i]), (LAS unsigned*)(lds + (bufoff) + ldsw + _i * 8192), 16, 0, 0); } while (0)
; #define PG8_LDA(dst, b, h) do { _Pragma("unroll") for (int m = 0; m < 4; ++m) _Pragma("unroll") for (int k = 0; k < 2; ++k) dst[m][k] = *(const LAS bf16x8*)(lds + PG8_SA(b, h) + aoff + m * 2048 + k * 1024); } while (0)
; #define PG8_LDB(dst, b, h) do { _Pragma("unroll") for (int n = 0; n < 2; ++n) _Pragma("unroll") for (int k = 0; k < 2; ++k) dst[n][k] = *(const LAS bf16x8*)(lds + PG8_SB(b, h) + boff + n * 2048 + k * 1024); } while (0)
; #define PG8_MMA(ai, bj, At, Bt) do { __builtin_amdgcn_s_setprio(1); _Pragma("unroll") for (int m = 0; m < 4; ++m) _Pragma("unroll") for (int n = 0; n < 2; ++n) _Pragma("unroll") for (int k = 0; k < 2; ++k) \
;         acc[ai][bj][m][n] = __builtin_amdgcn_mfma_f32_16x16x32_bf16(Bt[n][k], At[m][k], acc[ai][bj][m][n], 0, 0, 0); __builtin_amdgcn_s_setprio(0); } while (0)
; #define PG8_WAIT_V(n) asm volatile("s_waitcnt vmcnt(" #n ")" ::: "memory")
; #define PG8_WAIT_L(n) asm volatile("s_waitcnt lgkmcnt(" #n ")" ::: "memory")
; #define PG8_BAR __builtin_amdgcn_s_barrier()
; #define PG8_SCHED __builtin_amdgcn_sched_barrier(0)
;     ...
;             PG8_WAIT_V(8); PG8_WAIT_L(0); PG8_BAR; PG8_MMA(1, 0, At, B0); PG8_MMA(1, 1, At, B1); PG8_BAR; PG8_SCHED;
;             PG8_LDB(B0, 1, 0); PG8_LDB(B1, 1, 1); PG8_SCHED; PG8_LDA(At, 1, 0); PG8_STAGE(PG8_SA(0, 1), a2 + hA, voffA);
;             PG8_WAIT_V(8); PG8_WAIT_L(0); PG8_BAR; PG8_MMA(0, 0, At, B0); PG8_MMA(0, 1, At, B1); PG8_BAR; PG8_SCHED;
	s_setprio 1
	s_waitcnt lgkmcnt(0)
	v_mfma_f32_16x16x32_bf16 v[60:63], v[120:123], v[192:195], v[60:63]
	v_mfma_f32_16x16x32_bf16 v[60:63], v[132:135], v[196:199], v[60:63]
	v_mfma_f32_16x16x32_bf16 v[44:47], v[132:135], v[208:211], v[44:47]
	v_mfma_f32_16x16x32_bf16 v[44:47], v[120:123], v[200:203], v[44:47]
	v_mfma_f32_16x16x32_bf16 v[28:31], v[120:123], v[214:217], v[28:31]
	v_mfma_f32_16x16x32_bf16 v[28:31], v[132:135], v[230:233], v[28:31]
	v_mfma_f32_16x16x32_bf16 v[12:15], v[132:135], v[238:241], v[12:15]
	v_mfma_f32_16x16x32_bf16 v[12:15], v[120:123], v[234:237], v[12:15]
	v_mfma_f32_16x16x32_bf16 v[8:11], v[140:143], v[234:237], v[8:11]
	v_mfma_f32_16x16x32_bf16 v[8:11], v[168:171], v[238:241], v[8:11]
	v_mfma_f32_16x16x32_bf16 v[24:27], v[168:171], v[230:233], v[24:27]
	v_mfma_f32_16x16x32_bf16 v[24:27], v[140:143], v[214:217], v[24:27]
	v_mfma_f32_16x16x32_bf16 v[40:43], v[140:143], v[200:203], v[40:43]
	v_mfma_f32_16x16x32_bf16 v[40:43], v[168:171], v[208:211], v[40:43]
	v_mfma_f32_16x16x32_bf16 v[56:59], v[168:171], v[196:199], v[56:59]
	v_mfma_f32_16x16x32_bf16 v[56:59], v[140:143], v[192:195], v[56:59]
	s_setprio 0
	s_setprio 1
	v_mfma_f32_16x16x32_bf16 v[52:55], v[172:175], v[192:195], v[52:55]
	v_mfma_f32_16x16x32_bf16 v[52:55], v[176:179], v[196:199], v[52:55]
	v_mfma_f32_16x16x32_bf16 v[36:39], v[176:179], v[208:211], v[36:39]
	v_mfma_f32_16x16x32_bf16 v[36:39], v[172:175], v[200:203], v[36:39]
	v_mfma_f32_16x16x32_bf16 v[20:23], v[172:175], v[214:217], v[20:23]
	v_mfma_f32_16x16x32_bf16 v[20:23], v[176:179], v[230:233], v[20:23]
	v_mfma_f32_16x16x32_bf16 v[4:7], v[176:179], v[238:241], v[4:7]
	v_mfma_f32_16x16x32_bf16 v[4:7], v[172:175], v[234:237], v[4:7]
	v_mfma_f32_16x16x32_bf16 v[0:3], v[184:187], v[234:237], v[0:3]
	v_mfma_f32_16x16x32_bf16 v[0:3], v[188:191], v[238:241], v[0:3]
	v_mfma_f32_16x16x32_bf16 v[16:19], v[188:191], v[230:233], v[16:19]
	v_mfma_f32_16x16x32_bf16 v[16:19], v[184:187], v[214:217], v[16:19]
	v_mfma_f32_16x16x32_bf16 v[32:35], v[184:187], v[200:203], v[32:35]
	v_mfma_f32_16x16x32_bf16 v[32:35], v[188:191], v[208:211], v[32:35]
	v_mfma_f32_16x16x32_bf16 v[48:51], v[188:191], v[196:199], v[48:51]
	v_mfma_f32_16x16x32_bf16 v[48:51], v[184:187], v[192:195], v[48:51]
	s_setprio 0
	s_barrier
	s_add_i32 s29, 0, 0x18000
	s_add_i32 s36, 0, 0x1c000
	v_add_u32_e32 v168, s29, v180
	v_add_u32_e32 v183, s36, v180
	ds_read_b128 v[120:123], v168
	ds_read_b128 v[132:135], v168 offset:1024
	ds_read_b128 v[140:143], v168 offset:2048
	ds_read_b128 v[168:171], v168 offset:3072
	ds_read_b128 v[172:175], v183
	ds_read_b128 v[176:179], v183 offset:1024
	ds_read_b128 v[184:187], v183 offset:2048
	ds_read_b128 v[188:191], v183 offset:3072
	s_add_u32 s54, s74, 0x1000
	s_addc_u32 s55, s75, 0
	s_mov_b32 m0, s80
	v_lshl_add_u64 v[242:243], s[54:55], 0, v[144:145]
	ds_read_b128 v[192:195], v182 offset:32768
	ds_read_b128 v[196:199], v182 offset:33792
	ds_read_b128 v[200:203], v182 offset:34816
	ds_read_b128 v[208:211], v182 offset:35840
	ds_read_b128 v[214:217], v182 offset:36864
	ds_read_b128 v[230:233], v182 offset:37888
	ds_read_b128 v[234:237], v182 offset:38912
	ds_read_b128 v[238:241], v182 offset:39936
	global_load_lds_dwordx4 v[242:243], off
	v_lshl_add_u64 v[242:243], s[54:55], 0, v[148:149]
	s_mov_b32 m0, s81
	s_nop 0
	global_load_lds_dwordx4 v[242:243], off
	s_waitcnt vmcnt(8)
	s_waitcnt lgkmcnt(0)
	s_barrier
	s_setprio 1
	s_waitcnt lgkmcnt(0)
	v_mfma_f32_16x16x32_bf16 v[136:139], v[120:123], v[192:195], v[136:139]
	v_mfma_f32_16x16x32_bf16 v[136:139], v[132:135], v[196:199], v[136:139]
	v_mfma_f32_16x16x32_bf16 v[112:115], v[132:135], v[208:211], v[112:115]
	v_mfma_f32_16x16x32_bf16 v[112:115], v[120:123], v[200:203], v[112:115]
	v_mfma_f32_16x16x32_bf16 v[92:95], v[120:123], v[214:217], v[92:95]
	v_mfma_f32_16x16x32_bf16 v[92:95], v[132:135], v[230:233], v[92:95]
	v_mfma_f32_16x16x32_bf16 v[76:79], v[132:135], v[238:241], v[76:79]
	v_mfma_f32_16x16x32_bf16 v[76:79], v[120:123], v[234:237], v[76:79]
	v_mfma_f32_16x16x32_bf16 v[72:75], v[140:143], v[234:237], v[72:75]
	v_mfma_f32_16x16x32_bf16 v[72:75], v[168:171], v[238:241], v[72:75]
	v_mfma_f32_16x16x32_bf16 v[88:91], v[168:171], v[230:233], v[88:91]
	v_mfma_f32_16x16x32_bf16 v[88:91], v[140:143], v[214:217], v[88:91]
	v_mfma_f32_16x16x32_bf16 v[104:107], v[140:143], v[200:203], v[104:107]
	v_mfma_f32_16x16x32_bf16 v[104:107], v[168:171], v[208:211], v[104:107]
	v_mfma_f32_16x16x32_bf16 v[128:131], v[168:171], v[196:199], v[128:131]
	v_mfma_f32_16x16x32_bf16 v[128:131], v[140:143], v[192:195], v[128:131]
	s_setprio 0
	s_setprio 1
	v_mfma_f32_16x16x32_bf16 v[124:127], v[172:175], v[192:195], v[124:127]
	v_mfma_f32_16x16x32_bf16 v[124:127], v[176:179], v[196:199], v[124:127]
	v_mfma_f32_16x16x32_bf16 v[100:103], v[176:179], v[208:211], v[100:103]
	v_mfma_f32_16x16x32_bf16 v[100:103], v[172:175], v[200:203], v[100:103]
	v_mfma_f32_16x16x32_bf16 v[84:87], v[172:175], v[214:217], v[84:87]
	v_mfma_f32_16x16x32_bf16 v[84:87], v[176:179], v[230:233], v[84:87]
	v_mfma_f32_16x16x32_bf16 v[68:71], v[176:179], v[238:241], v[68:71]
	v_mfma_f32_16x16x32_bf16 v[68:71], v[172:175], v[234:237], v[68:71]
	v_mfma_f32_16x16x32_bf16 v[64:67], v[184:187], v[234:237], v[64:67]
	v_mfma_f32_16x16x32_bf16 v[64:67], v[188:191], v[238:241], v[64:67]
	v_mfma_f32_16x16x32_bf16 v[80:83], v[188:191], v[230:233], v[80:83]
	v_mfma_f32_16x16x32_bf16 v[80:83], v[184:187], v[214:217], v[80:83]
	v_mfma_f32_16x16x32_bf16 v[96:99], v[184:187], v[200:203], v[96:99]
	v_mfma_f32_16x16x32_bf16 v[96:99], v[188:191], v[208:211], v[96:99]
	v_mfma_f32_16x16x32_bf16 v[116:119], v[188:191], v[196:199], v[116:119]
	v_mfma_f32_16x16x32_bf16 v[116:119], v[184:187], v[192:195], v[116:119]
	s_setprio 0
	s_barrier
; #define PG8_STAGE(bufoff, gbase, voff) do { _Pragma("unroll") for (int _i = 0; _i < 2; ++_i) \
;         __builtin_amdgcn_global_load_lds((const unsigned*)((const char*)(gbase) + (voff)[_i]), (LAS unsigned*)(lds + (bufoff) + ldsw + _i * 8192), 16, 0, 0); } while (0)
; #define PG8_LDA(dst, b, h) do { _Pragma("unroll") for (int m = 0; m < 4; ++m) _Pragma("unroll") for (int k = 0; k < 2; ++k) dst[m][k] = *(const LAS bf16x8*)(lds + PG8_SA(b, h) + aoff + m * 2048 + k * 1024); } while (0)
; #define PG8_MMA(ai, bj, At, Bt) do { __builtin_amdgcn_s_setprio(1); _Pragma("unroll") for (int m = 0; m < 4; ++m) _Pragma("unroll") for (int n = 0; n < 2; ++n) _Pragma("unroll") for (int k = 0; k < 2; ++k) \
;         acc[ai][bj][m][n] = __builtin_amdgcn_mfma_f32_16x16x32_bf16(Bt[n][k], At[m][k], acc[ai][bj][m][n], 0, 0, 0); __builtin_amdgcn_s_setprio(0); } while (0)
; #define PG8_WAIT_V(n) asm volatile("s_waitcnt vmcnt(" #n ")" ::: "memory")
; #define PG8_WAIT_L(n) asm volatile("s_waitcnt lgkmcnt(" #n ")" ::: "memory")
; #define PG8_BAR __builtin_amdgcn_s_barrier()
; #define PG8_SCHED __builtin_amdgcn_sched_barrier(0)
;     ...
;         for (int t = 0; t < nt; t += 2) {
;             const bool last = (t == nt - 2);
;     ...
;             PG8_LDA(At, 1, 1); PG8_STAGE(PG8_SB(1, 0), b3, voffB); PG8_STAGE(PG8_SB(1, 1), b3 + hB, voffB); PG8_STAGE(PG8_SA(1, 0), a3, voffA);
;             PG8_WAIT_V(8); PG8_WAIT_L(0); PG8_BAR; PG8_MMA(1, 0, At, B0); PG8_MMA(1, 1, At, B1); PG8_BAR; PG8_SCHED;
	s_add_i32 s29, s29, s77
	v_lshl_add_u64 v[204:205], v[204:205], 0, s[38:39]
	s_mov_b32 m0, s29
	ds_read_b128 v[192:195], v182 offset:49152
	ds_read_b128 v[196:199], v182 offset:50176
	ds_read_b128 v[200:203], v182 offset:51200
	ds_read_b128 v[208:211], v182 offset:52224
	ds_read_b128 v[214:217], v182 offset:53248
	ds_read_b128 v[230:233], v182 offset:54272
	ds_read_b128 v[234:237], v182 offset:55296
	ds_read_b128 v[238:241], v182 offset:56320
	global_load_lds_dwordx4 v[204:205], off
	s_add_i32 m0, s29, 0x2000
	s_add_u32 s54, s72, 0x40080
	v_lshl_add_u64 v[204:205], v[206:207], 0, s[38:39]
	s_addc_u32 s55, s73, 0
	s_add_i32 s29, s36, s77
	global_load_lds_dwordx4 v[204:205], off
	v_lshl_add_u64 v[204:205], s[54:55], 0, v[146:147]
	s_mov_b32 m0, s29
	s_nop 0
	global_load_lds_dwordx4 v[204:205], off
	v_lshl_add_u64 v[204:205], s[54:55], 0, v[150:151]
	s_add_i32 m0, s29, 0x2000
	s_nop 0
	global_load_lds_dwordx4 v[204:205], off
	v_lshl_add_u64 v[204:205], s[52:53], 0, v[144:145]
	s_mov_b32 m0, s89
	s_nop 0
	global_load_lds_dwordx4 v[204:205], off
	v_lshl_add_u64 v[204:205], s[52:53], 0, v[148:149]
	s_mov_b32 m0, s90
	s_nop 0
	global_load_lds_dwordx4 v[204:205], off
	s_waitcnt vmcnt(8)
	s_waitcnt lgkmcnt(0)
	s_barrier
	s_setprio 1
	s_waitcnt lgkmcnt(0)
	v_mfma_f32_16x16x32_bf16 v[60:63], v[120:123], v[192:195], v[60:63]
	v_mfma_f32_16x16x32_bf16 v[60:63], v[132:135], v[196:199], v[60:63]
	v_mfma_f32_16x16x32_bf16 v[44:47], v[132:135], v[208:211], v[44:47]
	v_mfma_f32_16x16x32_bf16 v[44:47], v[120:123], v[200:203], v[44:47]
	v_mfma_f32_16x16x32_bf16 v[28:31], v[120:123], v[214:217], v[28:31]
	v_mfma_f32_16x16x32_bf16 v[28:31], v[132:135], v[230:233], v[28:31]
	v_mfma_f32_16x16x32_bf16 v[12:15], v[132:135], v[238:241], v[12:15]
	v_mfma_f32_16x16x32_bf16 v[12:15], v[120:123], v[234:237], v[12:15]
	v_mfma_f32_16x16x32_bf16 v[8:11], v[140:143], v[234:237], v[8:11]
	v_mfma_f32_16x16x32_bf16 v[8:11], v[168:171], v[238:241], v[8:11]
	v_mfma_f32_16x16x32_bf16 v[24:27], v[168:171], v[230:233], v[24:27]
	v_mfma_f32_16x16x32_bf16 v[24:27], v[140:143], v[214:217], v[24:27]
	v_mfma_f32_16x16x32_bf16 v[40:43], v[140:143], v[200:203], v[40:43]
	v_mfma_f32_16x16x32_bf16 v[40:43], v[168:171], v[208:211], v[40:43]
	v_mfma_f32_16x16x32_bf16 v[56:59], v[168:171], v[196:199], v[56:59]
	v_mfma_f32_16x16x32_bf16 v[56:59], v[140:143], v[192:195], v[56:59]
	s_setprio 0
	s_setprio 1
	v_mfma_f32_16x16x32_bf16 v[52:55], v[172:175], v[192:195], v[52:55]
	v_mfma_f32_16x16x32_bf16 v[52:55], v[176:179], v[196:199], v[52:55]
	v_mfma_f32_16x16x32_bf16 v[36:39], v[176:179], v[208:211], v[36:39]
	v_mfma_f32_16x16x32_bf16 v[36:39], v[172:175], v[200:203], v[36:39]
	v_mfma_f32_16x16x32_bf16 v[20:23], v[172:175], v[214:217], v[20:23]
	v_mfma_f32_16x16x32_bf16 v[20:23], v[176:179], v[230:233], v[20:23]
	v_mfma_f32_16x16x32_bf16 v[4:7], v[176:179], v[238:241], v[4:7]
	v_mfma_f32_16x16x32_bf16 v[4:7], v[172:175], v[234:237], v[4:7]
	v_mfma_f32_16x16x32_bf16 v[0:3], v[184:187], v[234:237], v[0:3]
	v_mfma_f32_16x16x32_bf16 v[0:3], v[188:191], v[238:241], v[0:3]
	v_mfma_f32_16x16x32_bf16 v[16:19], v[188:191], v[230:233], v[16:19]
	v_mfma_f32_16x16x32_bf16 v[16:19], v[184:187], v[214:217], v[16:19]
	v_mfma_f32_16x16x32_bf16 v[32:35], v[184:187], v[200:203], v[32:35]
	v_mfma_f32_16x16x32_bf16 v[32:35], v[188:191], v[208:211], v[32:35]
	v_mfma_f32_16x16x32_bf16 v[48:51], v[188:191], v[196:199], v[48:51]
	v_mfma_f32_16x16x32_bf16 v[48:51], v[184:187], v[192:195], v[48:51]
	s_setprio 0
	s_barrier
	s_add_i32 s27, s27, 2
	s_add_u32 s9, s9, 0x100
	s_addc_u32 s17, s17, 0
	s_add_u32 s44, s44, 0x800000
	s_addc_u32 s45, s45, 0
	s_cmp_gt_u32 s27, 13
	s_cbranch_scc0 .LBB0_155
	s_and_b64 vcc, exec, s[14:15]
	s_cbranch_vccz .LBB0_158
	s_barrier

; #define PG8_STAGE(bufoff, gbase, voff) do { _Pragma("unroll") for (int _i = 0; _i < 2; ++_i) \
;         __builtin_amdgcn_global_load_lds((const unsigned*)((const char*)(gbase) + (voff)[_i]), (LAS unsigned*)(lds + (bufoff) + ldsw + _i * 8192), 16, 0, 0); } while (0)
; #define PG8_LDA(dst, b, h) do { _Pragma("unroll") for (int m = 0; m < 4; ++m) _Pragma("unroll") for (int k = 0; k < 2; ++k) dst[m][k] = *(const LAS bf16x8*)(lds + PG8_SA(b, h) + aoff + m * 2048 + k * 1024); } while (0)
; #define PG8_LDB(dst, b, h) do { _Pragma("unroll") for (int n = 0; n < 2; ++n) _Pragma("unroll") for (int k = 0; k < 2; ++k) dst[n][k] = *(const LAS bf16x8*)(lds + PG8_SB(b, h) + boff + n * 2048 + k * 1024); } while (0)
; #define PG8_MMA(ai, bj, At, Bt) do { __builtin_amdgcn_s_setprio(1); _Pragma("unroll") for (int m = 0; m < 4; ++m) _Pragma("unroll") for (int n = 0; n < 2; ++n) _Pragma("unroll") for (int k = 0; k < 2; ++k) \
;         acc[ai][bj][m][n] = __builtin_amdgcn_mfma_f32_16x16x32_bf16(Bt[n][k], At[m][k], acc[ai][bj][m][n], 0, 0, 0); __builtin_amdgcn_s_setprio(0); } while (0)
; #define PG8_WAIT_V(n) asm volatile("s_waitcnt vmcnt(" #n ")" ::: "memory")
; #define PG8_WAIT_L(n) asm volatile("s_waitcnt lgkmcnt(" #n ")" ::: "memory")
; #define PG8_BAR __builtin_amdgcn_s_barrier()
;     ...
;         const bool has_next = S.next(ui + 1, nxt);
;         const char* nA = has_next ? oa.base + (size_t)nxt.pm * oa.tstep : cA; const char* nA2 = has_next ? oa.base2 + (size_t)nxt.pm * oa.tstep : cA2; const char* nB = has_next ? ob.base + (size_t)nxt.pn * ob.tstep : cB;
; #pragma nounroll
;         for (int t = 0; t < nt; t += 2) {
;             const bool last = (t == nt - 2);
;             const char* a1 = PG8_ATILE(cA, cA2, t + 1);
;             const char* a2 = last ? nA : PG8_ATILE(cA, cA2, t + 2); const char* b2 = last ? nB : cB + (size_t)(t + 2) * 128;
;             const char* a3 = last ? nA + kA1 : PG8_ATILE(cA, cA2, t + 3); const char* b3 = b2 + kB1;
;             if constexpr (SP2) {
;             PG8_LDB(B0, 0, 0); PG8_LDB(B1, 0, 1); PG8_SCHED; PG8_LDA(At, 0, 0); PG8_STAGE(PG8_SA(1, 1), a1 + hA, voffA);
;             PG8_WAIT_V(8); PG8_WAIT_L(0); PG8_BAR; PG8_MMA(0, 0, At, B0); PG8_MMA(0, 1, At, B1); PG8_BAR; PG8_SCHED;
;             PG8_LDA(At, 0, 1); PG8_STAGE(PG8_SB(0, 0), b2, voffB); PG8_STAGE(PG8_SB(0, 1), b2 + hB, voffB); PG8_STAGE(PG8_SA(0, 0), a2, voffA);
.LBB0_191:
	s_add_u32 s72, s44, s52
	s_addc_u32 s73, s45, s53
	s_add_u32 s76, s72, 0x100
	s_addc_u32 s77, s73, 0
	s_add_u32 s74, s80, s52
	s_addc_u32 s75, s81, s53
	s_add_u32 s72, s72, 0x180
	s_addc_u32 s73, s73, 0
	s_add_i32 s83, 0, 0x10000
	s_add_i32 s89, 0, 0x14000
	v_add_u32_e32 v146, s83, v150
	ds_read_b128 v[100:103], v146
	ds_read_b128 v[168:171], v146 offset:1024
	ds_read_b128 v[172:175], v146 offset:2048
	ds_read_b128 v[176:179], v146 offset:3072
	v_add_u32_e32 v146, s89, v150
	ds_read_b128 v[180:183], v146
	ds_read_b128 v[184:187], v146 offset:1024
	ds_read_b128 v[188:191], v146 offset:2048
	ds_read_b128 v[192:195], v146 offset:3072
	s_cmpk_eq_i32 s52, 0x700
	s_cselect_b32 s73, s79, s73
	s_cselect_b32 s72, s78, s72
	s_cselect_b32 s75, s17, s75
	s_cselect_b32 s74, s55, s74
	s_cselect_b32 s77, s27, s77
	s_cselect_b32 s76, s54, s76
	v_lshl_add_u64 v[146:147], v[96:97], 0, s[52:53]
	s_add_i32 m0, s6, 0xc000
	ds_read_b128 v[196:199], v154
	ds_read_b128 v[200:203], v154 offset:1024
	ds_read_b128 v[208:211], v154 offset:2048
	ds_read_b128 v[214:217], v154 offset:3072
	ds_read_b128 v[230:233], v154 offset:4096
	ds_read_b128 v[234:237], v154 offset:5120
	ds_read_b128 v[238:241], v154 offset:6144
	ds_read_b128 v[242:245], v154 offset:7168
	global_load_lds_dwordx4 v[146:147], off
	v_lshl_add_u64 v[146:147], v[98:99], 0, s[52:53]
	s_add_i32 m0, s6, 0xe000
	s_nop 0
	global_load_lds_dwordx4 v[146:147], off
	s_waitcnt vmcnt(8)
	s_waitcnt lgkmcnt(0)
	s_barrier
	s_setprio 1
	s_waitcnt lgkmcnt(0)
	v_mfma_f32_16x16x32_bf16 v[132:135], v[100:103], v[196:199], v[132:135]
	v_mfma_f32_16x16x32_bf16 v[132:135], v[168:171], v[200:203], v[132:135]
	v_mfma_f32_16x16x32_bf16 v[124:127], v[168:171], v[214:217], v[124:127]
	v_mfma_f32_16x16x32_bf16 v[124:127], v[100:103], v[208:211], v[124:127]
	v_mfma_f32_16x16x32_bf16 v[116:119], v[100:103], v[230:233], v[116:119]
	v_mfma_f32_16x16x32_bf16 v[116:119], v[168:171], v[234:237], v[116:119]
	v_mfma_f32_16x16x32_bf16 v[108:111], v[168:171], v[242:245], v[108:111]
	v_mfma_f32_16x16x32_bf16 v[108:111], v[100:103], v[238:241], v[108:111]
	v_mfma_f32_16x16x32_bf16 v[104:107], v[172:175], v[238:241], v[104:107]
	v_mfma_f32_16x16x32_bf16 v[104:107], v[176:179], v[242:245], v[104:107]
	v_mfma_f32_16x16x32_bf16 v[112:115], v[176:179], v[234:237], v[112:115]
	v_mfma_f32_16x16x32_bf16 v[112:115], v[172:175], v[230:233], v[112:115]
	v_mfma_f32_16x16x32_bf16 v[120:123], v[172:175], v[208:211], v[120:123]
	v_mfma_f32_16x16x32_bf16 v[120:123], v[176:179], v[214:217], v[120:123]
	v_mfma_f32_16x16x32_bf16 v[128:131], v[176:179], v[200:203], v[128:131]
	v_mfma_f32_16x16x32_bf16 v[128:131], v[172:175], v[196:199], v[128:131]
	s_setprio 0
	s_setprio 1
	v_mfma_f32_16x16x32_bf16 v[68:71], v[180:183], v[196:199], v[68:71]
	v_mfma_f32_16x16x32_bf16 v[68:71], v[184:187], v[200:203], v[68:71]
	v_mfma_f32_16x16x32_bf16 v[52:55], v[184:187], v[214:217], v[52:55]
	v_mfma_f32_16x16x32_bf16 v[52:55], v[180:183], v[208:211], v[52:55]
	v_mfma_f32_16x16x32_bf16 v[44:47], v[180:183], v[230:233], v[44:47]
	v_mfma_f32_16x16x32_bf16 v[44:47], v[184:187], v[234:237], v[44:47]
	v_mfma_f32_16x16x32_bf16 v[36:39], v[184:187], v[242:245], v[36:39]
	v_mfma_f32_16x16x32_bf16 v[36:39], v[180:183], v[238:241], v[36:39]
	v_mfma_f32_16x16x32_bf16 v[32:35], v[188:191], v[238:241], v[32:35]
	v_mfma_f32_16x16x32_bf16 v[32:35], v[192:195], v[242:245], v[32:35]
	v_mfma_f32_16x16x32_bf16 v[40:43], v[192:195], v[234:237], v[40:43]
	v_mfma_f32_16x16x32_bf16 v[40:43], v[188:191], v[230:233], v[40:43]
	v_mfma_f32_16x16x32_bf16 v[48:51], v[188:191], v[208:211], v[48:51]
	v_mfma_f32_16x16x32_bf16 v[48:51], v[192:195], v[214:217], v[48:51]
	v_mfma_f32_16x16x32_bf16 v[56:59], v[192:195], v[200:203], v[56:59]
	v_mfma_f32_16x16x32_bf16 v[56:59], v[188:191], v[196:199], v[56:59]
	s_setprio 0
	s_barrier
	s_add_i32 s83, s83, s5
	v_lshl_add_u64 v[146:147], s[74:75], 0, v[156:157]
	s_mov_b32 m0, s83
	ds_read_b128 v[196:199], v154 offset:16384
	ds_read_b128 v[200:203], v154 offset:17408
	ds_read_b128 v[208:211], v154 offset:18432
	ds_read_b128 v[214:217], v154 offset:19456
	ds_read_b128 v[230:233], v154 offset:20480
	ds_read_b128 v[234:237], v154 offset:21504
	ds_read_b128 v[238:241], v154 offset:22528
	ds_read_b128 v[242:245], v154 offset:23552
	global_load_lds_dwordx4 v[146:147], off
	s_add_i32 m0, s83, 0x2000
	s_add_u32 s90, s74, 0x40000
	v_lshl_add_u64 v[204:205], s[74:75], 0, v[140:141]
	s_addc_u32 s91, s75, 0
	s_add_i32 s83, s89, s5
	global_load_lds_dwordx4 v[204:205], off
	v_lshl_add_u64 v[206:207], s[90:91], 0, v[156:157]
	s_mov_b32 m0, s83
	s_nop 0
	global_load_lds_dwordx4 v[206:207], off
	v_lshl_add_u64 v[206:207], s[90:91], 0, v[140:141]
	s_add_i32 m0, s83, 0x2000
	s_nop 0
	global_load_lds_dwordx4 v[206:207], off
	v_lshl_add_u64 v[206:207], s[76:77], 0, v[136:137]
	s_mov_b32 m0, s6
	s_nop 0
	global_load_lds_dwordx4 v[206:207], off
	v_lshl_add_u64 v[206:207], s[76:77], 0, v[138:139]
	s_mov_b32 m0, s7
	s_nop 0
	global_load_lds_dwordx4 v[206:207], off
	s_waitcnt vmcnt(8)
	s_waitcnt lgkmcnt(0)
	s_barrier
; #define PG8_STAGE(bufoff, gbase, voff) do { _Pragma("unroll") for (int _i = 0; _i < 2; ++_i) \
;         __builtin_amdgcn_global_load_lds((const unsigned*)((const char*)(gbase) + (voff)[_i]), (LAS unsigned*)(lds + (bufoff) + ldsw + _i * 8192), 16, 0, 0); } while (0)
; #define PG8_LDA(dst, b, h) do { _Pragma("unroll") for (int m = 0; m < 4; ++m) _Pragma("unroll") for (int k = 0; k < 2; ++k) dst[m][k] = *(const LAS bf16x8*)(lds + PG8_SA(b, h) + aoff + m * 2048 + k * 1024); } while (0)
; #define PG8_LDB(dst, b, h) do { _Pragma("unroll") for (int n = 0; n < 2; ++n) _Pragma("unroll") for (int k = 0; k < 2; ++k) dst[n][k] = *(const LAS bf16x8*)(lds + PG8_SB(b, h) + boff + n * 2048 + k * 1024); } while (0)
; #define PG8_MMA(ai, bj, At, Bt) do { __builtin_amdgcn_s_setprio(1); _Pragma("unroll") for (int m = 0; m < 4; ++m) _Pragma("unroll") for (int n = 0; n < 2; ++n) _Pragma("unroll") for (int k = 0; k < 2; ++k) \
;         acc[ai][bj][m][n] = __builtin_amdgcn_mfma_f32_16x16x32_bf16(Bt[n][k], At[m][k], acc[ai][bj][m][n], 0, 0, 0); __builtin_amdgcn_s_setprio(0); } while (0)
; #define PG8_WAIT_V(n) asm volatile("s_waitcnt vmcnt(" #n ")" ::: "memory")
; #define PG8_WAIT_L(n) asm volatile("s_waitcnt lgkmcnt(" #n ")" ::: "memory")
; #define PG8_BAR __builtin_amdgcn_s_barrier()
; #define PG8_SCHED __builtin_amdgcn_sched_barrier(0)
;     ...
;             PG8_WAIT_V(8); PG8_WAIT_L(0); PG8_BAR; PG8_MMA(1, 0, At, B0); PG8_MMA(1, 1, At, B1); PG8_BAR; PG8_SCHED;
;             PG8_LDB(B0, 1, 0); PG8_LDB(B1, 1, 1); PG8_SCHED; PG8_LDA(At, 1, 0); PG8_STAGE(PG8_SA(0, 1), a2 + hA, voffA);
;             PG8_WAIT_V(8); PG8_WAIT_L(0); PG8_BAR; PG8_MMA(0, 0, At, B0); PG8_MMA(0, 1, At, B1); PG8_BAR; PG8_SCHED;
	s_setprio 1
	s_waitcnt lgkmcnt(0)
	v_mfma_f32_16x16x32_bf16 v[92:95], v[100:103], v[196:199], v[92:95]
	v_mfma_f32_16x16x32_bf16 v[92:95], v[168:171], v[200:203], v[92:95]
	v_mfma_f32_16x16x32_bf16 v[84:87], v[168:171], v[214:217], v[84:87]
	v_mfma_f32_16x16x32_bf16 v[84:87], v[100:103], v[208:211], v[84:87]
	v_mfma_f32_16x16x32_bf16 v[76:79], v[100:103], v[230:233], v[76:79]
	v_mfma_f32_16x16x32_bf16 v[76:79], v[168:171], v[234:237], v[76:79]
	v_mfma_f32_16x16x32_bf16 v[64:67], v[168:171], v[242:245], v[64:67]
	v_mfma_f32_16x16x32_bf16 v[64:67], v[100:103], v[238:241], v[64:67]
	v_mfma_f32_16x16x32_bf16 v[60:63], v[172:175], v[238:241], v[60:63]
	v_mfma_f32_16x16x32_bf16 v[60:63], v[176:179], v[242:245], v[60:63]
	v_mfma_f32_16x16x32_bf16 v[72:75], v[176:179], v[234:237], v[72:75]
	v_mfma_f32_16x16x32_bf16 v[72:75], v[172:175], v[230:233], v[72:75]
	v_mfma_f32_16x16x32_bf16 v[80:83], v[172:175], v[208:211], v[80:83]
	v_mfma_f32_16x16x32_bf16 v[80:83], v[176:179], v[214:217], v[80:83]
	v_mfma_f32_16x16x32_bf16 v[88:91], v[176:179], v[200:203], v[88:91]
	v_mfma_f32_16x16x32_bf16 v[88:91], v[172:175], v[196:199], v[88:91]
	s_setprio 0
	s_setprio 1
	v_mfma_f32_16x16x32_bf16 v[28:31], v[180:183], v[196:199], v[28:31]
	v_mfma_f32_16x16x32_bf16 v[28:31], v[184:187], v[200:203], v[28:31]
	v_mfma_f32_16x16x32_bf16 v[20:23], v[184:187], v[214:217], v[20:23]
	v_mfma_f32_16x16x32_bf16 v[20:23], v[180:183], v[208:211], v[20:23]
	v_mfma_f32_16x16x32_bf16 v[12:15], v[180:183], v[230:233], v[12:15]
	v_mfma_f32_16x16x32_bf16 v[12:15], v[184:187], v[234:237], v[12:15]
	v_mfma_f32_16x16x32_bf16 v[4:7], v[184:187], v[242:245], v[4:7]
	v_mfma_f32_16x16x32_bf16 v[4:7], v[180:183], v[238:241], v[4:7]
	v_mfma_f32_16x16x32_bf16 v[0:3], v[188:191], v[238:241], v[0:3]
	v_mfma_f32_16x16x32_bf16 v[0:3], v[192:195], v[242:245], v[0:3]
	v_mfma_f32_16x16x32_bf16 v[8:11], v[192:195], v[234:237], v[8:11]
	v_mfma_f32_16x16x32_bf16 v[8:11], v[188:191], v[230:233], v[8:11]
	v_mfma_f32_16x16x32_bf16 v[16:19], v[188:191], v[208:211], v[16:19]
	v_mfma_f32_16x16x32_bf16 v[16:19], v[192:195], v[214:217], v[16:19]
	v_mfma_f32_16x16x32_bf16 v[24:27], v[192:195], v[200:203], v[24:27]
	v_mfma_f32_16x16x32_bf16 v[24:27], v[188:191], v[196:199], v[24:27]
	s_setprio 0
	s_barrier
	s_add_i32 s83, 0, 0x18000
	v_add_u32_e32 v155, s83, v150
	s_add_i32 s89, 0, 0x1c000
	ds_read_b128 v[100:103], v155
	ds_read_b128 v[168:171], v155 offset:1024
	ds_read_b128 v[172:175], v155 offset:2048
	ds_read_b128 v[176:179], v155 offset:3072
	v_add_u32_e32 v155, s89, v150
	ds_read_b128 v[180:183], v155
	ds_read_b128 v[184:187], v155 offset:1024
	ds_read_b128 v[188:191], v155 offset:2048
	ds_read_b128 v[192:195], v155 offset:3072
	s_add_u32 s76, s76, 0x40000
	s_addc_u32 s77, s77, 0
	s_mov_b32 m0, s8
	v_lshl_add_u64 v[206:207], s[76:77], 0, v[136:137]
	ds_read_b128 v[196:199], v154 offset:32768
	ds_read_b128 v[200:203], v154 offset:33792
	ds_read_b128 v[208:211], v154 offset:34816
	ds_read_b128 v[214:217], v154 offset:35840
	ds_read_b128 v[230:233], v154 offset:36864
	ds_read_b128 v[234:237], v154 offset:37888
	ds_read_b128 v[238:241], v154 offset:38912
	ds_read_b128 v[242:245], v154 offset:39936
	global_load_lds_dwordx4 v[206:207], off
	v_lshl_add_u64 v[206:207], s[76:77], 0, v[138:139]
	s_mov_b32 m0, s9
	s_nop 0
	global_load_lds_dwordx4 v[206:207], off
	s_waitcnt vmcnt(8)
	s_waitcnt lgkmcnt(0)
	s_barrier
	s_setprio 1
	s_waitcnt lgkmcnt(0)
	v_mfma_f32_16x16x32_bf16 v[132:135], v[100:103], v[196:199], v[132:135]
	v_mfma_f32_16x16x32_bf16 v[132:135], v[168:171], v[200:203], v[132:135]
	v_mfma_f32_16x16x32_bf16 v[124:127], v[168:171], v[214:217], v[124:127]
	v_mfma_f32_16x16x32_bf16 v[124:127], v[100:103], v[208:211], v[124:127]
	v_mfma_f32_16x16x32_bf16 v[116:119], v[100:103], v[230:233], v[116:119]
	v_mfma_f32_16x16x32_bf16 v[116:119], v[168:171], v[234:237], v[116:119]
	v_mfma_f32_16x16x32_bf16 v[108:111], v[168:171], v[242:245], v[108:111]
	v_mfma_f32_16x16x32_bf16 v[108:111], v[100:103], v[238:241], v[108:111]
	v_mfma_f32_16x16x32_bf16 v[104:107], v[172:175], v[238:241], v[104:107]
	v_mfma_f32_16x16x32_bf16 v[104:107], v[176:179], v[242:245], v[104:107]
	v_mfma_f32_16x16x32_bf16 v[112:115], v[176:179], v[234:237], v[112:115]
	v_mfma_f32_16x16x32_bf16 v[112:115], v[172:175], v[230:233], v[112:115]
	v_mfma_f32_16x16x32_bf16 v[120:123], v[172:175], v[208:211], v[120:123]
	v_mfma_f32_16x16x32_bf16 v[120:123], v[176:179], v[214:217], v[120:123]
	v_mfma_f32_16x16x32_bf16 v[128:131], v[176:179], v[200:203], v[128:131]
	v_mfma_f32_16x16x32_bf16 v[128:131], v[172:175], v[196:199], v[128:131]
	s_setprio 0
	s_setprio 1
	v_mfma_f32_16x16x32_bf16 v[68:71], v[180:183], v[196:199], v[68:71]
	v_mfma_f32_16x16x32_bf16 v[68:71], v[184:187], v[200:203], v[68:71]
	v_mfma_f32_16x16x32_bf16 v[52:55], v[184:187], v[214:217], v[52:55]
	v_mfma_f32_16x16x32_bf16 v[52:55], v[180:183], v[208:211], v[52:55]
	v_mfma_f32_16x16x32_bf16 v[44:47], v[180:183], v[230:233], v[44:47]
	v_mfma_f32_16x16x32_bf16 v[44:47], v[184:187], v[234:237], v[44:47]
	v_mfma_f32_16x16x32_bf16 v[36:39], v[184:187], v[242:245], v[36:39]
	v_mfma_f32_16x16x32_bf16 v[36:39], v[180:183], v[238:241], v[36:39]
	v_mfma_f32_16x16x32_bf16 v[32:35], v[188:191], v[238:241], v[32:35]
	v_mfma_f32_16x16x32_bf16 v[32:35], v[192:195], v[242:245], v[32:35]
	v_mfma_f32_16x16x32_bf16 v[40:43], v[192:195], v[234:237], v[40:43]
	v_mfma_f32_16x16x32_bf16 v[40:43], v[188:191], v[230:233], v[40:43]
	v_mfma_f32_16x16x32_bf16 v[48:51], v[188:191], v[208:211], v[48:51]
	v_mfma_f32_16x16x32_bf16 v[48:51], v[192:195], v[214:217], v[48:51]
	v_mfma_f32_16x16x32_bf16 v[56:59], v[192:195], v[200:203], v[56:59]
	v_mfma_f32_16x16x32_bf16 v[56:59], v[188:191], v[196:199], v[56:59]
	s_setprio 0
	s_barrier
; #define PG8_STAGE(bufoff, gbase, voff) do { _Pragma("unroll") for (int _i = 0; _i < 2; ++_i) \
;         __builtin_amdgcn_global_load_lds((const unsigned*)((const char*)(gbase) + (voff)[_i]), (LAS unsigned*)(lds + (bufoff) + ldsw + _i * 8192), 16, 0, 0); } while (0)
; #define PG8_LDA(dst, b, h) do { _Pragma("unroll") for (int m = 0; m < 4; ++m) _Pragma("unroll") for (int k = 0; k < 2; ++k) dst[m][k] = *(const LAS bf16x8*)(lds + PG8_SA(b, h) + aoff + m * 2048 + k * 1024); } while (0)
; #define PG8_MMA(ai, bj, At, Bt) do { __builtin_amdgcn_s_setprio(1); _Pragma("unroll") for (int m = 0; m < 4; ++m) _Pragma("unroll") for (int n = 0; n < 2; ++n) _Pragma("unroll") for (int k = 0; k < 2; ++k) \
;         acc[ai][bj][m][n] = __builtin_amdgcn_mfma_f32_16x16x32_bf16(Bt[n][k], At[m][k], acc[ai][bj][m][n], 0, 0, 0); __builtin_amdgcn_s_setprio(0); } while (0)
; #define PG8_WAIT_V(n) asm volatile("s_waitcnt vmcnt(" #n ")" ::: "memory")
; #define PG8_WAIT_L(n) asm volatile("s_waitcnt lgkmcnt(" #n ")" ::: "memory")
; #define PG8_BAR __builtin_amdgcn_s_barrier()
; #define PG8_SCHED __builtin_amdgcn_sched_barrier(0)
;     ...
;             PG8_LDA(At, 1, 1); PG8_STAGE(PG8_SB(1, 0), b3, voffB); PG8_STAGE(PG8_SB(1, 1), b3 + hB, voffB); PG8_STAGE(PG8_SA(1, 0), a3, voffA);
;             PG8_WAIT_V(8); PG8_WAIT_L(0); PG8_BAR; PG8_MMA(1, 0, At, B0); PG8_MMA(1, 1, At, B1); PG8_BAR; PG8_SCHED;
;     ...
;         if constexpr (ALIGN_EPI) { if (wr == 0) PG8_BAR; }
	s_add_i32 s76, s83, s5
	v_lshl_add_u64 v[146:147], v[146:147], 0, s[38:39]
	s_mov_b32 m0, s76
	ds_read_b128 v[196:199], v154 offset:49152
	ds_read_b128 v[200:203], v154 offset:50176
	ds_read_b128 v[208:211], v154 offset:51200
	ds_read_b128 v[214:217], v154 offset:52224
	ds_read_b128 v[230:233], v154 offset:53248
	ds_read_b128 v[234:237], v154 offset:54272
	ds_read_b128 v[238:241], v154 offset:55296
	ds_read_b128 v[242:245], v154 offset:56320
	global_load_lds_dwordx4 v[146:147], off
	s_add_i32 m0, s76, 0x2000
	s_add_u32 s74, s74, 0x40080
	v_lshl_add_u64 v[146:147], v[204:205], 0, s[38:39]
	s_addc_u32 s75, s75, 0
	s_add_i32 s76, s89, s5
	global_load_lds_dwordx4 v[146:147], off
	v_lshl_add_u64 v[146:147], s[74:75], 0, v[156:157]
	s_mov_b32 m0, s76
	s_nop 0
	global_load_lds_dwordx4 v[146:147], off
	v_lshl_add_u64 v[146:147], s[74:75], 0, v[140:141]
	s_add_i32 m0, s76, 0x2000
	s_nop 0
	global_load_lds_dwordx4 v[146:147], off
	v_lshl_add_u64 v[146:147], s[72:73], 0, v[136:137]
	s_mov_b32 m0, s42
	s_nop 0
	global_load_lds_dwordx4 v[146:147], off
	v_lshl_add_u64 v[146:147], s[72:73], 0, v[138:139]
	s_mov_b32 m0, s43
	s_nop 0
	global_load_lds_dwordx4 v[146:147], off
	s_waitcnt vmcnt(8)
	s_waitcnt lgkmcnt(0)
	s_barrier
	s_setprio 1
	s_waitcnt lgkmcnt(0)
	v_mfma_f32_16x16x32_bf16 v[92:95], v[100:103], v[196:199], v[92:95]
	v_mfma_f32_16x16x32_bf16 v[92:95], v[168:171], v[200:203], v[92:95]
	v_mfma_f32_16x16x32_bf16 v[84:87], v[168:171], v[214:217], v[84:87]
	v_mfma_f32_16x16x32_bf16 v[84:87], v[100:103], v[208:211], v[84:87]
	v_mfma_f32_16x16x32_bf16 v[76:79], v[100:103], v[230:233], v[76:79]
	v_mfma_f32_16x16x32_bf16 v[76:79], v[168:171], v[234:237], v[76:79]
	v_mfma_f32_16x16x32_bf16 v[64:67], v[168:171], v[242:245], v[64:67]
	v_mfma_f32_16x16x32_bf16 v[64:67], v[100:103], v[238:241], v[64:67]
	v_mfma_f32_16x16x32_bf16 v[60:63], v[172:175], v[238:241], v[60:63]
	v_mfma_f32_16x16x32_bf16 v[60:63], v[176:179], v[242:245], v[60:63]
	v_mfma_f32_16x16x32_bf16 v[72:75], v[176:179], v[234:237], v[72:75]
	v_mfma_f32_16x16x32_bf16 v[72:75], v[172:175], v[230:233], v[72:75]
	v_mfma_f32_16x16x32_bf16 v[80:83], v[172:175], v[208:211], v[80:83]
	v_mfma_f32_16x16x32_bf16 v[80:83], v[176:179], v[214:217], v[80:83]
	v_mfma_f32_16x16x32_bf16 v[88:91], v[176:179], v[200:203], v[88:91]
	v_mfma_f32_16x16x32_bf16 v[88:91], v[172:175], v[196:199], v[88:91]
	s_setprio 0
	s_setprio 1
	v_mfma_f32_16x16x32_bf16 v[28:31], v[180:183], v[196:199], v[28:31]
	v_mfma_f32_16x16x32_bf16 v[28:31], v[184:187], v[200:203], v[28:31]
	v_mfma_f32_16x16x32_bf16 v[20:23], v[184:187], v[214:217], v[20:23]
	v_mfma_f32_16x16x32_bf16 v[20:23], v[180:183], v[208:211], v[20:23]
	v_mfma_f32_16x16x32_bf16 v[12:15], v[180:183], v[230:233], v[12:15]
	v_mfma_f32_16x16x32_bf16 v[12:15], v[184:187], v[234:237], v[12:15]
	v_mfma_f32_16x16x32_bf16 v[4:7], v[184:187], v[242:245], v[4:7]
	v_mfma_f32_16x16x32_bf16 v[4:7], v[180:183], v[238:241], v[4:7]
	v_mfma_f32_16x16x32_bf16 v[0:3], v[188:191], v[238:241], v[0:3]
	v_mfma_f32_16x16x32_bf16 v[0:3], v[192:195], v[242:245], v[0:3]
	v_mfma_f32_16x16x32_bf16 v[8:11], v[192:195], v[234:237], v[8:11]
	v_mfma_f32_16x16x32_bf16 v[8:11], v[188:191], v[230:233], v[8:11]
	v_mfma_f32_16x16x32_bf16 v[16:19], v[188:191], v[208:211], v[16:19]
	v_mfma_f32_16x16x32_bf16 v[16:19], v[192:195], v[214:217], v[16:19]
	v_mfma_f32_16x16x32_bf16 v[24:27], v[192:195], v[200:203], v[24:27]
	v_mfma_f32_16x16x32_bf16 v[24:27], v[188:191], v[196:199], v[24:27]
	s_setprio 0
	s_barrier
	s_add_i32 s82, s82, 2
	s_add_u32 s52, s52, 0x100
	s_addc_u32 s53, s53, 0
	s_cmp_gt_u32 s82, 13
	s_cbranch_scc0 .LBB0_191
	s_and_b64 vcc, exec, s[14:15]
	s_cbranch_vccz .LBB0_194
	s_barrier

; #define PG8_STAGE(bufoff, gbase, voff) do { _Pragma("unroll") for (int _i = 0; _i < 2; ++_i) \
;         __builtin_amdgcn_global_load_lds((const unsigned*)((const char*)(gbase) + (voff)[_i]), (LAS unsigned*)(lds + (bufoff) + ldsw + _i * 8192), 16, 0, 0); } while (0)
; #define PG8_LDA(dst, b, h) do { _Pragma("unroll") for (int m = 0; m < 4; ++m) _Pragma("unroll") for (int k = 0; k < 2; ++k) dst[m][k] = *(const LAS bf16x8*)(lds + PG8_SA(b, h) + aoff + m * 2048 + k * 1024); } while (0)
; #define PG8_LDB(dst, b, h) do { _Pragma("unroll") for (int n = 0; n < 2; ++n) _Pragma("unroll") for (int k = 0; k < 2; ++k) dst[n][k] = *(const LAS bf16x8*)(lds + PG8_SB(b, h) + boff + n * 2048 + k * 1024); } while (0)
; #define PG8_MMA(ai, bj, At, Bt) do { __builtin_amdgcn_s_setprio(1); _Pragma("unroll") for (int m = 0; m < 4; ++m) _Pragma("unroll") for (int n = 0; n < 2; ++n) _Pragma("unroll") for (int k = 0; k < 2; ++k) \
;         acc[ai][bj][m][n] = __builtin_amdgcn_mfma_f32_16x16x32_bf16(Bt[n][k], At[m][k], acc[ai][bj][m][n], 0, 0, 0); __builtin_amdgcn_s_setprio(0); } while (0)
; #define PG8_WAIT_V(n) asm volatile("s_waitcnt vmcnt(" #n ")" ::: "memory")
; #define PG8_WAIT_L(n) asm volatile("s_waitcnt lgkmcnt(" #n ")" ::: "memory")
; #define PG8_BAR __builtin_amdgcn_s_barrier()
; #define PG8_SCHED __builtin_amdgcn_sched_barrier(0)
;     ...
;         for (int t = 0; t < nt; t += 2) {
;             const bool last = (t == nt - 2);
;             const char* a1 = PG8_ATILE(cA, cA2, t + 1);
;             const char* a2 = last ? nA : PG8_ATILE(cA, cA2, t + 2); const char* b2 = last ? nB : cB + (size_t)(t + 2) * 128;
;             const char* a3 = last ? nA + kA1 : PG8_ATILE(cA, cA2, t + 3); const char* b3 = b2 + kB1;
;             if constexpr (SP2) {
;             PG8_LDB(B0, 0, 0); PG8_LDB(B1, 0, 1); PG8_SCHED; PG8_LDA(At, 0, 0); PG8_STAGE(PG8_SA(1, 1), a1 + hA, voffA);
;             PG8_WAIT_V(8); PG8_WAIT_L(0); PG8_BAR; PG8_MMA(0, 0, At, B0); PG8_MMA(0, 1, At, B1); PG8_BAR; PG8_SCHED;
;             PG8_LDA(At, 0, 1); PG8_STAGE(PG8_SB(0, 0), b2, voffB); PG8_STAGE(PG8_SB(0, 1), b2 + hB, voffB); PG8_STAGE(PG8_SA(0, 0), a2, voffA);
;             PG8_WAIT_V(8); PG8_WAIT_L(0); PG8_BAR; PG8_MMA(1, 0, At, B0); PG8_MMA(1, 1, At, B1); PG8_BAR; PG8_SCHED;
.LBB0_271:
	s_add_u32 s31, s52, s90
	s_addc_u32 s36, s53, s91
	s_add_u32 s45, s31, 0x100
	s_addc_u32 s54, s36, 0
	s_add_u32 s55, s8, s90
	s_addc_u32 s74, s9, s91
	s_add_u32 s31, s31, 0x180
	s_addc_u32 s36, s36, 0
	s_add_i32 s82, 0, 0x10000
	s_add_i32 s83, 0, 0x14000
	v_add_u32_e32 v144, s82, v231
	v_add_u32_e32 v156, s83, v231
	ds_read_b128 v[132:135], v144
	ds_read_b128 v[136:139], v144 offset:1024
	ds_read_b128 v[140:143], v144 offset:2048
	ds_read_b128 v[144:147], v144 offset:3072
	ds_read_b128 v[148:151], v156
	ds_read_b128 v[152:155], v156 offset:1024
	ds_read_b128 v[182:185], v156 offset:2048
	ds_read_b128 v[186:189], v156 offset:3072
	s_cmpk_eq_i32 s90, 0x700
	s_cselect_b32 s73, s7, s36
	s_cselect_b32 s72, s6, s31
	s_cselect_b32 s75, s4, s74
	s_cselect_b32 s74, s5, s55
	s_cselect_b32 s77, s1, s54
	s_cselect_b32 s76, s3, s45
	v_lshl_add_u64 v[206:207], v[128:129], 0, s[90:91]
	s_add_i32 m0, s80, 0xc000
	ds_read_b128 v[190:193], v233
	ds_read_b128 v[194:197], v233 offset:1024
	ds_read_b128 v[198:201], v233 offset:2048
	ds_read_b128 v[202:205], v233 offset:3072
	ds_read_b128 v[208:211], v233 offset:4096
	ds_read_b128 v[214:217], v233 offset:5120
	ds_read_b128 v[234:237], v233 offset:6144
	ds_read_b128 v[238:241], v233 offset:7168
	global_load_lds_dwordx4 v[206:207], off
	v_lshl_add_u64 v[206:207], v[130:131], 0, s[90:91]
	s_add_i32 m0, s80, 0xe000
	s_nop 0
	global_load_lds_dwordx4 v[206:207], off
	s_waitcnt vmcnt(8)
	s_waitcnt lgkmcnt(0)
	s_barrier
	s_setprio 1
	s_waitcnt lgkmcnt(0)
	v_mfma_f32_16x16x32_bf16 v[124:127], v[132:135], v[190:193], v[124:127]
	v_mfma_f32_16x16x32_bf16 v[124:127], v[136:139], v[194:197], v[124:127]
	v_mfma_f32_16x16x32_bf16 v[108:111], v[136:139], v[202:205], v[108:111]
	v_mfma_f32_16x16x32_bf16 v[108:111], v[132:135], v[198:201], v[108:111]
	v_mfma_f32_16x16x32_bf16 v[92:95], v[132:135], v[208:211], v[92:95]
	v_mfma_f32_16x16x32_bf16 v[92:95], v[136:139], v[214:217], v[92:95]
	v_mfma_f32_16x16x32_bf16 v[76:79], v[136:139], v[238:241], v[76:79]
	v_mfma_f32_16x16x32_bf16 v[76:79], v[132:135], v[234:237], v[76:79]
	v_mfma_f32_16x16x32_bf16 v[72:75], v[140:143], v[234:237], v[72:75]
	v_mfma_f32_16x16x32_bf16 v[72:75], v[144:147], v[238:241], v[72:75]
	v_mfma_f32_16x16x32_bf16 v[88:91], v[144:147], v[214:217], v[88:91]
	v_mfma_f32_16x16x32_bf16 v[88:91], v[140:143], v[208:211], v[88:91]
	v_mfma_f32_16x16x32_bf16 v[104:107], v[140:143], v[198:201], v[104:107]
	v_mfma_f32_16x16x32_bf16 v[104:107], v[144:147], v[202:205], v[104:107]
	v_mfma_f32_16x16x32_bf16 v[120:123], v[144:147], v[194:197], v[120:123]
	v_mfma_f32_16x16x32_bf16 v[120:123], v[140:143], v[190:193], v[120:123]
	s_setprio 0
	s_setprio 1
	v_mfma_f32_16x16x32_bf16 v[116:119], v[148:151], v[190:193], v[116:119]
	v_mfma_f32_16x16x32_bf16 v[116:119], v[152:155], v[194:197], v[116:119]
	v_mfma_f32_16x16x32_bf16 v[100:103], v[152:155], v[202:205], v[100:103]
	v_mfma_f32_16x16x32_bf16 v[100:103], v[148:151], v[198:201], v[100:103]
	v_mfma_f32_16x16x32_bf16 v[84:87], v[148:151], v[208:211], v[84:87]
	v_mfma_f32_16x16x32_bf16 v[84:87], v[152:155], v[214:217], v[84:87]
	v_mfma_f32_16x16x32_bf16 v[68:71], v[152:155], v[238:241], v[68:71]
	v_mfma_f32_16x16x32_bf16 v[68:71], v[148:151], v[234:237], v[68:71]
	v_mfma_f32_16x16x32_bf16 v[64:67], v[182:185], v[234:237], v[64:67]
	v_mfma_f32_16x16x32_bf16 v[64:67], v[186:189], v[238:241], v[64:67]
	v_mfma_f32_16x16x32_bf16 v[80:83], v[186:189], v[214:217], v[80:83]
	v_mfma_f32_16x16x32_bf16 v[80:83], v[182:185], v[208:211], v[80:83]
	v_mfma_f32_16x16x32_bf16 v[96:99], v[182:185], v[198:201], v[96:99]
	v_mfma_f32_16x16x32_bf16 v[96:99], v[186:189], v[202:205], v[96:99]
	v_mfma_f32_16x16x32_bf16 v[112:115], v[186:189], v[194:197], v[112:115]
	v_mfma_f32_16x16x32_bf16 v[112:115], v[182:185], v[190:193], v[112:115]
	s_setprio 0
	s_barrier
	s_add_i32 s31, s82, s79
	v_lshl_add_u64 v[206:207], s[74:75], 0, v[170:171]
	s_mov_b32 m0, s31
	ds_read_b128 v[190:193], v233 offset:16384
	ds_read_b128 v[194:197], v233 offset:17408
	ds_read_b128 v[198:201], v233 offset:18432
	ds_read_b128 v[202:205], v233 offset:19456
	ds_read_b128 v[208:211], v233 offset:20480
	ds_read_b128 v[214:217], v233 offset:21504
	ds_read_b128 v[234:237], v233 offset:22528
	ds_read_b128 v[238:241], v233 offset:23552
	global_load_lds_dwordx4 v[206:207], off
	s_add_i32 m0, s31, 0x2000
	s_add_u32 s54, s74, 0x40000
	v_lshl_add_u64 v[242:243], s[74:75], 0, v[174:175]
	s_addc_u32 s55, s75, 0
	s_add_i32 s31, s83, s79
	global_load_lds_dwordx4 v[242:243], off
	v_lshl_add_u64 v[244:245], s[54:55], 0, v[170:171]
	s_mov_b32 m0, s31
	s_nop 0
	global_load_lds_dwordx4 v[244:245], off
	v_lshl_add_u64 v[244:245], s[54:55], 0, v[174:175]
	s_add_i32 m0, s31, 0x2000
	s_nop 0
	global_load_lds_dwordx4 v[244:245], off
	v_lshl_add_u64 v[244:245], s[76:77], 0, v[168:169]
	s_mov_b32 m0, s80
	s_nop 0
	global_load_lds_dwordx4 v[244:245], off
	v_lshl_add_u64 v[244:245], s[76:77], 0, v[172:173]
	s_mov_b32 m0, s81
	s_nop 0
	global_load_lds_dwordx4 v[244:245], off
	s_waitcnt vmcnt(8)
	s_waitcnt lgkmcnt(0)
	s_barrier
; #define PG8_STAGE(bufoff, gbase, voff) do { _Pragma("unroll") for (int _i = 0; _i < 2; ++_i) \
;         __builtin_amdgcn_global_load_lds((const unsigned*)((const char*)(gbase) + (voff)[_i]), (LAS unsigned*)(lds + (bufoff) + ldsw + _i * 8192), 16, 0, 0); } while (0)
; #define PG8_LDA(dst, b, h) do { _Pragma("unroll") for (int m = 0; m < 4; ++m) _Pragma("unroll") for (int k = 0; k < 2; ++k) dst[m][k] = *(const LAS bf16x8*)(lds + PG8_SA(b, h) + aoff + m * 2048 + k * 1024); } while (0)
; #define PG8_LDB(dst, b, h) do { _Pragma("unroll") for (int n = 0; n < 2; ++n) _Pragma("unroll") for (int k = 0; k < 2; ++k) dst[n][k] = *(const LAS bf16x8*)(lds + PG8_SB(b, h) + boff + n * 2048 + k * 1024); } while (0)
; #define PG8_MMA(ai, bj, At, Bt) do { __builtin_amdgcn_s_setprio(1); _Pragma("unroll") for (int m = 0; m < 4; ++m) _Pragma("unroll") for (int n = 0; n < 2; ++n) _Pragma("unroll") for (int k = 0; k < 2; ++k) \
;         acc[ai][bj][m][n] = __builtin_amdgcn_mfma_f32_16x16x32_bf16(Bt[n][k], At[m][k], acc[ai][bj][m][n], 0, 0, 0); __builtin_amdgcn_s_setprio(0); } while (0)
; #define PG8_WAIT_V(n) asm volatile("s_waitcnt vmcnt(" #n ")" ::: "memory")
; #define PG8_WAIT_L(n) asm volatile("s_waitcnt lgkmcnt(" #n ")" ::: "memory")
; #define PG8_BAR __builtin_amdgcn_s_barrier()
; #define PG8_SCHED __builtin_amdgcn_sched_barrier(0)
;     ...
;             PG8_WAIT_V(8); PG8_WAIT_L(0); PG8_BAR; PG8_MMA(1, 0, At, B0); PG8_MMA(1, 1, At, B1); PG8_BAR; PG8_SCHED;
;             PG8_LDB(B0, 1, 0); PG8_LDB(B1, 1, 1); PG8_SCHED; PG8_LDA(At, 1, 0); PG8_STAGE(PG8_SA(0, 1), a2 + hA, voffA);
;             PG8_WAIT_V(8); PG8_WAIT_L(0); PG8_BAR; PG8_MMA(0, 0, At, B0); PG8_MMA(0, 1, At, B1); PG8_BAR; PG8_SCHED;
	s_setprio 1
	s_waitcnt lgkmcnt(0)
	v_mfma_f32_16x16x32_bf16 v[60:63], v[132:135], v[190:193], v[60:63]
	v_mfma_f32_16x16x32_bf16 v[60:63], v[136:139], v[194:197], v[60:63]
	v_mfma_f32_16x16x32_bf16 v[44:47], v[136:139], v[202:205], v[44:47]
	v_mfma_f32_16x16x32_bf16 v[44:47], v[132:135], v[198:201], v[44:47]
	v_mfma_f32_16x16x32_bf16 v[28:31], v[132:135], v[208:211], v[28:31]
	v_mfma_f32_16x16x32_bf16 v[28:31], v[136:139], v[214:217], v[28:31]
	v_mfma_f32_16x16x32_bf16 v[12:15], v[136:139], v[238:241], v[12:15]
	v_mfma_f32_16x16x32_bf16 v[12:15], v[132:135], v[234:237], v[12:15]
	v_mfma_f32_16x16x32_bf16 v[8:11], v[140:143], v[234:237], v[8:11]
	v_mfma_f32_16x16x32_bf16 v[8:11], v[144:147], v[238:241], v[8:11]
	v_mfma_f32_16x16x32_bf16 v[24:27], v[144:147], v[214:217], v[24:27]
	v_mfma_f32_16x16x32_bf16 v[24:27], v[140:143], v[208:211], v[24:27]
	v_mfma_f32_16x16x32_bf16 v[40:43], v[140:143], v[198:201], v[40:43]
	v_mfma_f32_16x16x32_bf16 v[40:43], v[144:147], v[202:205], v[40:43]
	v_mfma_f32_16x16x32_bf16 v[56:59], v[144:147], v[194:197], v[56:59]
	v_mfma_f32_16x16x32_bf16 v[56:59], v[140:143], v[190:193], v[56:59]
	s_setprio 0
	s_setprio 1
	v_mfma_f32_16x16x32_bf16 v[52:55], v[148:151], v[190:193], v[52:55]
	v_mfma_f32_16x16x32_bf16 v[52:55], v[152:155], v[194:197], v[52:55]
	v_mfma_f32_16x16x32_bf16 v[36:39], v[152:155], v[202:205], v[36:39]
	v_mfma_f32_16x16x32_bf16 v[36:39], v[148:151], v[198:201], v[36:39]
	v_mfma_f32_16x16x32_bf16 v[20:23], v[148:151], v[208:211], v[20:23]
	v_mfma_f32_16x16x32_bf16 v[20:23], v[152:155], v[214:217], v[20:23]
	v_mfma_f32_16x16x32_bf16 v[4:7], v[152:155], v[238:241], v[4:7]
	v_mfma_f32_16x16x32_bf16 v[4:7], v[148:151], v[234:237], v[4:7]
	v_mfma_f32_16x16x32_bf16 v[0:3], v[182:185], v[234:237], v[0:3]
	v_mfma_f32_16x16x32_bf16 v[0:3], v[186:189], v[238:241], v[0:3]
	v_mfma_f32_16x16x32_bf16 v[16:19], v[186:189], v[214:217], v[16:19]
	v_mfma_f32_16x16x32_bf16 v[16:19], v[182:185], v[208:211], v[16:19]
	v_mfma_f32_16x16x32_bf16 v[32:35], v[182:185], v[198:201], v[32:35]
	v_mfma_f32_16x16x32_bf16 v[32:35], v[186:189], v[202:205], v[32:35]
	v_mfma_f32_16x16x32_bf16 v[48:51], v[186:189], v[194:197], v[48:51]
	v_mfma_f32_16x16x32_bf16 v[48:51], v[182:185], v[190:193], v[48:51]
	s_setprio 0
	s_barrier
	s_add_i32 s31, 0, 0x18000
	s_add_i32 s36, 0, 0x1c000
	v_add_u32_e32 v144, s31, v231
	v_add_u32_e32 v156, s36, v231
	ds_read_b128 v[132:135], v144
	ds_read_b128 v[136:139], v144 offset:1024
	ds_read_b128 v[140:143], v144 offset:2048
	ds_read_b128 v[144:147], v144 offset:3072
	ds_read_b128 v[148:151], v156
	ds_read_b128 v[152:155], v156 offset:1024
	ds_read_b128 v[182:185], v156 offset:2048
	ds_read_b128 v[186:189], v156 offset:3072
	s_add_u32 s54, s76, 0x40000
	s_addc_u32 s55, s77, 0
	s_mov_b32 m0, s89
	v_lshl_add_u64 v[244:245], s[54:55], 0, v[168:169]
	ds_read_b128 v[190:193], v233 offset:32768
	ds_read_b128 v[194:197], v233 offset:33792
	ds_read_b128 v[198:201], v233 offset:34816
	ds_read_b128 v[202:205], v233 offset:35840
	ds_read_b128 v[208:211], v233 offset:36864
	ds_read_b128 v[214:217], v233 offset:37888
	ds_read_b128 v[234:237], v233 offset:38912
	ds_read_b128 v[238:241], v233 offset:39936
	global_load_lds_dwordx4 v[244:245], off
	v_lshl_add_u64 v[244:245], s[54:55], 0, v[172:173]
	s_mov_b32 m0, s92
	s_nop 0
	global_load_lds_dwordx4 v[244:245], off
	s_waitcnt vmcnt(8)
	s_waitcnt lgkmcnt(0)
	s_barrier
	s_setprio 1
	s_waitcnt lgkmcnt(0)
	v_mfma_f32_16x16x32_bf16 v[124:127], v[132:135], v[190:193], v[124:127]
	v_mfma_f32_16x16x32_bf16 v[124:127], v[136:139], v[194:197], v[124:127]
	v_mfma_f32_16x16x32_bf16 v[108:111], v[136:139], v[202:205], v[108:111]
	v_mfma_f32_16x16x32_bf16 v[108:111], v[132:135], v[198:201], v[108:111]
	v_mfma_f32_16x16x32_bf16 v[92:95], v[132:135], v[208:211], v[92:95]
	v_mfma_f32_16x16x32_bf16 v[92:95], v[136:139], v[214:217], v[92:95]
	v_mfma_f32_16x16x32_bf16 v[76:79], v[136:139], v[238:241], v[76:79]
	v_mfma_f32_16x16x32_bf16 v[76:79], v[132:135], v[234:237], v[76:79]
	v_mfma_f32_16x16x32_bf16 v[72:75], v[140:143], v[234:237], v[72:75]
	v_mfma_f32_16x16x32_bf16 v[72:75], v[144:147], v[238:241], v[72:75]
	v_mfma_f32_16x16x32_bf16 v[88:91], v[144:147], v[214:217], v[88:91]
	v_mfma_f32_16x16x32_bf16 v[88:91], v[140:143], v[208:211], v[88:91]
	v_mfma_f32_16x16x32_bf16 v[104:107], v[140:143], v[198:201], v[104:107]
	v_mfma_f32_16x16x32_bf16 v[104:107], v[144:147], v[202:205], v[104:107]
	v_mfma_f32_16x16x32_bf16 v[120:123], v[144:147], v[194:197], v[120:123]
	v_mfma_f32_16x16x32_bf16 v[120:123], v[140:143], v[190:193], v[120:123]
	s_setprio 0
	s_setprio 1
	v_mfma_f32_16x16x32_bf16 v[116:119], v[148:151], v[190:193], v[116:119]
	v_mfma_f32_16x16x32_bf16 v[116:119], v[152:155], v[194:197], v[116:119]
	v_mfma_f32_16x16x32_bf16 v[100:103], v[152:155], v[202:205], v[100:103]
	v_mfma_f32_16x16x32_bf16 v[100:103], v[148:151], v[198:201], v[100:103]
	v_mfma_f32_16x16x32_bf16 v[84:87], v[148:151], v[208:211], v[84:87]
	v_mfma_f32_16x16x32_bf16 v[84:87], v[152:155], v[214:217], v[84:87]
	v_mfma_f32_16x16x32_bf16 v[68:71], v[152:155], v[238:241], v[68:71]
	v_mfma_f32_16x16x32_bf16 v[68:71], v[148:151], v[234:237], v[68:71]
	v_mfma_f32_16x16x32_bf16 v[64:67], v[182:185], v[234:237], v[64:67]
	v_mfma_f32_16x16x32_bf16 v[64:67], v[186:189], v[238:241], v[64:67]
	v_mfma_f32_16x16x32_bf16 v[80:83], v[186:189], v[214:217], v[80:83]
	v_mfma_f32_16x16x32_bf16 v[80:83], v[182:185], v[208:211], v[80:83]
	v_mfma_f32_16x16x32_bf16 v[96:99], v[182:185], v[198:201], v[96:99]
	v_mfma_f32_16x16x32_bf16 v[96:99], v[186:189], v[202:205], v[96:99]
	v_mfma_f32_16x16x32_bf16 v[112:115], v[186:189], v[194:197], v[112:115]
	v_mfma_f32_16x16x32_bf16 v[112:115], v[182:185], v[190:193], v[112:115]
	s_setprio 0
	s_barrier
; #define PG8_STAGE(bufoff, gbase, voff) do { _Pragma("unroll") for (int _i = 0; _i < 2; ++_i) \
;         __builtin_amdgcn_global_load_lds((const unsigned*)((const char*)(gbase) + (voff)[_i]), (LAS unsigned*)(lds + (bufoff) + ldsw + _i * 8192), 16, 0, 0); } while (0)
; #define PG8_LDA(dst, b, h) do { _Pragma("unroll") for (int m = 0; m < 4; ++m) _Pragma("unroll") for (int k = 0; k < 2; ++k) dst[m][k] = *(const LAS bf16x8*)(lds + PG8_SA(b, h) + aoff + m * 2048 + k * 1024); } while (0)
; #define PG8_MMA(ai, bj, At, Bt) do { __builtin_amdgcn_s_setprio(1); _Pragma("unroll") for (int m = 0; m < 4; ++m) _Pragma("unroll") for (int n = 0; n < 2; ++n) _Pragma("unroll") for (int k = 0; k < 2; ++k) \
;         acc[ai][bj][m][n] = __builtin_amdgcn_mfma_f32_16x16x32_bf16(Bt[n][k], At[m][k], acc[ai][bj][m][n], 0, 0, 0); __builtin_amdgcn_s_setprio(0); } while (0)
; #define PG8_WAIT_V(n) asm volatile("s_waitcnt vmcnt(" #n ")" ::: "memory")
; #define PG8_WAIT_L(n) asm volatile("s_waitcnt lgkmcnt(" #n ")" ::: "memory")
; #define PG8_BAR __builtin_amdgcn_s_barrier()
; #define PG8_SCHED __builtin_amdgcn_sched_barrier(0)
;     ...
;             PG8_LDA(At, 1, 1); PG8_STAGE(PG8_SB(1, 0), b3, voffB); PG8_STAGE(PG8_SB(1, 1), b3 + hB, voffB); PG8_STAGE(PG8_SA(1, 0), a3, voffA);
;             PG8_WAIT_V(8); PG8_WAIT_L(0); PG8_BAR; PG8_MMA(1, 0, At, B0); PG8_MMA(1, 1, At, B1); PG8_BAR; PG8_SCHED;
;     ...
;         if constexpr (ALIGN_EPI) { if (wr == 0) PG8_BAR; }
	s_add_i32 s31, s31, s79
	v_lshl_add_u64 v[206:207], v[206:207], 0, s[38:39]
	s_mov_b32 m0, s31
	ds_read_b128 v[190:193], v233 offset:49152
	ds_read_b128 v[194:197], v233 offset:50176
	ds_read_b128 v[198:201], v233 offset:51200
	ds_read_b128 v[202:205], v233 offset:52224
	ds_read_b128 v[208:211], v233 offset:53248
	ds_read_b128 v[214:217], v233 offset:54272
	ds_read_b128 v[234:237], v233 offset:55296
	ds_read_b128 v[238:241], v233 offset:56320
	global_load_lds_dwordx4 v[206:207], off
	s_add_i32 m0, s31, 0x2000
	s_add_u32 s54, s74, 0x40080
	v_lshl_add_u64 v[206:207], v[242:243], 0, s[38:39]
	s_addc_u32 s55, s75, 0
	s_add_i32 s31, s36, s79
	global_load_lds_dwordx4 v[206:207], off
	v_lshl_add_u64 v[206:207], s[54:55], 0, v[170:171]
	s_mov_b32 m0, s31
	s_nop 0
	global_load_lds_dwordx4 v[206:207], off
	v_lshl_add_u64 v[206:207], s[54:55], 0, v[174:175]
	s_add_i32 m0, s31, 0x2000
	s_nop 0
	global_load_lds_dwordx4 v[206:207], off
	v_lshl_add_u64 v[206:207], s[72:73], 0, v[168:169]
	s_mov_b32 m0, s95
	s_nop 0
	global_load_lds_dwordx4 v[206:207], off
	v_lshl_add_u64 v[206:207], s[72:73], 0, v[172:173]
	s_mov_b32 m0, s42
	s_nop 0
	global_load_lds_dwordx4 v[206:207], off
	s_waitcnt vmcnt(8)
	s_waitcnt lgkmcnt(0)
	s_barrier
	s_setprio 1
	s_waitcnt lgkmcnt(0)
	v_mfma_f32_16x16x32_bf16 v[60:63], v[132:135], v[190:193], v[60:63]
	v_mfma_f32_16x16x32_bf16 v[60:63], v[136:139], v[194:197], v[60:63]
	v_mfma_f32_16x16x32_bf16 v[44:47], v[136:139], v[202:205], v[44:47]
	v_mfma_f32_16x16x32_bf16 v[44:47], v[132:135], v[198:201], v[44:47]
	v_mfma_f32_16x16x32_bf16 v[28:31], v[132:135], v[208:211], v[28:31]
	v_mfma_f32_16x16x32_bf16 v[28:31], v[136:139], v[214:217], v[28:31]
	v_mfma_f32_16x16x32_bf16 v[12:15], v[136:139], v[238:241], v[12:15]
	v_mfma_f32_16x16x32_bf16 v[12:15], v[132:135], v[234:237], v[12:15]
	v_mfma_f32_16x16x32_bf16 v[8:11], v[140:143], v[234:237], v[8:11]
	v_mfma_f32_16x16x32_bf16 v[8:11], v[144:147], v[238:241], v[8:11]
	v_mfma_f32_16x16x32_bf16 v[24:27], v[144:147], v[214:217], v[24:27]
	v_mfma_f32_16x16x32_bf16 v[24:27], v[140:143], v[208:211], v[24:27]
	v_mfma_f32_16x16x32_bf16 v[40:43], v[140:143], v[198:201], v[40:43]
	v_mfma_f32_16x16x32_bf16 v[40:43], v[144:147], v[202:205], v[40:43]
	v_mfma_f32_16x16x32_bf16 v[56:59], v[144:147], v[194:197], v[56:59]
	v_mfma_f32_16x16x32_bf16 v[56:59], v[140:143], v[190:193], v[56:59]
	s_setprio 0
	s_setprio 1
	v_mfma_f32_16x16x32_bf16 v[52:55], v[148:151], v[190:193], v[52:55]
	v_mfma_f32_16x16x32_bf16 v[52:55], v[152:155], v[194:197], v[52:55]
	v_mfma_f32_16x16x32_bf16 v[36:39], v[152:155], v[202:205], v[36:39]
	v_mfma_f32_16x16x32_bf16 v[36:39], v[148:151], v[198:201], v[36:39]
	v_mfma_f32_16x16x32_bf16 v[20:23], v[148:151], v[208:211], v[20:23]
	v_mfma_f32_16x16x32_bf16 v[20:23], v[152:155], v[214:217], v[20:23]
	v_mfma_f32_16x16x32_bf16 v[4:7], v[152:155], v[238:241], v[4:7]
	v_mfma_f32_16x16x32_bf16 v[4:7], v[148:151], v[234:237], v[4:7]
	v_mfma_f32_16x16x32_bf16 v[0:3], v[182:185], v[234:237], v[0:3]
	v_mfma_f32_16x16x32_bf16 v[0:3], v[186:189], v[238:241], v[0:3]
	v_mfma_f32_16x16x32_bf16 v[16:19], v[186:189], v[214:217], v[16:19]
	v_mfma_f32_16x16x32_bf16 v[16:19], v[182:185], v[208:211], v[16:19]
	v_mfma_f32_16x16x32_bf16 v[32:35], v[182:185], v[198:201], v[32:35]
	v_mfma_f32_16x16x32_bf16 v[32:35], v[186:189], v[202:205], v[32:35]
	v_mfma_f32_16x16x32_bf16 v[48:51], v[186:189], v[194:197], v[48:51]
	v_mfma_f32_16x16x32_bf16 v[48:51], v[182:185], v[190:193], v[48:51]
	s_setprio 0
	s_barrier
	s_add_i32 s13, s13, 2
	s_add_u32 s90, s90, 0x100
	s_addc_u32 s91, s91, 0
	s_cmp_gt_u32 s13, 13
	s_cbranch_scc0 .LBB0_271
	s_and_b64 vcc, exec, s[28:29]
	s_cbranch_vccz .LBB0_274
	s_barrier

; #define PG8_STAGE(bufoff, gbase, voff) do { _Pragma("unroll") for (int _i = 0; _i < 2; ++_i) \
;         __builtin_amdgcn_global_load_lds((const unsigned*)((const char*)(gbase) + (voff)[_i]), (LAS unsigned*)(lds + (bufoff) + ldsw + _i * 8192), 16, 0, 0); } while (0)
; #define PG8_LDA(dst, b, h) do { _Pragma("unroll") for (int m = 0; m < 4; ++m) _Pragma("unroll") for (int k = 0; k < 2; ++k) dst[m][k] = *(const LAS bf16x8*)(lds + PG8_SA(b, h) + aoff + m * 2048 + k * 1024); } while (0)
; #define PG8_LDB(dst, b, h) do { _Pragma("unroll") for (int n = 0; n < 2; ++n) _Pragma("unroll") for (int k = 0; k < 2; ++k) dst[n][k] = *(const LAS bf16x8*)(lds + PG8_SB(b, h) + boff + n * 2048 + k * 1024); } while (0)
; #define PG8_MMA(ai, bj, At, Bt) do { __builtin_amdgcn_s_setprio(1); _Pragma("unroll") for (int m = 0; m < 4; ++m) _Pragma("unroll") for (int n = 0; n < 2; ++n) _Pragma("unroll") for (int k = 0; k < 2; ++k) \
;         acc[ai][bj][m][n] = __builtin_amdgcn_mfma_f32_16x16x32_bf16(Bt[n][k], At[m][k], acc[ai][bj][m][n], 0, 0, 0); __builtin_amdgcn_s_setprio(0); } while (0)
; #define PG8_WAIT_V(n) asm volatile("s_waitcnt vmcnt(" #n ")" ::: "memory")
; #define PG8_WAIT_L(n) asm volatile("s_waitcnt lgkmcnt(" #n ")" ::: "memory")
; #define PG8_BAR __builtin_amdgcn_s_barrier()
; #define PG8_SCHED __builtin_amdgcn_sched_barrier(0)
;     ...
;         for (int t = 0; t < nt; t += 2) {
;             const bool last = (t == nt - 2);
;             const char* a1 = PG8_ATILE(cA, cA2, t + 1);
;             const char* a2 = last ? nA : PG8_ATILE(cA, cA2, t + 2); const char* b2 = last ? nB : cB + (size_t)(t + 2) * 128;
;             const char* a3 = last ? nA + kA1 : PG8_ATILE(cA, cA2, t + 3); const char* b3 = b2 + kB1;
;             if constexpr (SP2) {
;             PG8_LDB(B0, 0, 0); PG8_LDB(B1, 0, 1); PG8_SCHED; PG8_LDA(At, 0, 0); PG8_STAGE(PG8_SA(1, 1), a1 + hA, voffA);
;             PG8_WAIT_V(8); PG8_WAIT_L(0); PG8_BAR; PG8_MMA(0, 0, At, B0); PG8_MMA(0, 1, At, B1); PG8_BAR; PG8_SCHED;
;             PG8_LDA(At, 0, 1); PG8_STAGE(PG8_SB(0, 0), b2, voffB); PG8_STAGE(PG8_SB(0, 1), b2 + hB, voffB); PG8_STAGE(PG8_SA(0, 0), a2, voffA);
;             PG8_WAIT_V(8); PG8_WAIT_L(0); PG8_BAR; PG8_MMA(1, 0, At, B0); PG8_MMA(1, 1, At, B1); PG8_BAR; PG8_SCHED;
.LBB0_299:
	s_add_u32 s72, s44, s52
	s_addc_u32 s73, s45, s53
	s_add_u32 s98, s72, 0x40080
	s_addc_u32 s99, s73, 0
	s_add_u32 s76, s72, 0x100
	s_addc_u32 s77, s73, 0
	s_add_u32 s74, s79, s52
	s_addc_u32 s75, s80, s53
	s_add_u32 s72, s72, 0x180
	s_addc_u32 s73, s73, 0
	s_add_i32 s82, 0, 0x10000
	s_add_i32 s89, 0, 0x14000
	v_add_u32_e32 v144, s82, v193
	v_add_u32_e32 v184, s89, v193
	ds_read_b128 v[132:135], v144
	ds_read_b128 v[136:139], v144 offset:1024
	ds_read_b128 v[140:143], v144 offset:2048
	ds_read_b128 v[144:147], v144 offset:3072
	ds_read_b128 v[148:151], v184
	ds_read_b128 v[176:179], v184 offset:1024
	ds_read_b128 v[180:183], v184 offset:2048
	ds_read_b128 v[184:187], v184 offset:3072
	s_cmpk_eq_i32 s52, 0x700
	s_cselect_b32 s73, s78, s73
	s_cselect_b32 s72, s55, s72
	s_cselect_b32 s75, s27, s75
	s_cselect_b32 s74, s54, s74
	s_cselect_b32 s77, s3, s77
	s_cselect_b32 s76, s29, s76
	s_add_i32 m0, s6, 0xc000
	ds_read_b128 v[188:191], v198
	ds_read_b128 v[200:203], v198 offset:1024
	ds_read_b128 v[208:211], v198 offset:2048
	ds_read_b128 v[214:217], v198 offset:3072
	ds_read_b128 v[230:233], v198 offset:4096
	ds_read_b128 v[234:237], v198 offset:5120
	ds_read_b128 v[238:241], v198 offset:6144
	ds_read_b128 v[242:245], v198 offset:7168
	global_load_lds_dwordx4 v172, s[98:99]
	s_add_i32 m0, s6, 0xe000
	s_nop 0
	global_load_lds_dwordx4 v174, s[98:99]
	s_waitcnt vmcnt(8)
	s_waitcnt lgkmcnt(0)
	s_barrier
	s_setprio 1
	s_waitcnt lgkmcnt(0)
	v_mfma_f32_16x16x32_bf16 v[124:127], v[132:135], v[188:191], v[124:127]
	v_mfma_f32_16x16x32_bf16 v[124:127], v[136:139], v[200:203], v[124:127]
	v_mfma_f32_16x16x32_bf16 v[108:111], v[136:139], v[214:217], v[108:111]
	v_mfma_f32_16x16x32_bf16 v[108:111], v[132:135], v[208:211], v[108:111]
	v_mfma_f32_16x16x32_bf16 v[92:95], v[132:135], v[230:233], v[92:95]
	v_mfma_f32_16x16x32_bf16 v[92:95], v[136:139], v[234:237], v[92:95]
	v_mfma_f32_16x16x32_bf16 v[76:79], v[136:139], v[242:245], v[76:79]
	v_mfma_f32_16x16x32_bf16 v[76:79], v[132:135], v[238:241], v[76:79]
	v_mfma_f32_16x16x32_bf16 v[72:75], v[140:143], v[238:241], v[72:75]
	v_mfma_f32_16x16x32_bf16 v[72:75], v[144:147], v[242:245], v[72:75]
	v_mfma_f32_16x16x32_bf16 v[88:91], v[144:147], v[234:237], v[88:91]
	v_mfma_f32_16x16x32_bf16 v[88:91], v[140:143], v[230:233], v[88:91]
	v_mfma_f32_16x16x32_bf16 v[104:107], v[140:143], v[208:211], v[104:107]
	v_mfma_f32_16x16x32_bf16 v[104:107], v[144:147], v[214:217], v[104:107]
	v_mfma_f32_16x16x32_bf16 v[120:123], v[144:147], v[200:203], v[120:123]
	v_mfma_f32_16x16x32_bf16 v[120:123], v[140:143], v[188:191], v[120:123]
	s_setprio 0
	s_setprio 1
	v_mfma_f32_16x16x32_bf16 v[116:119], v[148:151], v[188:191], v[116:119]
	v_mfma_f32_16x16x32_bf16 v[116:119], v[176:179], v[200:203], v[116:119]
	v_mfma_f32_16x16x32_bf16 v[100:103], v[176:179], v[214:217], v[100:103]
	v_mfma_f32_16x16x32_bf16 v[100:103], v[148:151], v[208:211], v[100:103]
	v_mfma_f32_16x16x32_bf16 v[84:87], v[148:151], v[230:233], v[84:87]
	v_mfma_f32_16x16x32_bf16 v[84:87], v[176:179], v[234:237], v[84:87]
	v_mfma_f32_16x16x32_bf16 v[68:71], v[176:179], v[242:245], v[68:71]
	v_mfma_f32_16x16x32_bf16 v[68:71], v[148:151], v[238:241], v[68:71]
	v_mfma_f32_16x16x32_bf16 v[64:67], v[180:183], v[238:241], v[64:67]
	v_mfma_f32_16x16x32_bf16 v[64:67], v[184:187], v[242:245], v[64:67]
	v_mfma_f32_16x16x32_bf16 v[80:83], v[184:187], v[234:237], v[80:83]
	v_mfma_f32_16x16x32_bf16 v[80:83], v[180:183], v[230:233], v[80:83]
	v_mfma_f32_16x16x32_bf16 v[96:99], v[180:183], v[208:211], v[96:99]
	v_mfma_f32_16x16x32_bf16 v[96:99], v[184:187], v[214:217], v[96:99]
	v_mfma_f32_16x16x32_bf16 v[112:115], v[184:187], v[200:203], v[112:115]
	v_mfma_f32_16x16x32_bf16 v[112:115], v[180:183], v[188:191], v[112:115]
	s_setprio 0
	s_barrier
	s_add_i32 s82, s82, s5
	s_mov_b32 m0, s82
	ds_read_b128 v[188:191], v198 offset:16384
	ds_read_b128 v[200:203], v198 offset:17408
	ds_read_b128 v[208:211], v198 offset:18432
	ds_read_b128 v[214:217], v198 offset:19456
	ds_read_b128 v[230:233], v198 offset:20480
	ds_read_b128 v[234:237], v198 offset:21504
	ds_read_b128 v[238:241], v198 offset:22528
	ds_read_b128 v[242:245], v198 offset:23552
	global_load_lds_dwordx4 v156, s[74:75]
	s_add_i32 m0, s82, 0x2000
	s_add_u32 s82, s74, 0x40000
	s_addc_u32 s83, s75, 0
	s_add_i32 s89, s89, s5
	global_load_lds_dwordx4 v168, s[74:75]
	s_mov_b32 m0, s89
	s_nop 0
	global_load_lds_dwordx4 v156, s[82:83]
	s_add_i32 m0, s89, 0x2000
	s_nop 0
	global_load_lds_dwordx4 v168, s[82:83]
	s_mov_b32 m0, s6
	s_nop 0
	global_load_lds_dwordx4 v152, s[76:77]
	s_mov_b32 m0, s7
	s_nop 0
	global_load_lds_dwordx4 v154, s[76:77]
	s_waitcnt vmcnt(8)
	s_waitcnt lgkmcnt(0)
	s_barrier
; #define PG8_STAGE(bufoff, gbase, voff) do { _Pragma("unroll") for (int _i = 0; _i < 2; ++_i) \
;         __builtin_amdgcn_global_load_lds((const unsigned*)((const char*)(gbase) + (voff)[_i]), (LAS unsigned*)(lds + (bufoff) + ldsw + _i * 8192), 16, 0, 0); } while (0)
; #define PG8_LDA(dst, b, h) do { _Pragma("unroll") for (int m = 0; m < 4; ++m) _Pragma("unroll") for (int k = 0; k < 2; ++k) dst[m][k] = *(const LAS bf16x8*)(lds + PG8_SA(b, h) + aoff + m * 2048 + k * 1024); } while (0)
; #define PG8_LDB(dst, b, h) do { _Pragma("unroll") for (int n = 0; n < 2; ++n) _Pragma("unroll") for (int k = 0; k < 2; ++k) dst[n][k] = *(const LAS bf16x8*)(lds + PG8_SB(b, h) + boff + n * 2048 + k * 1024); } while (0)
; #define PG8_MMA(ai, bj, At, Bt) do { __builtin_amdgcn_s_setprio(1); _Pragma("unroll") for (int m = 0; m < 4; ++m) _Pragma("unroll") for (int n = 0; n < 2; ++n) _Pragma("unroll") for (int k = 0; k < 2; ++k) \
;         acc[ai][bj][m][n] = __builtin_amdgcn_mfma_f32_16x16x32_bf16(Bt[n][k], At[m][k], acc[ai][bj][m][n], 0, 0, 0); __builtin_amdgcn_s_setprio(0); } while (0)
; #define PG8_WAIT_V(n) asm volatile("s_waitcnt vmcnt(" #n ")" ::: "memory")
; #define PG8_WAIT_L(n) asm volatile("s_waitcnt lgkmcnt(" #n ")" ::: "memory")
; #define PG8_BAR __builtin_amdgcn_s_barrier()
; #define PG8_SCHED __builtin_amdgcn_sched_barrier(0)
;     ...
;             PG8_WAIT_V(8); PG8_WAIT_L(0); PG8_BAR; PG8_MMA(1, 0, At, B0); PG8_MMA(1, 1, At, B1); PG8_BAR; PG8_SCHED;
;             PG8_LDB(B0, 1, 0); PG8_LDB(B1, 1, 1); PG8_SCHED; PG8_LDA(At, 1, 0); PG8_STAGE(PG8_SA(0, 1), a2 + hA, voffA);
;             PG8_WAIT_V(8); PG8_WAIT_L(0); PG8_BAR; PG8_MMA(0, 0, At, B0); PG8_MMA(0, 1, At, B1); PG8_BAR; PG8_SCHED;
	s_setprio 1
	s_waitcnt lgkmcnt(0)
	v_mfma_f32_16x16x32_bf16 v[60:63], v[132:135], v[188:191], v[60:63]
	v_mfma_f32_16x16x32_bf16 v[60:63], v[136:139], v[200:203], v[60:63]
	v_mfma_f32_16x16x32_bf16 v[44:47], v[136:139], v[214:217], v[44:47]
	v_mfma_f32_16x16x32_bf16 v[44:47], v[132:135], v[208:211], v[44:47]
	v_mfma_f32_16x16x32_bf16 v[28:31], v[132:135], v[230:233], v[28:31]
	v_mfma_f32_16x16x32_bf16 v[28:31], v[136:139], v[234:237], v[28:31]
	v_mfma_f32_16x16x32_bf16 v[12:15], v[136:139], v[242:245], v[12:15]
	v_mfma_f32_16x16x32_bf16 v[12:15], v[132:135], v[238:241], v[12:15]
	v_mfma_f32_16x16x32_bf16 v[8:11], v[140:143], v[238:241], v[8:11]
	v_mfma_f32_16x16x32_bf16 v[8:11], v[144:147], v[242:245], v[8:11]
	v_mfma_f32_16x16x32_bf16 v[24:27], v[144:147], v[234:237], v[24:27]
	v_mfma_f32_16x16x32_bf16 v[24:27], v[140:143], v[230:233], v[24:27]
	v_mfma_f32_16x16x32_bf16 v[40:43], v[140:143], v[208:211], v[40:43]
	v_mfma_f32_16x16x32_bf16 v[40:43], v[144:147], v[214:217], v[40:43]
	v_mfma_f32_16x16x32_bf16 v[56:59], v[144:147], v[200:203], v[56:59]
	v_mfma_f32_16x16x32_bf16 v[56:59], v[140:143], v[188:191], v[56:59]
	s_setprio 0
	s_setprio 1
	v_mfma_f32_16x16x32_bf16 v[52:55], v[148:151], v[188:191], v[52:55]
	v_mfma_f32_16x16x32_bf16 v[52:55], v[176:179], v[200:203], v[52:55]
	v_mfma_f32_16x16x32_bf16 v[36:39], v[176:179], v[214:217], v[36:39]
	v_mfma_f32_16x16x32_bf16 v[36:39], v[148:151], v[208:211], v[36:39]
	v_mfma_f32_16x16x32_bf16 v[20:23], v[148:151], v[230:233], v[20:23]
	v_mfma_f32_16x16x32_bf16 v[20:23], v[176:179], v[234:237], v[20:23]
	v_mfma_f32_16x16x32_bf16 v[4:7], v[176:179], v[242:245], v[4:7]
	v_mfma_f32_16x16x32_bf16 v[4:7], v[148:151], v[238:241], v[4:7]
	v_mfma_f32_16x16x32_bf16 v[0:3], v[180:183], v[238:241], v[0:3]
	v_mfma_f32_16x16x32_bf16 v[0:3], v[184:187], v[242:245], v[0:3]
	v_mfma_f32_16x16x32_bf16 v[16:19], v[184:187], v[234:237], v[16:19]
	v_mfma_f32_16x16x32_bf16 v[16:19], v[180:183], v[230:233], v[16:19]
	v_mfma_f32_16x16x32_bf16 v[32:35], v[180:183], v[208:211], v[32:35]
	v_mfma_f32_16x16x32_bf16 v[32:35], v[184:187], v[214:217], v[32:35]
	v_mfma_f32_16x16x32_bf16 v[48:51], v[184:187], v[200:203], v[48:51]
	v_mfma_f32_16x16x32_bf16 v[48:51], v[180:183], v[188:191], v[48:51]
	s_setprio 0
	s_barrier
	s_add_i32 s82, 0, 0x18000
	s_add_i32 s83, 0, 0x1c000
	v_add_u32_e32 v144, s82, v193
	v_add_u32_e32 v184, s83, v193
	ds_read_b128 v[132:135], v144
	ds_read_b128 v[136:139], v144 offset:1024
	ds_read_b128 v[140:143], v144 offset:2048
	ds_read_b128 v[144:147], v144 offset:3072
	ds_read_b128 v[148:151], v184
	ds_read_b128 v[176:179], v184 offset:1024
	ds_read_b128 v[180:183], v184 offset:2048
	ds_read_b128 v[184:187], v184 offset:3072
	s_add_u32 s76, s76, 0x40000
	s_addc_u32 s77, s77, 0
	s_mov_b32 m0, s8
	ds_read_b128 v[188:191], v198 offset:32768
	ds_read_b128 v[200:203], v198 offset:33792
	ds_read_b128 v[208:211], v198 offset:34816
	ds_read_b128 v[214:217], v198 offset:35840
	ds_read_b128 v[230:233], v198 offset:36864
	ds_read_b128 v[234:237], v198 offset:37888
	ds_read_b128 v[238:241], v198 offset:38912
	ds_read_b128 v[242:245], v198 offset:39936
	global_load_lds_dwordx4 v152, s[76:77]
	s_mov_b32 m0, s9
	s_nop 0
	global_load_lds_dwordx4 v154, s[76:77]
	s_waitcnt vmcnt(8)
	s_waitcnt lgkmcnt(0)
	s_barrier
	s_setprio 1
	s_waitcnt lgkmcnt(0)
	v_mfma_f32_16x16x32_bf16 v[124:127], v[132:135], v[188:191], v[124:127]
	v_mfma_f32_16x16x32_bf16 v[124:127], v[136:139], v[200:203], v[124:127]
	v_mfma_f32_16x16x32_bf16 v[108:111], v[136:139], v[214:217], v[108:111]
	v_mfma_f32_16x16x32_bf16 v[108:111], v[132:135], v[208:211], v[108:111]
	v_mfma_f32_16x16x32_bf16 v[92:95], v[132:135], v[230:233], v[92:95]
	v_mfma_f32_16x16x32_bf16 v[92:95], v[136:139], v[234:237], v[92:95]
	v_mfma_f32_16x16x32_bf16 v[76:79], v[136:139], v[242:245], v[76:79]
	v_mfma_f32_16x16x32_bf16 v[76:79], v[132:135], v[238:241], v[76:79]
	v_mfma_f32_16x16x32_bf16 v[72:75], v[140:143], v[238:241], v[72:75]
	v_mfma_f32_16x16x32_bf16 v[72:75], v[144:147], v[242:245], v[72:75]
	v_mfma_f32_16x16x32_bf16 v[88:91], v[144:147], v[234:237], v[88:91]
	v_mfma_f32_16x16x32_bf16 v[88:91], v[140:143], v[230:233], v[88:91]
	v_mfma_f32_16x16x32_bf16 v[104:107], v[140:143], v[208:211], v[104:107]
	v_mfma_f32_16x16x32_bf16 v[104:107], v[144:147], v[214:217], v[104:107]
	v_mfma_f32_16x16x32_bf16 v[120:123], v[144:147], v[200:203], v[120:123]
	v_mfma_f32_16x16x32_bf16 v[120:123], v[140:143], v[188:191], v[120:123]
	s_setprio 0
	s_setprio 1
	v_mfma_f32_16x16x32_bf16 v[116:119], v[148:151], v[188:191], v[116:119]
	v_mfma_f32_16x16x32_bf16 v[116:119], v[176:179], v[200:203], v[116:119]
	v_mfma_f32_16x16x32_bf16 v[100:103], v[176:179], v[214:217], v[100:103]
	v_mfma_f32_16x16x32_bf16 v[100:103], v[148:151], v[208:211], v[100:103]
	v_mfma_f32_16x16x32_bf16 v[84:87], v[148:151], v[230:233], v[84:87]
	v_mfma_f32_16x16x32_bf16 v[84:87], v[176:179], v[234:237], v[84:87]
	v_mfma_f32_16x16x32_bf16 v[68:71], v[176:179], v[242:245], v[68:71]
	v_mfma_f32_16x16x32_bf16 v[68:71], v[148:151], v[238:241], v[68:71]
	v_mfma_f32_16x16x32_bf16 v[64:67], v[180:183], v[238:241], v[64:67]
	v_mfma_f32_16x16x32_bf16 v[64:67], v[184:187], v[242:245], v[64:67]
	v_mfma_f32_16x16x32_bf16 v[80:83], v[184:187], v[234:237], v[80:83]
	v_mfma_f32_16x16x32_bf16 v[80:83], v[180:183], v[230:233], v[80:83]
	v_mfma_f32_16x16x32_bf16 v[96:99], v[180:183], v[208:211], v[96:99]
	v_mfma_f32_16x16x32_bf16 v[96:99], v[184:187], v[214:217], v[96:99]
	v_mfma_f32_16x16x32_bf16 v[112:115], v[184:187], v[200:203], v[112:115]
	v_mfma_f32_16x16x32_bf16 v[112:115], v[180:183], v[188:191], v[112:115]
	s_setprio 0
	s_barrier
; #define PG8_STAGE(bufoff, gbase, voff) do { _Pragma("unroll") for (int _i = 0; _i < 2; ++_i) \
;         __builtin_amdgcn_global_load_lds((const unsigned*)((const char*)(gbase) + (voff)[_i]), (LAS unsigned*)(lds + (bufoff) + ldsw + _i * 8192), 16, 0, 0); } while (0)
; #define PG8_LDA(dst, b, h) do { _Pragma("unroll") for (int m = 0; m < 4; ++m) _Pragma("unroll") for (int k = 0; k < 2; ++k) dst[m][k] = *(const LAS bf16x8*)(lds + PG8_SA(b, h) + aoff + m * 2048 + k * 1024); } while (0)
; #define PG8_MMA(ai, bj, At, Bt) do { __builtin_amdgcn_s_setprio(1); _Pragma("unroll") for (int m = 0; m < 4; ++m) _Pragma("unroll") for (int n = 0; n < 2; ++n) _Pragma("unroll") for (int k = 0; k < 2; ++k) \
;         acc[ai][bj][m][n] = __builtin_amdgcn_mfma_f32_16x16x32_bf16(Bt[n][k], At[m][k], acc[ai][bj][m][n], 0, 0, 0); __builtin_amdgcn_s_setprio(0); } while (0)
; #define PG8_WAIT_V(n) asm volatile("s_waitcnt vmcnt(" #n ")" ::: "memory")
; #define PG8_WAIT_L(n) asm volatile("s_waitcnt lgkmcnt(" #n ")" ::: "memory")
; #define PG8_BAR __builtin_amdgcn_s_barrier()
; #define PG8_SCHED __builtin_amdgcn_sched_barrier(0)
;     ...
;             PG8_LDA(At, 1, 1); PG8_STAGE(PG8_SB(1, 0), b3, voffB); PG8_STAGE(PG8_SB(1, 1), b3 + hB, voffB); PG8_STAGE(PG8_SA(1, 0), a3, voffA);
;             PG8_WAIT_V(8); PG8_WAIT_L(0); PG8_BAR; PG8_MMA(1, 0, At, B0); PG8_MMA(1, 1, At, B1); PG8_BAR; PG8_SCHED;
;     ...
;         if constexpr (ALIGN_EPI) { if (wr == 0) PG8_BAR; }
	s_add_i32 s76, s82, s5
	s_add_u32 s100, s74, s38
	s_addc_u32 s101, s75, s39
	s_mov_b32 m0, s76
	ds_read_b128 v[188:191], v198 offset:49152
	ds_read_b128 v[200:203], v198 offset:50176
	ds_read_b128 v[208:211], v198 offset:51200
	ds_read_b128 v[214:217], v198 offset:52224
	ds_read_b128 v[230:233], v198 offset:53248
	ds_read_b128 v[234:237], v198 offset:54272
	ds_read_b128 v[238:241], v198 offset:55296
	ds_read_b128 v[242:245], v198 offset:56320
	global_load_lds_dwordx4 v156, s[100:101]
	s_add_i32 m0, s76, 0x2000
	s_add_u32 s74, s74, 0x40080
	s_addc_u32 s75, s75, 0
	s_add_i32 s76, s83, s5
	global_load_lds_dwordx4 v168, s[100:101]
	s_mov_b32 m0, s76
	s_nop 0
	global_load_lds_dwordx4 v156, s[74:75]
	s_add_i32 m0, s76, 0x2000
	s_nop 0
	global_load_lds_dwordx4 v168, s[74:75]
	s_mov_b32 m0, s36
	s_nop 0
	global_load_lds_dwordx4 v152, s[72:73]
	s_mov_b32 m0, s42
	s_nop 0
	global_load_lds_dwordx4 v154, s[72:73]
	s_waitcnt vmcnt(8)
	s_waitcnt lgkmcnt(0)
	s_barrier
	s_setprio 1
	s_waitcnt lgkmcnt(0)
	v_mfma_f32_16x16x32_bf16 v[60:63], v[132:135], v[188:191], v[60:63]
	v_mfma_f32_16x16x32_bf16 v[60:63], v[136:139], v[200:203], v[60:63]
	v_mfma_f32_16x16x32_bf16 v[44:47], v[136:139], v[214:217], v[44:47]
	v_mfma_f32_16x16x32_bf16 v[44:47], v[132:135], v[208:211], v[44:47]
	v_mfma_f32_16x16x32_bf16 v[28:31], v[132:135], v[230:233], v[28:31]
	v_mfma_f32_16x16x32_bf16 v[28:31], v[136:139], v[234:237], v[28:31]
	v_mfma_f32_16x16x32_bf16 v[12:15], v[136:139], v[242:245], v[12:15]
	v_mfma_f32_16x16x32_bf16 v[12:15], v[132:135], v[238:241], v[12:15]
	v_mfma_f32_16x16x32_bf16 v[8:11], v[140:143], v[238:241], v[8:11]
	v_mfma_f32_16x16x32_bf16 v[8:11], v[144:147], v[242:245], v[8:11]
	v_mfma_f32_16x16x32_bf16 v[24:27], v[144:147], v[234:237], v[24:27]
	v_mfma_f32_16x16x32_bf16 v[24:27], v[140:143], v[230:233], v[24:27]
	v_mfma_f32_16x16x32_bf16 v[40:43], v[140:143], v[208:211], v[40:43]
	v_mfma_f32_16x16x32_bf16 v[40:43], v[144:147], v[214:217], v[40:43]
	v_mfma_f32_16x16x32_bf16 v[56:59], v[144:147], v[200:203], v[56:59]
	v_mfma_f32_16x16x32_bf16 v[56:59], v[140:143], v[188:191], v[56:59]
	s_setprio 0
	s_setprio 1
	v_mfma_f32_16x16x32_bf16 v[52:55], v[148:151], v[188:191], v[52:55]
	v_mfma_f32_16x16x32_bf16 v[52:55], v[176:179], v[200:203], v[52:55]
	v_mfma_f32_16x16x32_bf16 v[36:39], v[176:179], v[214:217], v[36:39]
	v_mfma_f32_16x16x32_bf16 v[36:39], v[148:151], v[208:211], v[36:39]
	v_mfma_f32_16x16x32_bf16 v[20:23], v[148:151], v[230:233], v[20:23]
	v_mfma_f32_16x16x32_bf16 v[20:23], v[176:179], v[234:237], v[20:23]
	v_mfma_f32_16x16x32_bf16 v[4:7], v[176:179], v[242:245], v[4:7]
	v_mfma_f32_16x16x32_bf16 v[4:7], v[148:151], v[238:241], v[4:7]
	v_mfma_f32_16x16x32_bf16 v[0:3], v[180:183], v[238:241], v[0:3]
	v_mfma_f32_16x16x32_bf16 v[0:3], v[184:187], v[242:245], v[0:3]
	v_mfma_f32_16x16x32_bf16 v[16:19], v[184:187], v[234:237], v[16:19]
	v_mfma_f32_16x16x32_bf16 v[16:19], v[180:183], v[230:233], v[16:19]
	v_mfma_f32_16x16x32_bf16 v[32:35], v[180:183], v[208:211], v[32:35]
	v_mfma_f32_16x16x32_bf16 v[32:35], v[184:187], v[214:217], v[32:35]
	v_mfma_f32_16x16x32_bf16 v[48:51], v[184:187], v[200:203], v[48:51]
	v_mfma_f32_16x16x32_bf16 v[48:51], v[180:183], v[188:191], v[48:51]
	s_setprio 0
	s_barrier
	s_add_i32 s81, s81, 2
	s_add_u32 s52, s52, 0x100
	s_addc_u32 s53, s53, 0
	s_cmp_gt_u32 s81, 13
	s_cbranch_scc0 .LBB0_299
	s_and_b64 vcc, exec, s[16:17]
	s_cbranch_vccz .LBB0_302
	s_barrier

; #define PG8_STAGE(bufoff, gbase, voff) do { _Pragma("unroll") for (int _i = 0; _i < 2; ++_i) \
;         __builtin_amdgcn_global_load_lds((const unsigned*)((const char*)(gbase) + (voff)[_i]), (LAS unsigned*)(lds + (bufoff) + ldsw + _i * 8192), 16, 0, 0); } while (0)
; #define PG8_LDA(dst, b, h) do { _Pragma("unroll") for (int m = 0; m < 4; ++m) _Pragma("unroll") for (int k = 0; k < 2; ++k) dst[m][k] = *(const LAS bf16x8*)(lds + PG8_SA(b, h) + aoff + m * 2048 + k * 1024); } while (0)
; #define PG8_LDB(dst, b, h) do { _Pragma("unroll") for (int n = 0; n < 2; ++n) _Pragma("unroll") for (int k = 0; k < 2; ++k) dst[n][k] = *(const LAS bf16x8*)(lds + PG8_SB(b, h) + boff + n * 2048 + k * 1024); } while (0)
; #define PG8_MMA(ai, bj, At, Bt) do { __builtin_amdgcn_s_setprio(1); _Pragma("unroll") for (int m = 0; m < 4; ++m) _Pragma("unroll") for (int n = 0; n < 2; ++n) _Pragma("unroll") for (int k = 0; k < 2; ++k) \
;         acc[ai][bj][m][n] = __builtin_amdgcn_mfma_f32_16x16x32_bf16(Bt[n][k], At[m][k], acc[ai][bj][m][n], 0, 0, 0); __builtin_amdgcn_s_setprio(0); } while (0)
; #define PG8_WAIT_V(n) asm volatile("s_waitcnt vmcnt(" #n ")" ::: "memory")
; #define PG8_WAIT_L(n) asm volatile("s_waitcnt lgkmcnt(" #n ")" ::: "memory")
; #define PG8_BAR __builtin_amdgcn_s_barrier()
; #define PG8_SCHED __builtin_amdgcn_sched_barrier(0)
;     ...
;         for (int t = 0; t < nt; t += 2) {
;             const bool last = (t == nt - 2);
;             const char* a1 = PG8_ATILE(cA, cA2, t + 1);
;             const char* a2 = last ? nA : PG8_ATILE(cA, cA2, t + 2); const char* b2 = last ? nB : cB + (size_t)(t + 2) * 128;
;             const char* a3 = last ? nA + kA1 : PG8_ATILE(cA, cA2, t + 3); const char* b3 = b2 + kB1;
;             if constexpr (SP2) {
;             PG8_LDB(B0, 0, 0); PG8_LDB(B1, 0, 1); PG8_SCHED; PG8_LDA(At, 0, 0); PG8_STAGE(PG8_SA(1, 1), a1 + hA, voffA);
;             PG8_WAIT_V(8); PG8_WAIT_L(0); PG8_BAR; PG8_MMA(0, 0, At, B0); PG8_MMA(0, 1, At, B1); PG8_BAR; PG8_SCHED;
;             PG8_LDA(At, 0, 1); PG8_STAGE(PG8_SB(0, 0), b2, voffB); PG8_STAGE(PG8_SB(0, 1), b2 + hB, voffB); PG8_STAGE(PG8_SA(0, 0), a2, voffA);
;             PG8_WAIT_V(8); PG8_WAIT_L(0); PG8_BAR; PG8_MMA(1, 0, At, B0); PG8_MMA(1, 1, At, B1); PG8_BAR; PG8_SCHED;
.LBB0_364:
	s_add_i32 s6, s74, 2
	s_add_u32 s26, s92, vcc_lo
	s_addc_u32 s27, s93, vcc_hi
	s_add_u32 s98, s26, 0x80
	s_addc_u32 s99, s27, 0
	s_add_u32 s76, s26, 0x100
	s_addc_u32 s77, s27, 0
	s_add_u32 s9, s94, vcc_lo
	s_addc_u32 s8, s95, vcc_hi
	s_add_u32 s26, s26, 0x180
	s_addc_u32 s27, s27, 0
	s_add_i32 s50, 0, 0x10000
	s_add_i32 s51, 0, 0x14000
	v_add_u32_e32 v154, s50, v168
	ds_read_b128 v[132:135], v154
	ds_read_b128 v[146:149], v154 offset:1024
	ds_read_b128 v[150:153], v154 offset:2048
	ds_read_b128 v[172:175], v154 offset:3072
	v_add_u32_e32 v154, s51, v168
	ds_read_b128 v[176:179], v154
	ds_read_b128 v[180:183], v154 offset:1024
	ds_read_b128 v[184:187], v154 offset:2048
	ds_read_b128 v[188:191], v154 offset:3072
	s_cmp_eq_u32 s5, s74
	s_cselect_b32 s74, s97, s26
	s_cselect_b32 s75, s79, s27
	s_cselect_b32 s27, s45, s8
	s_cselect_b32 s26, s96, s9
	s_cselect_b32 s77, s43, s77
	s_cselect_b32 s76, s82, s76
	s_add_i32 m0, s83, 0xc000
	ds_read_b128 v[192:195], v170
	ds_read_b128 v[196:199], v170 offset:1024
	ds_read_b128 v[200:203], v170 offset:2048
	ds_read_b128 v[208:211], v170 offset:3072
	ds_read_b128 v[214:217], v170 offset:4096
	ds_read_b128 v[230:233], v170 offset:5120
	ds_read_b128 v[234:237], v170 offset:6144
	ds_read_b128 v[238:241], v170 offset:7168
	global_load_lds_dwordx4 v144, s[98:99]
	s_add_i32 m0, s83, 0xe000
	s_nop 0
	global_load_lds_dwordx4 v142, s[98:99]
	s_waitcnt vmcnt(8)
	s_waitcnt lgkmcnt(0)
	s_barrier
	s_setprio 1
	s_waitcnt lgkmcnt(0)
	v_mfma_f32_16x16x32_bf16 v[124:127], v[132:135], v[192:195], v[124:127]
	v_mfma_f32_16x16x32_bf16 v[124:127], v[146:149], v[196:199], v[124:127]
	v_mfma_f32_16x16x32_bf16 v[108:111], v[146:149], v[208:211], v[108:111]
	v_mfma_f32_16x16x32_bf16 v[108:111], v[132:135], v[200:203], v[108:111]
	v_mfma_f32_16x16x32_bf16 v[92:95], v[132:135], v[214:217], v[92:95]
	v_mfma_f32_16x16x32_bf16 v[92:95], v[146:149], v[230:233], v[92:95]
	v_mfma_f32_16x16x32_bf16 v[76:79], v[146:149], v[238:241], v[76:79]
	v_mfma_f32_16x16x32_bf16 v[76:79], v[132:135], v[234:237], v[76:79]
	v_mfma_f32_16x16x32_bf16 v[72:75], v[150:153], v[234:237], v[72:75]
	v_mfma_f32_16x16x32_bf16 v[72:75], v[172:175], v[238:241], v[72:75]
	v_mfma_f32_16x16x32_bf16 v[88:91], v[172:175], v[230:233], v[88:91]
	v_mfma_f32_16x16x32_bf16 v[88:91], v[150:153], v[214:217], v[88:91]
	v_mfma_f32_16x16x32_bf16 v[104:107], v[150:153], v[200:203], v[104:107]
	v_mfma_f32_16x16x32_bf16 v[104:107], v[172:175], v[208:211], v[104:107]
	v_mfma_f32_16x16x32_bf16 v[120:123], v[172:175], v[196:199], v[120:123]
	v_mfma_f32_16x16x32_bf16 v[120:123], v[150:153], v[192:195], v[120:123]
	s_setprio 0
	s_setprio 1
	v_mfma_f32_16x16x32_bf16 v[116:119], v[176:179], v[192:195], v[116:119]
	v_mfma_f32_16x16x32_bf16 v[116:119], v[180:183], v[196:199], v[116:119]
	v_mfma_f32_16x16x32_bf16 v[100:103], v[180:183], v[208:211], v[100:103]
	v_mfma_f32_16x16x32_bf16 v[100:103], v[176:179], v[200:203], v[100:103]
	v_mfma_f32_16x16x32_bf16 v[84:87], v[176:179], v[214:217], v[84:87]
	v_mfma_f32_16x16x32_bf16 v[84:87], v[180:183], v[230:233], v[84:87]
	v_mfma_f32_16x16x32_bf16 v[68:71], v[180:183], v[238:241], v[68:71]
	v_mfma_f32_16x16x32_bf16 v[68:71], v[176:179], v[234:237], v[68:71]
	v_mfma_f32_16x16x32_bf16 v[64:67], v[184:187], v[234:237], v[64:67]
	v_mfma_f32_16x16x32_bf16 v[64:67], v[188:191], v[238:241], v[64:67]
	v_mfma_f32_16x16x32_bf16 v[80:83], v[188:191], v[230:233], v[80:83]
	v_mfma_f32_16x16x32_bf16 v[80:83], v[184:187], v[214:217], v[80:83]
	v_mfma_f32_16x16x32_bf16 v[96:99], v[184:187], v[200:203], v[96:99]
	v_mfma_f32_16x16x32_bf16 v[96:99], v[188:191], v[208:211], v[96:99]
	v_mfma_f32_16x16x32_bf16 v[112:115], v[188:191], v[196:199], v[112:115]
	v_mfma_f32_16x16x32_bf16 v[112:115], v[184:187], v[192:195], v[112:115]
	s_setprio 0
	s_barrier
	s_add_i32 s8, s50, s81
	s_mov_b32 m0, s8
	ds_read_b128 v[192:195], v170 offset:16384
	ds_read_b128 v[196:199], v170 offset:17408
	ds_read_b128 v[200:203], v170 offset:18432
	ds_read_b128 v[208:211], v170 offset:19456
	ds_read_b128 v[214:217], v170 offset:20480
	ds_read_b128 v[230:233], v170 offset:21504
	ds_read_b128 v[234:237], v170 offset:22528
	ds_read_b128 v[238:241], v170 offset:23552
	global_load_lds_dwordx4 v156, s[26:27]
	s_add_i32 m0, s8, 0x2000
	s_mov_b64 s[100:101], s[26:27]
	s_add_u32 s26, s26, s16
	s_addc_u32 s27, s27, 0
	s_add_i32 s8, s51, s81
	global_load_lds_dwordx4 v140, s[100:101]
	s_mov_b32 m0, s8
	s_nop 0
	global_load_lds_dwordx4 v156, s[26:27]
	s_add_i32 m0, s8, 0x2000
	s_nop 0
	global_load_lds_dwordx4 v140, s[26:27]
	s_mov_b32 m0, s83
	s_nop 0
	global_load_lds_dwordx4 v136, s[76:77]
	s_mov_b32 m0, s2
	s_nop 0
	global_load_lds_dwordx4 v138, s[76:77]
	s_waitcnt vmcnt(8)
	s_waitcnt lgkmcnt(0)
	s_barrier
; #define PG8_STAGE(bufoff, gbase, voff) do { _Pragma("unroll") for (int _i = 0; _i < 2; ++_i) \
;         __builtin_amdgcn_global_load_lds((const unsigned*)((const char*)(gbase) + (voff)[_i]), (LAS unsigned*)(lds + (bufoff) + ldsw + _i * 8192), 16, 0, 0); } while (0)
; #define PG8_LDA(dst, b, h) do { _Pragma("unroll") for (int m = 0; m < 4; ++m) _Pragma("unroll") for (int k = 0; k < 2; ++k) dst[m][k] = *(const LAS bf16x8*)(lds + PG8_SA(b, h) + aoff + m * 2048 + k * 1024); } while (0)
; #define PG8_LDB(dst, b, h) do { _Pragma("unroll") for (int n = 0; n < 2; ++n) _Pragma("unroll") for (int k = 0; k < 2; ++k) dst[n][k] = *(const LAS bf16x8*)(lds + PG8_SB(b, h) + boff + n * 2048 + k * 1024); } while (0)
; #define PG8_MMA(ai, bj, At, Bt) do { __builtin_amdgcn_s_setprio(1); _Pragma("unroll") for (int m = 0; m < 4; ++m) _Pragma("unroll") for (int n = 0; n < 2; ++n) _Pragma("unroll") for (int k = 0; k < 2; ++k) \
;         acc[ai][bj][m][n] = __builtin_amdgcn_mfma_f32_16x16x32_bf16(Bt[n][k], At[m][k], acc[ai][bj][m][n], 0, 0, 0); __builtin_amdgcn_s_setprio(0); } while (0)
; #define PG8_WAIT_V(n) asm volatile("s_waitcnt vmcnt(" #n ")" ::: "memory")
; #define PG8_WAIT_L(n) asm volatile("s_waitcnt lgkmcnt(" #n ")" ::: "memory")
; #define PG8_BAR __builtin_amdgcn_s_barrier()
; #define PG8_SCHED __builtin_amdgcn_sched_barrier(0)
;     ...
;             PG8_WAIT_V(8); PG8_WAIT_L(0); PG8_BAR; PG8_MMA(1, 0, At, B0); PG8_MMA(1, 1, At, B1); PG8_BAR; PG8_SCHED;
;             PG8_LDB(B0, 1, 0); PG8_LDB(B1, 1, 1); PG8_SCHED; PG8_LDA(At, 1, 0); PG8_STAGE(PG8_SA(0, 1), a2 + hA, voffA);
;             PG8_WAIT_V(8); PG8_WAIT_L(0); PG8_BAR; PG8_MMA(0, 0, At, B0); PG8_MMA(0, 1, At, B1); PG8_BAR; PG8_SCHED;
	s_setprio 1
	s_waitcnt lgkmcnt(0)
	v_mfma_f32_16x16x32_bf16 v[60:63], v[132:135], v[192:195], v[60:63]
	v_mfma_f32_16x16x32_bf16 v[60:63], v[146:149], v[196:199], v[60:63]
	v_mfma_f32_16x16x32_bf16 v[44:47], v[146:149], v[208:211], v[44:47]
	v_mfma_f32_16x16x32_bf16 v[44:47], v[132:135], v[200:203], v[44:47]
	v_mfma_f32_16x16x32_bf16 v[28:31], v[132:135], v[214:217], v[28:31]
	v_mfma_f32_16x16x32_bf16 v[28:31], v[146:149], v[230:233], v[28:31]
	v_mfma_f32_16x16x32_bf16 v[12:15], v[146:149], v[238:241], v[12:15]
	v_mfma_f32_16x16x32_bf16 v[12:15], v[132:135], v[234:237], v[12:15]
	v_mfma_f32_16x16x32_bf16 v[8:11], v[150:153], v[234:237], v[8:11]
	v_mfma_f32_16x16x32_bf16 v[8:11], v[172:175], v[238:241], v[8:11]
	v_mfma_f32_16x16x32_bf16 v[24:27], v[172:175], v[230:233], v[24:27]
	v_mfma_f32_16x16x32_bf16 v[24:27], v[150:153], v[214:217], v[24:27]
	v_mfma_f32_16x16x32_bf16 v[40:43], v[150:153], v[200:203], v[40:43]
	v_mfma_f32_16x16x32_bf16 v[40:43], v[172:175], v[208:211], v[40:43]
	v_mfma_f32_16x16x32_bf16 v[56:59], v[172:175], v[196:199], v[56:59]
	v_mfma_f32_16x16x32_bf16 v[56:59], v[150:153], v[192:195], v[56:59]
	s_setprio 0
	s_setprio 1
	v_mfma_f32_16x16x32_bf16 v[52:55], v[176:179], v[192:195], v[52:55]
	v_mfma_f32_16x16x32_bf16 v[52:55], v[180:183], v[196:199], v[52:55]
	v_mfma_f32_16x16x32_bf16 v[36:39], v[180:183], v[208:211], v[36:39]
	v_mfma_f32_16x16x32_bf16 v[36:39], v[176:179], v[200:203], v[36:39]
	v_mfma_f32_16x16x32_bf16 v[20:23], v[176:179], v[214:217], v[20:23]
	v_mfma_f32_16x16x32_bf16 v[20:23], v[180:183], v[230:233], v[20:23]
	v_mfma_f32_16x16x32_bf16 v[4:7], v[180:183], v[238:241], v[4:7]
	v_mfma_f32_16x16x32_bf16 v[4:7], v[176:179], v[234:237], v[4:7]
	v_mfma_f32_16x16x32_bf16 v[0:3], v[184:187], v[234:237], v[0:3]
	v_mfma_f32_16x16x32_bf16 v[0:3], v[188:191], v[238:241], v[0:3]
	v_mfma_f32_16x16x32_bf16 v[16:19], v[188:191], v[230:233], v[16:19]
	v_mfma_f32_16x16x32_bf16 v[16:19], v[184:187], v[214:217], v[16:19]
	v_mfma_f32_16x16x32_bf16 v[32:35], v[184:187], v[200:203], v[32:35]
	v_mfma_f32_16x16x32_bf16 v[32:35], v[188:191], v[208:211], v[32:35]
	v_mfma_f32_16x16x32_bf16 v[48:51], v[188:191], v[196:199], v[48:51]
	v_mfma_f32_16x16x32_bf16 v[48:51], v[184:187], v[192:195], v[48:51]
	s_setprio 0
	s_barrier
	s_add_i32 s8, 0, 0x18000
	v_add_u32_e32 v171, s8, v168
	s_add_i32 s9, 0, 0x1c000
	ds_read_b128 v[132:135], v171
	ds_read_b128 v[146:149], v171 offset:1024
	ds_read_b128 v[150:153], v171 offset:2048
	ds_read_b128 v[172:175], v171 offset:3072
	v_add_u32_e32 v171, s9, v168
	ds_read_b128 v[176:179], v171
	ds_read_b128 v[180:183], v171 offset:1024
	ds_read_b128 v[184:187], v171 offset:2048
	ds_read_b128 v[188:191], v171 offset:3072
	s_add_u32 s26, s76, s16
	s_addc_u32 s27, s77, 0
	s_mov_b32 m0, s3
	ds_read_b128 v[192:195], v170 offset:32768
	ds_read_b128 v[196:199], v170 offset:33792
	ds_read_b128 v[200:203], v170 offset:34816
	ds_read_b128 v[208:211], v170 offset:35840
	ds_read_b128 v[214:217], v170 offset:36864
	ds_read_b128 v[230:233], v170 offset:37888
	ds_read_b128 v[234:237], v170 offset:38912
	ds_read_b128 v[238:241], v170 offset:39936
	global_load_lds_dwordx4 v136, s[26:27]
	s_mov_b32 m0, s0
	s_nop 0
	global_load_lds_dwordx4 v138, s[26:27]
	s_waitcnt vmcnt(8)
	s_waitcnt lgkmcnt(0)
	s_barrier
	s_setprio 1
	s_waitcnt lgkmcnt(0)
	v_mfma_f32_16x16x32_bf16 v[124:127], v[132:135], v[192:195], v[124:127]
	v_mfma_f32_16x16x32_bf16 v[124:127], v[146:149], v[196:199], v[124:127]
	v_mfma_f32_16x16x32_bf16 v[108:111], v[146:149], v[208:211], v[108:111]
	v_mfma_f32_16x16x32_bf16 v[108:111], v[132:135], v[200:203], v[108:111]
	v_mfma_f32_16x16x32_bf16 v[92:95], v[132:135], v[214:217], v[92:95]
	v_mfma_f32_16x16x32_bf16 v[92:95], v[146:149], v[230:233], v[92:95]
	v_mfma_f32_16x16x32_bf16 v[76:79], v[146:149], v[238:241], v[76:79]
	v_mfma_f32_16x16x32_bf16 v[76:79], v[132:135], v[234:237], v[76:79]
	v_mfma_f32_16x16x32_bf16 v[72:75], v[150:153], v[234:237], v[72:75]
	v_mfma_f32_16x16x32_bf16 v[72:75], v[172:175], v[238:241], v[72:75]
	v_mfma_f32_16x16x32_bf16 v[88:91], v[172:175], v[230:233], v[88:91]
	v_mfma_f32_16x16x32_bf16 v[88:91], v[150:153], v[214:217], v[88:91]
	v_mfma_f32_16x16x32_bf16 v[104:107], v[150:153], v[200:203], v[104:107]
	v_mfma_f32_16x16x32_bf16 v[104:107], v[172:175], v[208:211], v[104:107]
	v_mfma_f32_16x16x32_bf16 v[120:123], v[172:175], v[196:199], v[120:123]
	v_mfma_f32_16x16x32_bf16 v[120:123], v[150:153], v[192:195], v[120:123]
	s_setprio 0
	s_setprio 1
	v_mfma_f32_16x16x32_bf16 v[116:119], v[176:179], v[192:195], v[116:119]
	v_mfma_f32_16x16x32_bf16 v[116:119], v[180:183], v[196:199], v[116:119]
	v_mfma_f32_16x16x32_bf16 v[100:103], v[180:183], v[208:211], v[100:103]
	v_mfma_f32_16x16x32_bf16 v[100:103], v[176:179], v[200:203], v[100:103]
	v_mfma_f32_16x16x32_bf16 v[84:87], v[176:179], v[214:217], v[84:87]
	v_mfma_f32_16x16x32_bf16 v[84:87], v[180:183], v[230:233], v[84:87]
	v_mfma_f32_16x16x32_bf16 v[68:71], v[180:183], v[238:241], v[68:71]
	v_mfma_f32_16x16x32_bf16 v[68:71], v[176:179], v[234:237], v[68:71]
	v_mfma_f32_16x16x32_bf16 v[64:67], v[184:187], v[234:237], v[64:67]
	v_mfma_f32_16x16x32_bf16 v[64:67], v[188:191], v[238:241], v[64:67]
	v_mfma_f32_16x16x32_bf16 v[80:83], v[188:191], v[230:233], v[80:83]
	v_mfma_f32_16x16x32_bf16 v[80:83], v[184:187], v[214:217], v[80:83]
	v_mfma_f32_16x16x32_bf16 v[96:99], v[184:187], v[200:203], v[96:99]
	v_mfma_f32_16x16x32_bf16 v[96:99], v[188:191], v[208:211], v[96:99]
	v_mfma_f32_16x16x32_bf16 v[112:115], v[188:191], v[196:199], v[112:115]
	v_mfma_f32_16x16x32_bf16 v[112:115], v[184:187], v[192:195], v[112:115]
	s_setprio 0
	s_barrier
; #define PG8_STAGE(bufoff, gbase, voff) do { _Pragma("unroll") for (int _i = 0; _i < 2; ++_i) \
;         __builtin_amdgcn_global_load_lds((const unsigned*)((const char*)(gbase) + (voff)[_i]), (LAS unsigned*)(lds + (bufoff) + ldsw + _i * 8192), 16, 0, 0); } while (0)
; #define PG8_LDA(dst, b, h) do { _Pragma("unroll") for (int m = 0; m < 4; ++m) _Pragma("unroll") for (int k = 0; k < 2; ++k) dst[m][k] = *(const LAS bf16x8*)(lds + PG8_SA(b, h) + aoff + m * 2048 + k * 1024); } while (0)
; #define PG8_MMA(ai, bj, At, Bt) do { __builtin_amdgcn_s_setprio(1); _Pragma("unroll") for (int m = 0; m < 4; ++m) _Pragma("unroll") for (int n = 0; n < 2; ++n) _Pragma("unroll") for (int k = 0; k < 2; ++k) \
;         acc[ai][bj][m][n] = __builtin_amdgcn_mfma_f32_16x16x32_bf16(Bt[n][k], At[m][k], acc[ai][bj][m][n], 0, 0, 0); __builtin_amdgcn_s_setprio(0); } while (0)
; #define PG8_WAIT_V(n) asm volatile("s_waitcnt vmcnt(" #n ")" ::: "memory")
; #define PG8_WAIT_L(n) asm volatile("s_waitcnt lgkmcnt(" #n ")" ::: "memory")
; #define PG8_BAR __builtin_amdgcn_s_barrier()
; #define PG8_SCHED __builtin_amdgcn_sched_barrier(0)
;     ...
;             PG8_LDA(At, 1, 1); PG8_STAGE(PG8_SB(1, 0), b3, voffB); PG8_STAGE(PG8_SB(1, 1), b3 + hB, voffB); PG8_STAGE(PG8_SA(1, 0), a3, voffA);
;             PG8_WAIT_V(8); PG8_WAIT_L(0); PG8_BAR; PG8_MMA(1, 0, At, B0); PG8_MMA(1, 1, At, B1); PG8_BAR; PG8_SCHED;
;     ...
;         if constexpr (ALIGN_EPI) { if (wr == 0) PG8_BAR; }
	s_add_i32 s8, s8, s81
	s_add_u32 s98, s100, s38
	s_addc_u32 s99, s101, s39
	s_add_u32 s100, s98, s16
	s_addc_u32 s101, s99, 0
	s_mov_b32 m0, s8
	ds_read_b128 v[192:195], v170 offset:49152
	ds_read_b128 v[196:199], v170 offset:50176
	ds_read_b128 v[200:203], v170 offset:51200
	ds_read_b128 v[208:211], v170 offset:52224
	ds_read_b128 v[214:217], v170 offset:53248
	ds_read_b128 v[230:233], v170 offset:54272
	ds_read_b128 v[234:237], v170 offset:55296
	ds_read_b128 v[238:241], v170 offset:56320
	global_load_lds_dwordx4 v156, s[98:99]
	s_add_i32 m0, s8, 0x2000
	s_add_i32 s8, s9, s81
	global_load_lds_dwordx4 v140, s[98:99]
	s_mov_b32 m0, s8
	s_nop 0
	global_load_lds_dwordx4 v156, s[100:101]
	s_add_i32 m0, s8, 0x2000
	s_nop 0
	global_load_lds_dwordx4 v140, s[100:101]
	s_mov_b32 m0, s1
	s_nop 0
	global_load_lds_dwordx4 v136, s[74:75]
	s_mov_b32 m0, s54
	s_nop 0
	global_load_lds_dwordx4 v138, s[74:75]
	s_waitcnt vmcnt(8)
	s_waitcnt lgkmcnt(0)
	s_barrier
	s_setprio 1
	s_waitcnt lgkmcnt(0)
	v_mfma_f32_16x16x32_bf16 v[60:63], v[132:135], v[192:195], v[60:63]
	v_mfma_f32_16x16x32_bf16 v[60:63], v[146:149], v[196:199], v[60:63]
	v_mfma_f32_16x16x32_bf16 v[44:47], v[146:149], v[208:211], v[44:47]
	v_mfma_f32_16x16x32_bf16 v[44:47], v[132:135], v[200:203], v[44:47]
	v_mfma_f32_16x16x32_bf16 v[28:31], v[132:135], v[214:217], v[28:31]
	v_mfma_f32_16x16x32_bf16 v[28:31], v[146:149], v[230:233], v[28:31]
	v_mfma_f32_16x16x32_bf16 v[12:15], v[146:149], v[238:241], v[12:15]
	v_mfma_f32_16x16x32_bf16 v[12:15], v[132:135], v[234:237], v[12:15]
	v_mfma_f32_16x16x32_bf16 v[8:11], v[150:153], v[234:237], v[8:11]
	v_mfma_f32_16x16x32_bf16 v[8:11], v[172:175], v[238:241], v[8:11]
	v_mfma_f32_16x16x32_bf16 v[24:27], v[172:175], v[230:233], v[24:27]
	v_mfma_f32_16x16x32_bf16 v[24:27], v[150:153], v[214:217], v[24:27]
	v_mfma_f32_16x16x32_bf16 v[40:43], v[150:153], v[200:203], v[40:43]
	v_mfma_f32_16x16x32_bf16 v[40:43], v[172:175], v[208:211], v[40:43]
	v_mfma_f32_16x16x32_bf16 v[56:59], v[172:175], v[196:199], v[56:59]
	v_mfma_f32_16x16x32_bf16 v[56:59], v[150:153], v[192:195], v[56:59]
	s_setprio 0
	s_setprio 1
	v_mfma_f32_16x16x32_bf16 v[52:55], v[176:179], v[192:195], v[52:55]
	v_mfma_f32_16x16x32_bf16 v[52:55], v[180:183], v[196:199], v[52:55]
	v_mfma_f32_16x16x32_bf16 v[36:39], v[180:183], v[208:211], v[36:39]
	v_mfma_f32_16x16x32_bf16 v[36:39], v[176:179], v[200:203], v[36:39]
	v_mfma_f32_16x16x32_bf16 v[20:23], v[176:179], v[214:217], v[20:23]
	v_mfma_f32_16x16x32_bf16 v[20:23], v[180:183], v[230:233], v[20:23]
	v_mfma_f32_16x16x32_bf16 v[4:7], v[180:183], v[238:241], v[4:7]
	v_mfma_f32_16x16x32_bf16 v[4:7], v[176:179], v[234:237], v[4:7]
	v_mfma_f32_16x16x32_bf16 v[0:3], v[184:187], v[234:237], v[0:3]
	v_mfma_f32_16x16x32_bf16 v[0:3], v[188:191], v[238:241], v[0:3]
	v_mfma_f32_16x16x32_bf16 v[16:19], v[188:191], v[230:233], v[16:19]
	v_mfma_f32_16x16x32_bf16 v[16:19], v[184:187], v[214:217], v[16:19]
	v_mfma_f32_16x16x32_bf16 v[32:35], v[184:187], v[200:203], v[32:35]
	v_mfma_f32_16x16x32_bf16 v[32:35], v[188:191], v[208:211], v[32:35]
	v_mfma_f32_16x16x32_bf16 v[48:51], v[188:191], v[196:199], v[48:51]
	v_mfma_f32_16x16x32_bf16 v[48:51], v[184:187], v[192:195], v[48:51]
	s_setprio 0
	s_barrier
	s_add_u32 vcc_lo, vcc_lo, 0x100
	s_addc_u32 vcc_hi, vcc_hi, 0
	s_cmp_ge_u32 s6, s4
	s_mov_b32 s74, s6
	s_cbranch_scc0 .LBB0_364
	s_and_b64 vcc, exec, s[30:31]
	s_cbranch_vccz .LBB0_367
	s_barrier

; #define PG8_STAGE(bufoff, gbase, voff) do { _Pragma("unroll") for (int _i = 0; _i < 2; ++_i) \
;         __builtin_amdgcn_global_load_lds((const unsigned*)((const char*)(gbase) + (voff)[_i]), (LAS unsigned*)(lds + (bufoff) + ldsw + _i * 8192), 16, 0, 0); } while (0)
; #define PG8_LDA(dst, b, h) do { _Pragma("unroll") for (int m = 0; m < 4; ++m) _Pragma("unroll") for (int k = 0; k < 2; ++k) dst[m][k] = *(const LAS bf16x8*)(lds + PG8_SA(b, h) + aoff + m * 2048 + k * 1024); } while (0)
; #define PG8_LDB(dst, b, h) do { _Pragma("unroll") for (int n = 0; n < 2; ++n) _Pragma("unroll") for (int k = 0; k < 2; ++k) dst[n][k] = *(const LAS bf16x8*)(lds + PG8_SB(b, h) + boff + n * 2048 + k * 1024); } while (0)
; #define PG8_MMA(ai, bj, At, Bt) do { __builtin_amdgcn_s_setprio(1); _Pragma("unroll") for (int m = 0; m < 4; ++m) _Pragma("unroll") for (int n = 0; n < 2; ++n) _Pragma("unroll") for (int k = 0; k < 2; ++k) \
;         acc[ai][bj][m][n] = __builtin_amdgcn_mfma_f32_16x16x32_bf16(Bt[n][k], At[m][k], acc[ai][bj][m][n], 0, 0, 0); __builtin_amdgcn_s_setprio(0); } while (0)
; #define PG8_WAIT_V(n) asm volatile("s_waitcnt vmcnt(" #n ")" ::: "memory")
; #define PG8_WAIT_L(n) asm volatile("s_waitcnt lgkmcnt(" #n ")" ::: "memory")
; #define PG8_BAR __builtin_amdgcn_s_barrier()
; #define PG8_SCHED __builtin_amdgcn_sched_barrier(0)
;     ...
;         for (int t = 0; t < nt; t += 2) {
;             const bool last = (t == nt - 2);
;             const char* a1 = PG8_ATILE(cA, cA2, t + 1);
;             const char* a2 = last ? nA : PG8_ATILE(cA, cA2, t + 2); const char* b2 = last ? nB : cB + (size_t)(t + 2) * 128;
;             const char* a3 = last ? nA + kA1 : PG8_ATILE(cA, cA2, t + 3); const char* b3 = b2 + kB1;
;             if constexpr (SP2) {
;             PG8_LDB(B0, 0, 0); PG8_LDB(B1, 0, 1); PG8_SCHED; PG8_LDA(At, 0, 0); PG8_STAGE(PG8_SA(1, 1), a1 + hA, voffA);
;             PG8_WAIT_V(8); PG8_WAIT_L(0); PG8_BAR; PG8_MMA(0, 0, At, B0); PG8_MMA(0, 1, At, B1); PG8_BAR; PG8_SCHED;
;             PG8_LDA(At, 0, 1); PG8_STAGE(PG8_SB(0, 0), b2, voffB); PG8_STAGE(PG8_SB(0, 1), b2 + hB, voffB); PG8_STAGE(PG8_SA(0, 0), a2, voffA);
;             PG8_WAIT_V(8); PG8_WAIT_L(0); PG8_BAR; PG8_MMA(1, 0, At, B0); PG8_MMA(1, 1, At, B1); PG8_BAR; PG8_SCHED;
.LBB0_406:
	s_add_u32 s42, s30, s34
	s_addc_u32 s43, s31, s35
	s_add_u32 s48, s42, 0x100
	s_addc_u32 s49, s43, 0
	s_add_u32 s44, s74, s34
	s_addc_u32 s45, s75, s35
	s_add_u32 s42, s42, 0x180
	s_addc_u32 s43, s43, 0
	s_add_i32 s77, 0, 0x10000
	s_add_i32 s80, 0, 0x14000
	v_add_u32_e32 v144, s77, v179
	v_add_u32_e32 v178, s80, v179
	ds_read_b128 v[132:135], v144
	ds_read_b128 v[136:139], v144 offset:1024
	ds_read_b128 v[140:143], v144 offset:2048
	ds_read_b128 v[144:147], v144 offset:3072
	ds_read_b128 v[148:151], v178
	ds_read_b128 v[186:189], v178 offset:1024
	ds_read_b128 v[190:193], v178 offset:2048
	ds_read_b128 v[194:197], v178 offset:3072
	s_cmpk_eq_i32 s34, 0x700
	s_cselect_b32 s43, s73, s43
	s_cselect_b32 s42, s72, s42
	s_cselect_b32 s45, s17, s45
	s_cselect_b32 s44, s55, s44
	s_cselect_b32 s49, s3, s49
	s_cselect_b32 s48, s25, s48
	v_lshl_add_u64 v[182:183], v[128:129], 0, s[34:35]
	s_add_i32 m0, s6, 0xc000
	ds_read_b128 v[208:211], v181
	ds_read_b128 v[230:233], v181 offset:1024
	ds_read_b128 v[234:237], v181 offset:2048
	ds_read_b128 v[238:241], v181 offset:3072
	ds_read_b128 v[242:245], v181 offset:4096
	ds_read_b128 v[246:249], v181 offset:5120
	ds_read_b128 v[214:217], v181 offset:6144
	ds_read_b128 v[198:201], v181 offset:7168
	global_load_lds_dwordx4 v[182:183], off
	v_lshl_add_u64 v[182:183], v[130:131], 0, s[34:35]
	s_add_i32 m0, s6, 0xe000
	s_nop 0
	global_load_lds_dwordx4 v[182:183], off
	s_waitcnt vmcnt(8)
	s_waitcnt lgkmcnt(0)
	s_barrier
	s_setprio 1
	s_waitcnt lgkmcnt(0)
	v_mfma_f32_16x16x32_bf16 v[124:127], v[132:135], v[208:211], v[124:127]
	v_mfma_f32_16x16x32_bf16 v[124:127], v[136:139], v[230:233], v[124:127]
	v_mfma_f32_16x16x32_bf16 v[108:111], v[136:139], v[238:241], v[108:111]
	v_mfma_f32_16x16x32_bf16 v[108:111], v[132:135], v[234:237], v[108:111]
	v_mfma_f32_16x16x32_bf16 v[92:95], v[132:135], v[242:245], v[92:95]
	v_mfma_f32_16x16x32_bf16 v[92:95], v[136:139], v[246:249], v[92:95]
	v_mfma_f32_16x16x32_bf16 v[76:79], v[136:139], v[198:201], v[76:79]
	v_mfma_f32_16x16x32_bf16 v[76:79], v[132:135], v[214:217], v[76:79]
	v_mfma_f32_16x16x32_bf16 v[72:75], v[140:143], v[214:217], v[72:75]
	v_mfma_f32_16x16x32_bf16 v[72:75], v[144:147], v[198:201], v[72:75]
	v_mfma_f32_16x16x32_bf16 v[88:91], v[144:147], v[246:249], v[88:91]
	v_mfma_f32_16x16x32_bf16 v[88:91], v[140:143], v[242:245], v[88:91]
	v_mfma_f32_16x16x32_bf16 v[104:107], v[140:143], v[234:237], v[104:107]
	v_mfma_f32_16x16x32_bf16 v[104:107], v[144:147], v[238:241], v[104:107]
	v_mfma_f32_16x16x32_bf16 v[120:123], v[144:147], v[230:233], v[120:123]
	v_mfma_f32_16x16x32_bf16 v[120:123], v[140:143], v[208:211], v[120:123]
	s_setprio 0
	s_setprio 1
	v_mfma_f32_16x16x32_bf16 v[116:119], v[148:151], v[208:211], v[116:119]
	v_mfma_f32_16x16x32_bf16 v[116:119], v[186:189], v[230:233], v[116:119]
	v_mfma_f32_16x16x32_bf16 v[100:103], v[186:189], v[238:241], v[100:103]
	v_mfma_f32_16x16x32_bf16 v[100:103], v[148:151], v[234:237], v[100:103]
	v_mfma_f32_16x16x32_bf16 v[84:87], v[148:151], v[242:245], v[84:87]
	v_mfma_f32_16x16x32_bf16 v[84:87], v[186:189], v[246:249], v[84:87]
	v_mfma_f32_16x16x32_bf16 v[68:71], v[186:189], v[198:201], v[68:71]
	v_mfma_f32_16x16x32_bf16 v[68:71], v[148:151], v[214:217], v[68:71]
	v_mfma_f32_16x16x32_bf16 v[64:67], v[190:193], v[214:217], v[64:67]
	v_mfma_f32_16x16x32_bf16 v[64:67], v[194:197], v[198:201], v[64:67]
	v_mfma_f32_16x16x32_bf16 v[80:83], v[194:197], v[246:249], v[80:83]
	v_mfma_f32_16x16x32_bf16 v[80:83], v[190:193], v[242:245], v[80:83]
	v_mfma_f32_16x16x32_bf16 v[96:99], v[190:193], v[234:237], v[96:99]
	v_mfma_f32_16x16x32_bf16 v[96:99], v[194:197], v[238:241], v[96:99]
	v_mfma_f32_16x16x32_bf16 v[112:115], v[194:197], v[230:233], v[112:115]
	v_mfma_f32_16x16x32_bf16 v[112:115], v[190:193], v[208:211], v[112:115]
	s_setprio 0
	s_barrier
	s_add_i32 s77, s77, s5
	v_lshl_add_u64 v[182:183], s[44:45], 0, v[156:157]
	s_mov_b32 m0, s77
	ds_read_b128 v[198:201], v181 offset:16384
	ds_read_b128 v[208:211], v181 offset:17408
	ds_read_b128 v[214:217], v181 offset:18432
	ds_read_b128 v[230:233], v181 offset:19456
	ds_read_b128 v[234:237], v181 offset:20480
	ds_read_b128 v[238:241], v181 offset:21504
	ds_read_b128 v[242:245], v181 offset:22528
	ds_read_b128 v[246:249], v181 offset:23552
	global_load_lds_dwordx4 v[182:183], off
	s_add_i32 m0, s77, 0x2000
	s_add_u32 s78, s44, 0x40000
	v_lshl_add_u64 v[202:203], s[44:45], 0, v[168:169]
	s_addc_u32 s79, s45, 0
	s_add_i32 s77, s80, s5
	global_load_lds_dwordx4 v[202:203], off
	v_lshl_add_u64 v[204:205], s[78:79], 0, v[156:157]
	s_mov_b32 m0, s77
	s_nop 0
	global_load_lds_dwordx4 v[204:205], off
	v_lshl_add_u64 v[204:205], s[78:79], 0, v[168:169]
	s_add_i32 m0, s77, 0x2000
	s_nop 0
	global_load_lds_dwordx4 v[204:205], off
	v_lshl_add_u64 v[204:205], s[48:49], 0, v[152:153]
	s_mov_b32 m0, s6
	s_nop 0
	global_load_lds_dwordx4 v[204:205], off
	v_lshl_add_u64 v[204:205], s[48:49], 0, v[154:155]
	s_mov_b32 m0, s7
	s_nop 0
	global_load_lds_dwordx4 v[204:205], off
	s_waitcnt vmcnt(8)
	s_waitcnt lgkmcnt(0)
	s_barrier
; #define PG8_STAGE(bufoff, gbase, voff) do { _Pragma("unroll") for (int _i = 0; _i < 2; ++_i) \
;         __builtin_amdgcn_global_load_lds((const unsigned*)((const char*)(gbase) + (voff)[_i]), (LAS unsigned*)(lds + (bufoff) + ldsw + _i * 8192), 16, 0, 0); } while (0)
; #define PG8_LDA(dst, b, h) do { _Pragma("unroll") for (int m = 0; m < 4; ++m) _Pragma("unroll") for (int k = 0; k < 2; ++k) dst[m][k] = *(const LAS bf16x8*)(lds + PG8_SA(b, h) + aoff + m * 2048 + k * 1024); } while (0)
; #define PG8_LDB(dst, b, h) do { _Pragma("unroll") for (int n = 0; n < 2; ++n) _Pragma("unroll") for (int k = 0; k < 2; ++k) dst[n][k] = *(const LAS bf16x8*)(lds + PG8_SB(b, h) + boff + n * 2048 + k * 1024); } while (0)
; #define PG8_MMA(ai, bj, At, Bt) do { __builtin_amdgcn_s_setprio(1); _Pragma("unroll") for (int m = 0; m < 4; ++m) _Pragma("unroll") for (int n = 0; n < 2; ++n) _Pragma("unroll") for (int k = 0; k < 2; ++k) \
;         acc[ai][bj][m][n] = __builtin_amdgcn_mfma_f32_16x16x32_bf16(Bt[n][k], At[m][k], acc[ai][bj][m][n], 0, 0, 0); __builtin_amdgcn_s_setprio(0); } while (0)
; #define PG8_WAIT_V(n) asm volatile("s_waitcnt vmcnt(" #n ")" ::: "memory")
; #define PG8_WAIT_L(n) asm volatile("s_waitcnt lgkmcnt(" #n ")" ::: "memory")
; #define PG8_BAR __builtin_amdgcn_s_barrier()
; #define PG8_SCHED __builtin_amdgcn_sched_barrier(0)
;     ...
;             PG8_WAIT_V(8); PG8_WAIT_L(0); PG8_BAR; PG8_MMA(1, 0, At, B0); PG8_MMA(1, 1, At, B1); PG8_BAR; PG8_SCHED;
;             PG8_LDB(B0, 1, 0); PG8_LDB(B1, 1, 1); PG8_SCHED; PG8_LDA(At, 1, 0); PG8_STAGE(PG8_SA(0, 1), a2 + hA, voffA);
;             PG8_WAIT_V(8); PG8_WAIT_L(0); PG8_BAR; PG8_MMA(0, 0, At, B0); PG8_MMA(0, 1, At, B1); PG8_BAR; PG8_SCHED;
	s_setprio 1
	s_waitcnt lgkmcnt(0)
	v_mfma_f32_16x16x32_bf16 v[60:63], v[132:135], v[198:201], v[60:63]
	v_mfma_f32_16x16x32_bf16 v[60:63], v[136:139], v[208:211], v[60:63]
	v_mfma_f32_16x16x32_bf16 v[44:47], v[136:139], v[230:233], v[44:47]
	v_mfma_f32_16x16x32_bf16 v[44:47], v[132:135], v[214:217], v[44:47]
	v_mfma_f32_16x16x32_bf16 v[28:31], v[132:135], v[234:237], v[28:31]
	v_mfma_f32_16x16x32_bf16 v[28:31], v[136:139], v[238:241], v[28:31]
	v_mfma_f32_16x16x32_bf16 v[12:15], v[136:139], v[246:249], v[12:15]
	v_mfma_f32_16x16x32_bf16 v[12:15], v[132:135], v[242:245], v[12:15]
	v_mfma_f32_16x16x32_bf16 v[8:11], v[140:143], v[242:245], v[8:11]
	v_mfma_f32_16x16x32_bf16 v[8:11], v[144:147], v[246:249], v[8:11]
	v_mfma_f32_16x16x32_bf16 v[24:27], v[144:147], v[238:241], v[24:27]
	v_mfma_f32_16x16x32_bf16 v[24:27], v[140:143], v[234:237], v[24:27]
	v_mfma_f32_16x16x32_bf16 v[40:43], v[140:143], v[214:217], v[40:43]
	v_mfma_f32_16x16x32_bf16 v[40:43], v[144:147], v[230:233], v[40:43]
	v_mfma_f32_16x16x32_bf16 v[56:59], v[144:147], v[208:211], v[56:59]
	v_mfma_f32_16x16x32_bf16 v[56:59], v[140:143], v[198:201], v[56:59]
	s_setprio 0
	s_setprio 1
	v_mfma_f32_16x16x32_bf16 v[52:55], v[148:151], v[198:201], v[52:55]
	v_mfma_f32_16x16x32_bf16 v[52:55], v[186:189], v[208:211], v[52:55]
	v_mfma_f32_16x16x32_bf16 v[36:39], v[186:189], v[230:233], v[36:39]
	v_mfma_f32_16x16x32_bf16 v[36:39], v[148:151], v[214:217], v[36:39]
	v_mfma_f32_16x16x32_bf16 v[20:23], v[148:151], v[234:237], v[20:23]
	v_mfma_f32_16x16x32_bf16 v[20:23], v[186:189], v[238:241], v[20:23]
	v_mfma_f32_16x16x32_bf16 v[4:7], v[186:189], v[246:249], v[4:7]
	v_mfma_f32_16x16x32_bf16 v[4:7], v[148:151], v[242:245], v[4:7]
	v_mfma_f32_16x16x32_bf16 v[0:3], v[190:193], v[242:245], v[0:3]
	v_mfma_f32_16x16x32_bf16 v[0:3], v[194:197], v[246:249], v[0:3]
	v_mfma_f32_16x16x32_bf16 v[16:19], v[194:197], v[238:241], v[16:19]
	v_mfma_f32_16x16x32_bf16 v[16:19], v[190:193], v[234:237], v[16:19]
	v_mfma_f32_16x16x32_bf16 v[32:35], v[190:193], v[214:217], v[32:35]
	v_mfma_f32_16x16x32_bf16 v[32:35], v[194:197], v[230:233], v[32:35]
	v_mfma_f32_16x16x32_bf16 v[48:51], v[194:197], v[208:211], v[48:51]
	v_mfma_f32_16x16x32_bf16 v[48:51], v[190:193], v[198:201], v[48:51]
	s_setprio 0
	s_barrier
	s_add_i32 s77, 0, 0x18000
	s_add_i32 s78, 0, 0x1c000
	v_add_u32_e32 v144, s77, v179
	v_add_u32_e32 v178, s78, v179
	ds_read_b128 v[132:135], v144
	ds_read_b128 v[136:139], v144 offset:1024
	ds_read_b128 v[140:143], v144 offset:2048
	ds_read_b128 v[144:147], v144 offset:3072
	ds_read_b128 v[148:151], v178
	ds_read_b128 v[186:189], v178 offset:1024
	ds_read_b128 v[190:193], v178 offset:2048
	ds_read_b128 v[194:197], v178 offset:3072
	s_add_u32 s48, s48, 0x40000
	s_addc_u32 s49, s49, 0
	s_mov_b32 m0, s8
	v_lshl_add_u64 v[204:205], s[48:49], 0, v[152:153]
	ds_read_b128 v[198:201], v181 offset:32768
	ds_read_b128 v[208:211], v181 offset:33792
	ds_read_b128 v[214:217], v181 offset:34816
	ds_read_b128 v[230:233], v181 offset:35840
	ds_read_b128 v[234:237], v181 offset:36864
	ds_read_b128 v[238:241], v181 offset:37888
	ds_read_b128 v[242:245], v181 offset:38912
	ds_read_b128 v[246:249], v181 offset:39936
	global_load_lds_dwordx4 v[204:205], off
	v_lshl_add_u64 v[204:205], s[48:49], 0, v[154:155]
	s_mov_b32 m0, s9
	s_nop 0
	global_load_lds_dwordx4 v[204:205], off
	s_waitcnt vmcnt(8)
	s_waitcnt lgkmcnt(0)
	s_barrier
	s_setprio 1
	s_waitcnt lgkmcnt(0)
	v_mfma_f32_16x16x32_bf16 v[124:127], v[132:135], v[198:201], v[124:127]
	v_mfma_f32_16x16x32_bf16 v[124:127], v[136:139], v[208:211], v[124:127]
	v_mfma_f32_16x16x32_bf16 v[108:111], v[136:139], v[230:233], v[108:111]
	v_mfma_f32_16x16x32_bf16 v[108:111], v[132:135], v[214:217], v[108:111]
	v_mfma_f32_16x16x32_bf16 v[92:95], v[132:135], v[234:237], v[92:95]
	v_mfma_f32_16x16x32_bf16 v[92:95], v[136:139], v[238:241], v[92:95]
	v_mfma_f32_16x16x32_bf16 v[76:79], v[136:139], v[246:249], v[76:79]
	v_mfma_f32_16x16x32_bf16 v[76:79], v[132:135], v[242:245], v[76:79]
	v_mfma_f32_16x16x32_bf16 v[72:75], v[140:143], v[242:245], v[72:75]
	v_mfma_f32_16x16x32_bf16 v[72:75], v[144:147], v[246:249], v[72:75]
	v_mfma_f32_16x16x32_bf16 v[88:91], v[144:147], v[238:241], v[88:91]
	v_mfma_f32_16x16x32_bf16 v[88:91], v[140:143], v[234:237], v[88:91]
	v_mfma_f32_16x16x32_bf16 v[104:107], v[140:143], v[214:217], v[104:107]
	v_mfma_f32_16x16x32_bf16 v[104:107], v[144:147], v[230:233], v[104:107]
	v_mfma_f32_16x16x32_bf16 v[120:123], v[144:147], v[208:211], v[120:123]
	v_mfma_f32_16x16x32_bf16 v[120:123], v[140:143], v[198:201], v[120:123]
	s_setprio 0
	s_setprio 1
	v_mfma_f32_16x16x32_bf16 v[116:119], v[148:151], v[198:201], v[116:119]
	v_mfma_f32_16x16x32_bf16 v[116:119], v[186:189], v[208:211], v[116:119]
	v_mfma_f32_16x16x32_bf16 v[100:103], v[186:189], v[230:233], v[100:103]
	v_mfma_f32_16x16x32_bf16 v[100:103], v[148:151], v[214:217], v[100:103]
	v_mfma_f32_16x16x32_bf16 v[84:87], v[148:151], v[234:237], v[84:87]
	v_mfma_f32_16x16x32_bf16 v[84:87], v[186:189], v[238:241], v[84:87]
	v_mfma_f32_16x16x32_bf16 v[68:71], v[186:189], v[246:249], v[68:71]
	v_mfma_f32_16x16x32_bf16 v[68:71], v[148:151], v[242:245], v[68:71]
	v_mfma_f32_16x16x32_bf16 v[64:67], v[190:193], v[242:245], v[64:67]
	v_mfma_f32_16x16x32_bf16 v[64:67], v[194:197], v[246:249], v[64:67]
	v_mfma_f32_16x16x32_bf16 v[80:83], v[194:197], v[238:241], v[80:83]
	v_mfma_f32_16x16x32_bf16 v[80:83], v[190:193], v[234:237], v[80:83]
	v_mfma_f32_16x16x32_bf16 v[96:99], v[190:193], v[214:217], v[96:99]
	v_mfma_f32_16x16x32_bf16 v[96:99], v[194:197], v[230:233], v[96:99]
	v_mfma_f32_16x16x32_bf16 v[112:115], v[194:197], v[208:211], v[112:115]
	v_mfma_f32_16x16x32_bf16 v[112:115], v[190:193], v[198:201], v[112:115]
	s_setprio 0
	s_barrier
; #define PG8_STAGE(bufoff, gbase, voff) do { _Pragma("unroll") for (int _i = 0; _i < 2; ++_i) \
;         __builtin_amdgcn_global_load_lds((const unsigned*)((const char*)(gbase) + (voff)[_i]), (LAS unsigned*)(lds + (bufoff) + ldsw + _i * 8192), 16, 0, 0); } while (0)
; #define PG8_LDA(dst, b, h) do { _Pragma("unroll") for (int m = 0; m < 4; ++m) _Pragma("unroll") for (int k = 0; k < 2; ++k) dst[m][k] = *(const LAS bf16x8*)(lds + PG8_SA(b, h) + aoff + m * 2048 + k * 1024); } while (0)
; #define PG8_MMA(ai, bj, At, Bt) do { __builtin_amdgcn_s_setprio(1); _Pragma("unroll") for (int m = 0; m < 4; ++m) _Pragma("unroll") for (int n = 0; n < 2; ++n) _Pragma("unroll") for (int k = 0; k < 2; ++k) \
;         acc[ai][bj][m][n] = __builtin_amdgcn_mfma_f32_16x16x32_bf16(Bt[n][k], At[m][k], acc[ai][bj][m][n], 0, 0, 0); __builtin_amdgcn_s_setprio(0); } while (0)
; #define PG8_WAIT_V(n) asm volatile("s_waitcnt vmcnt(" #n ")" ::: "memory")
; #define PG8_WAIT_L(n) asm volatile("s_waitcnt lgkmcnt(" #n ")" ::: "memory")
; #define PG8_BAR __builtin_amdgcn_s_barrier()
; #define PG8_SCHED __builtin_amdgcn_sched_barrier(0)
;     ...
;             PG8_LDA(At, 1, 1); PG8_STAGE(PG8_SB(1, 0), b3, voffB); PG8_STAGE(PG8_SB(1, 1), b3 + hB, voffB); PG8_STAGE(PG8_SA(1, 0), a3, voffA);
;             PG8_WAIT_V(8); PG8_WAIT_L(0); PG8_BAR; PG8_MMA(1, 0, At, B0); PG8_MMA(1, 1, At, B1); PG8_BAR; PG8_SCHED;
;     ...
;         if constexpr (ALIGN_EPI) { if (wr == 0) PG8_BAR; }
	s_add_i32 s48, s77, s5
	v_lshl_add_u64 v[182:183], v[182:183], 0, s[38:39]
	s_mov_b32 m0, s48
	ds_read_b128 v[198:201], v181 offset:49152
	ds_read_b128 v[208:211], v181 offset:50176
	ds_read_b128 v[214:217], v181 offset:51200
	ds_read_b128 v[230:233], v181 offset:52224
	ds_read_b128 v[234:237], v181 offset:53248
	ds_read_b128 v[238:241], v181 offset:54272
	ds_read_b128 v[242:245], v181 offset:55296
	ds_read_b128 v[246:249], v181 offset:56320
	global_load_lds_dwordx4 v[182:183], off
	s_add_i32 m0, s48, 0x2000
	s_add_u32 s44, s44, 0x40080
	v_lshl_add_u64 v[182:183], v[202:203], 0, s[38:39]
	s_addc_u32 s45, s45, 0
	s_add_i32 s48, s78, s5
	global_load_lds_dwordx4 v[182:183], off
	v_lshl_add_u64 v[182:183], s[44:45], 0, v[156:157]
	s_mov_b32 m0, s48
	s_nop 0
	global_load_lds_dwordx4 v[182:183], off
	v_lshl_add_u64 v[182:183], s[44:45], 0, v[168:169]
	s_add_i32 m0, s48, 0x2000
	s_nop 0
	global_load_lds_dwordx4 v[182:183], off
	v_lshl_add_u64 v[182:183], s[42:43], 0, v[152:153]
	s_mov_b32 m0, s50
	s_nop 0
	global_load_lds_dwordx4 v[182:183], off
	v_lshl_add_u64 v[182:183], s[42:43], 0, v[154:155]
	s_mov_b32 m0, s51
	s_nop 0
	global_load_lds_dwordx4 v[182:183], off
	s_waitcnt vmcnt(8)
	s_waitcnt lgkmcnt(0)
	s_barrier
	s_setprio 1
	s_waitcnt lgkmcnt(0)
	v_mfma_f32_16x16x32_bf16 v[60:63], v[132:135], v[198:201], v[60:63]
	v_mfma_f32_16x16x32_bf16 v[60:63], v[136:139], v[208:211], v[60:63]
	v_mfma_f32_16x16x32_bf16 v[44:47], v[136:139], v[230:233], v[44:47]
	v_mfma_f32_16x16x32_bf16 v[44:47], v[132:135], v[214:217], v[44:47]
	v_mfma_f32_16x16x32_bf16 v[28:31], v[132:135], v[234:237], v[28:31]
	v_mfma_f32_16x16x32_bf16 v[28:31], v[136:139], v[238:241], v[28:31]
	v_mfma_f32_16x16x32_bf16 v[12:15], v[136:139], v[246:249], v[12:15]
	v_mfma_f32_16x16x32_bf16 v[12:15], v[132:135], v[242:245], v[12:15]
	v_mfma_f32_16x16x32_bf16 v[8:11], v[140:143], v[242:245], v[8:11]
	v_mfma_f32_16x16x32_bf16 v[8:11], v[144:147], v[246:249], v[8:11]
	v_mfma_f32_16x16x32_bf16 v[24:27], v[144:147], v[238:241], v[24:27]
	v_mfma_f32_16x16x32_bf16 v[24:27], v[140:143], v[234:237], v[24:27]
	v_mfma_f32_16x16x32_bf16 v[40:43], v[140:143], v[214:217], v[40:43]
	v_mfma_f32_16x16x32_bf16 v[40:43], v[144:147], v[230:233], v[40:43]
	v_mfma_f32_16x16x32_bf16 v[56:59], v[144:147], v[208:211], v[56:59]
	v_mfma_f32_16x16x32_bf16 v[56:59], v[140:143], v[198:201], v[56:59]
	s_setprio 0
	s_setprio 1
	v_mfma_f32_16x16x32_bf16 v[52:55], v[148:151], v[198:201], v[52:55]
	v_mfma_f32_16x16x32_bf16 v[52:55], v[186:189], v[208:211], v[52:55]
	v_mfma_f32_16x16x32_bf16 v[36:39], v[186:189], v[230:233], v[36:39]
	v_mfma_f32_16x16x32_bf16 v[36:39], v[148:151], v[214:217], v[36:39]
	v_mfma_f32_16x16x32_bf16 v[20:23], v[148:151], v[234:237], v[20:23]
	v_mfma_f32_16x16x32_bf16 v[20:23], v[186:189], v[238:241], v[20:23]
	v_mfma_f32_16x16x32_bf16 v[4:7], v[186:189], v[246:249], v[4:7]
	v_mfma_f32_16x16x32_bf16 v[4:7], v[148:151], v[242:245], v[4:7]
	v_mfma_f32_16x16x32_bf16 v[0:3], v[190:193], v[242:245], v[0:3]
	v_mfma_f32_16x16x32_bf16 v[0:3], v[194:197], v[246:249], v[0:3]
	v_mfma_f32_16x16x32_bf16 v[16:19], v[194:197], v[238:241], v[16:19]
	v_mfma_f32_16x16x32_bf16 v[16:19], v[190:193], v[234:237], v[16:19]
	v_mfma_f32_16x16x32_bf16 v[32:35], v[190:193], v[214:217], v[32:35]
	v_mfma_f32_16x16x32_bf16 v[32:35], v[194:197], v[230:233], v[32:35]
	v_mfma_f32_16x16x32_bf16 v[48:51], v[194:197], v[208:211], v[48:51]
	v_mfma_f32_16x16x32_bf16 v[48:51], v[190:193], v[198:201], v[48:51]
	s_setprio 0
	s_barrier
	s_add_i32 s76, s76, 2
	s_add_u32 s34, s34, 0x100
	s_addc_u32 s35, s35, 0
	s_cmp_gt_u32 s76, 13
	s_cbranch_scc0 .LBB0_406
	s_and_b64 vcc, exec, s[14:15]
	s_cbranch_vccz .LBB0_409
	s_barrier
